# handover variant + K loops: s_nop 0 between the M0 write and its LDS-DMA load replaced by the load's own address VALU (101 sites)
# baseline (speedup 1.0000x reference)
.LBB0_297:
	s_add_u32 s0, s36, 0xfff80080
	s_addc_u32 s6, s37, -1
	s_add_i32 s49, 0, 0x10000
	s_cmp_eq_u32 s55, 28
	s_cselect_b32 s35, s25, s6
	s_cselect_b32 s34, s33, s0
	v_add_u32_e32 v156, s49, v159
	s_cselect_b32 s31, s40, s39
	s_cselect_b32 s30, s50, s38
	s_add_i32 s0, 0, 0x14000
	ds_read_b128 v[144:147], v156
	ds_read_b128 v[148:151], v156 offset:1024
	ds_read_b128 v[152:155], v156 offset:2048
	ds_read_b128 v[164:167], v156 offset:3072
	v_add_u32_e32 v156, s0, v159
	ds_read_b128 v[168:171], v156
	ds_read_b128 v[172:175], v156 offset:1024
	ds_read_b128 v[176:179], v156 offset:2048
	ds_read_b128 v[180:183], v156 offset:3072
	v_lshl_add_u64 v[156:157], s[36:37], 0, v[140:141]
	s_add_i32 m0, s47, 0xc000
	ds_read_b128 v[184:187], v163
	ds_read_b128 v[188:191], v163 offset:1024
	ds_read_b128 v[192:195], v163 offset:2048
	ds_read_b128 v[200:203], v163 offset:3072
	ds_read_b128 v[204:207], v163 offset:4096
	ds_read_b128 v[208:211], v163 offset:5120
	ds_read_b128 v[212:215], v163 offset:6144
	ds_read_b128 v[216:219], v163 offset:7168
	global_load_lds_dwordx4 v[156:157], off
	s_add_i32 m0, s47, 0xe000
	v_lshl_add_u64 v[156:157], s[36:37], 0, v[142:143]
	global_load_lds_dwordx4 v[156:157], off
	s_waitcnt vmcnt(8)
	s_waitcnt lgkmcnt(0)
	s_setprio 1
	s_barrier
	v_mfma_f32_16x16x32_bf16 v[128:131], v[144:147], v[184:187], v[128:131]
	v_mfma_f32_16x16x32_bf16 v[124:127], v[152:155], v[184:187], v[124:127]
	v_mfma_f32_16x16x32_bf16 v[112:115], v[144:147], v[192:195], v[112:115]
	v_mfma_f32_16x16x32_bf16 v[108:111], v[152:155], v[192:195], v[108:111]
	v_mfma_f32_16x16x32_bf16 v[96:99], v[144:147], v[204:207], v[96:99]
	v_mfma_f32_16x16x32_bf16 v[92:95], v[152:155], v[204:207], v[92:95]
	v_mfma_f32_16x16x32_bf16 v[80:83], v[144:147], v[212:215], v[80:83]
	v_mfma_f32_16x16x32_bf16 v[76:79], v[152:155], v[212:215], v[76:79]
	v_mfma_f32_16x16x32_bf16 v[128:131], v[148:151], v[188:191], v[128:131]
	v_mfma_f32_16x16x32_bf16 v[124:127], v[164:167], v[188:191], v[124:127]
	v_mfma_f32_16x16x32_bf16 v[112:115], v[148:151], v[200:203], v[112:115]
	v_mfma_f32_16x16x32_bf16 v[108:111], v[164:167], v[200:203], v[108:111]
	v_mfma_f32_16x16x32_bf16 v[96:99], v[148:151], v[208:211], v[96:99]
	v_mfma_f32_16x16x32_bf16 v[92:95], v[164:167], v[208:211], v[92:95]
	v_mfma_f32_16x16x32_bf16 v[80:83], v[148:151], v[216:219], v[80:83]
	v_mfma_f32_16x16x32_bf16 v[76:79], v[164:167], v[216:219], v[76:79]
	s_setprio 0
	s_setprio 1
	v_mfma_f32_16x16x32_bf16 v[120:123], v[168:171], v[184:187], v[120:123]
	v_mfma_f32_16x16x32_bf16 v[116:119], v[176:179], v[184:187], v[116:119]
	v_mfma_f32_16x16x32_bf16 v[104:107], v[168:171], v[192:195], v[104:107]
	v_mfma_f32_16x16x32_bf16 v[100:103], v[176:179], v[192:195], v[100:103]
	v_mfma_f32_16x16x32_bf16 v[88:91], v[168:171], v[204:207], v[88:91]
	v_mfma_f32_16x16x32_bf16 v[84:87], v[176:179], v[204:207], v[84:87]
	v_mfma_f32_16x16x32_bf16 v[72:75], v[168:171], v[212:215], v[72:75]
	v_mfma_f32_16x16x32_bf16 v[68:71], v[176:179], v[212:215], v[68:71]
	v_mfma_f32_16x16x32_bf16 v[120:123], v[172:175], v[188:191], v[120:123]
	v_mfma_f32_16x16x32_bf16 v[116:119], v[180:183], v[188:191], v[116:119]
	v_mfma_f32_16x16x32_bf16 v[104:107], v[172:175], v[200:203], v[104:107]
	v_mfma_f32_16x16x32_bf16 v[100:103], v[180:183], v[200:203], v[100:103]
	v_mfma_f32_16x16x32_bf16 v[88:91], v[172:175], v[208:211], v[88:91]
	v_mfma_f32_16x16x32_bf16 v[84:87], v[180:183], v[208:211], v[84:87]
	v_mfma_f32_16x16x32_bf16 v[72:75], v[172:175], v[216:219], v[72:75]
	v_mfma_f32_16x16x32_bf16 v[68:71], v[180:183], v[216:219], v[68:71]
	s_barrier
	s_setprio 0
	s_add_i32 s6, s49, s46
	v_lshl_add_u64 v[156:157], s[30:31], 0, v[136:137]
	s_mov_b32 m0, s6
	ds_read_b128 v[184:187], v163 offset:16384
	ds_read_b128 v[188:191], v163 offset:17408
	ds_read_b128 v[192:195], v163 offset:18432
	ds_read_b128 v[200:203], v163 offset:19456
	ds_read_b128 v[204:207], v163 offset:20480
	ds_read_b128 v[208:211], v163 offset:21504
	ds_read_b128 v[212:215], v163 offset:22528
	ds_read_b128 v[216:219], v163 offset:23552
	global_load_lds_dwordx4 v[156:157], off
	s_add_i32 m0, s6, 0x2000
	s_add_u32 s66, s30, 0x80000
	v_lshl_add_u64 v[220:221], s[30:31], 0, v[132:133]
	s_addc_u32 s67, s31, 0
	s_add_i32 s0, s0, s46
	global_load_lds_dwordx4 v[220:221], off
	v_lshl_add_u64 v[222:223], s[66:67], 0, v[136:137]
	s_mov_b32 m0, s0
	global_load_lds_dwordx4 v[222:223], off
	s_add_i32 m0, s0, 0x2000
	v_lshl_add_u64 v[222:223], s[66:67], 0, v[132:133]
	global_load_lds_dwordx4 v[222:223], off
	s_mov_b32 m0, s47
	v_lshl_add_u64 v[222:223], s[34:35], 0, v[138:139]
	global_load_lds_dwordx4 v[222:223], off
	s_mov_b32 m0, s52
	v_lshl_add_u64 v[224:225], s[34:35], 0, v[134:135]
	global_load_lds_dwordx4 v[224:225], off
	s_waitcnt vmcnt(8)
	s_waitcnt lgkmcnt(0)
	s_setprio 1
	s_barrier
	v_mfma_f32_16x16x32_bf16 v[64:67], v[144:147], v[184:187], v[64:67]
	v_mfma_f32_16x16x32_bf16 v[60:63], v[152:155], v[184:187], v[60:63]
	v_mfma_f32_16x16x32_bf16 v[48:51], v[144:147], v[192:195], v[48:51]
	v_mfma_f32_16x16x32_bf16 v[44:47], v[152:155], v[192:195], v[44:47]
	v_mfma_f32_16x16x32_bf16 v[32:35], v[144:147], v[204:207], v[32:35]
	v_mfma_f32_16x16x32_bf16 v[28:31], v[152:155], v[204:207], v[28:31]
	v_mfma_f32_16x16x32_bf16 v[16:19], v[144:147], v[212:215], v[16:19]
	v_mfma_f32_16x16x32_bf16 v[12:15], v[152:155], v[212:215], v[12:15]
	v_mfma_f32_16x16x32_bf16 v[64:67], v[148:151], v[188:191], v[64:67]
	v_mfma_f32_16x16x32_bf16 v[60:63], v[164:167], v[188:191], v[60:63]
	v_mfma_f32_16x16x32_bf16 v[48:51], v[148:151], v[200:203], v[48:51]
	v_mfma_f32_16x16x32_bf16 v[44:47], v[164:167], v[200:203], v[44:47]
	v_mfma_f32_16x16x32_bf16 v[32:35], v[148:151], v[208:211], v[32:35]
	v_mfma_f32_16x16x32_bf16 v[28:31], v[164:167], v[208:211], v[28:31]
	v_mfma_f32_16x16x32_bf16 v[16:19], v[148:151], v[216:219], v[16:19]
	v_mfma_f32_16x16x32_bf16 v[12:15], v[164:167], v[216:219], v[12:15]
	s_setprio 0
	s_setprio 1
	v_mfma_f32_16x16x32_bf16 v[56:59], v[168:171], v[184:187], v[56:59]
	v_mfma_f32_16x16x32_bf16 v[52:55], v[176:179], v[184:187], v[52:55]
	v_mfma_f32_16x16x32_bf16 v[40:43], v[168:171], v[192:195], v[40:43]
	v_mfma_f32_16x16x32_bf16 v[36:39], v[176:179], v[192:195], v[36:39]
	v_mfma_f32_16x16x32_bf16 v[24:27], v[168:171], v[204:207], v[24:27]
	v_mfma_f32_16x16x32_bf16 v[20:23], v[176:179], v[204:207], v[20:23]
	v_mfma_f32_16x16x32_bf16 v[8:11], v[168:171], v[212:215], v[8:11]
	v_mfma_f32_16x16x32_bf16 v[4:7], v[176:179], v[212:215], v[4:7]
	v_mfma_f32_16x16x32_bf16 v[56:59], v[172:175], v[188:191], v[56:59]
	v_mfma_f32_16x16x32_bf16 v[52:55], v[180:183], v[188:191], v[52:55]
	v_mfma_f32_16x16x32_bf16 v[40:43], v[172:175], v[200:203], v[40:43]
	v_mfma_f32_16x16x32_bf16 v[36:39], v[180:183], v[200:203], v[36:39]
	v_mfma_f32_16x16x32_bf16 v[24:27], v[172:175], v[208:211], v[24:27]
	v_mfma_f32_16x16x32_bf16 v[20:23], v[180:183], v[208:211], v[20:23]
	v_mfma_f32_16x16x32_bf16 v[8:11], v[172:175], v[216:219], v[8:11]
	v_mfma_f32_16x16x32_bf16 v[4:7], v[180:183], v[216:219], v[4:7]
	s_barrier
	s_setprio 0
	s_add_i32 s0, 0, 0x18000
	v_add_u32_e32 v158, s0, v159
	s_add_i32 s6, 0, 0x1c000
	ds_read_b128 v[144:147], v158
	ds_read_b128 v[148:151], v158 offset:1024
	ds_read_b128 v[152:155], v158 offset:2048
	ds_read_b128 v[164:167], v158 offset:3072
	v_add_u32_e32 v158, s6, v159
	ds_read_b128 v[168:171], v158
	ds_read_b128 v[172:175], v158 offset:1024
	ds_read_b128 v[176:179], v158 offset:2048
	ds_read_b128 v[180:183], v158 offset:3072
	s_add_u32 s34, s34, 0x80000
	s_addc_u32 s35, s35, 0
	s_mov_b32 m0, s53
	v_lshl_add_u64 v[226:227], s[34:35], 0, v[138:139]
	ds_read_b128 v[184:187], v163 offset:32768
	ds_read_b128 v[188:191], v163 offset:33792
	ds_read_b128 v[192:195], v163 offset:34816
	ds_read_b128 v[200:203], v163 offset:35840
	ds_read_b128 v[204:207], v163 offset:36864
	ds_read_b128 v[208:211], v163 offset:37888
	ds_read_b128 v[212:215], v163 offset:38912
	ds_read_b128 v[216:219], v163 offset:39936
	global_load_lds_dwordx4 v[226:227], off
	s_mov_b32 m0, s60
	v_lshl_add_u64 v[226:227], s[34:35], 0, v[134:135]
	global_load_lds_dwordx4 v[226:227], off
	s_waitcnt vmcnt(8)
	s_waitcnt lgkmcnt(0)
	s_setprio 1
	s_barrier
	v_mfma_f32_16x16x32_bf16 v[128:131], v[144:147], v[184:187], v[128:131]
	v_mfma_f32_16x16x32_bf16 v[124:127], v[152:155], v[184:187], v[124:127]
	v_mfma_f32_16x16x32_bf16 v[112:115], v[144:147], v[192:195], v[112:115]
	v_mfma_f32_16x16x32_bf16 v[108:111], v[152:155], v[192:195], v[108:111]
	v_mfma_f32_16x16x32_bf16 v[96:99], v[144:147], v[204:207], v[96:99]
	v_mfma_f32_16x16x32_bf16 v[92:95], v[152:155], v[204:207], v[92:95]
	v_mfma_f32_16x16x32_bf16 v[80:83], v[144:147], v[212:215], v[80:83]
	v_mfma_f32_16x16x32_bf16 v[76:79], v[152:155], v[212:215], v[76:79]
	v_mfma_f32_16x16x32_bf16 v[128:131], v[148:151], v[188:191], v[128:131]
	v_mfma_f32_16x16x32_bf16 v[124:127], v[164:167], v[188:191], v[124:127]
	v_mfma_f32_16x16x32_bf16 v[112:115], v[148:151], v[200:203], v[112:115]
	v_mfma_f32_16x16x32_bf16 v[108:111], v[164:167], v[200:203], v[108:111]
	v_mfma_f32_16x16x32_bf16 v[96:99], v[148:151], v[208:211], v[96:99]
	v_mfma_f32_16x16x32_bf16 v[92:95], v[164:167], v[208:211], v[92:95]
	v_mfma_f32_16x16x32_bf16 v[80:83], v[148:151], v[216:219], v[80:83]
	v_mfma_f32_16x16x32_bf16 v[76:79], v[164:167], v[216:219], v[76:79]
	s_setprio 0
	s_setprio 1
	v_mfma_f32_16x16x32_bf16 v[120:123], v[168:171], v[184:187], v[120:123]
	v_mfma_f32_16x16x32_bf16 v[116:119], v[176:179], v[184:187], v[116:119]
	v_mfma_f32_16x16x32_bf16 v[104:107], v[168:171], v[192:195], v[104:107]
	v_mfma_f32_16x16x32_bf16 v[100:103], v[176:179], v[192:195], v[100:103]
	v_mfma_f32_16x16x32_bf16 v[88:91], v[168:171], v[204:207], v[88:91]
	v_mfma_f32_16x16x32_bf16 v[84:87], v[176:179], v[204:207], v[84:87]
	v_mfma_f32_16x16x32_bf16 v[72:75], v[168:171], v[212:215], v[72:75]
	v_mfma_f32_16x16x32_bf16 v[68:71], v[176:179], v[212:215], v[68:71]
	v_mfma_f32_16x16x32_bf16 v[120:123], v[172:175], v[188:191], v[120:123]
	v_mfma_f32_16x16x32_bf16 v[116:119], v[180:183], v[188:191], v[116:119]
	v_mfma_f32_16x16x32_bf16 v[104:107], v[172:175], v[200:203], v[104:107]
	v_mfma_f32_16x16x32_bf16 v[100:103], v[180:183], v[200:203], v[100:103]
	v_mfma_f32_16x16x32_bf16 v[88:91], v[172:175], v[208:211], v[88:91]
	v_mfma_f32_16x16x32_bf16 v[84:87], v[180:183], v[208:211], v[84:87]
	v_mfma_f32_16x16x32_bf16 v[72:75], v[172:175], v[216:219], v[72:75]
	v_mfma_f32_16x16x32_bf16 v[68:71], v[180:183], v[216:219], v[68:71]
	s_barrier
	s_setprio 0
	s_add_i32 s0, s0, s46
	v_lshl_add_u64 v[156:157], v[156:157], 0, s[90:91]
	s_mov_b32 m0, s0
	ds_read_b128 v[184:187], v163 offset:49152
	ds_read_b128 v[188:191], v163 offset:50176
	ds_read_b128 v[192:195], v163 offset:51200
	ds_read_b128 v[200:203], v163 offset:52224
	ds_read_b128 v[204:207], v163 offset:53248
	ds_read_b128 v[208:211], v163 offset:54272
	ds_read_b128 v[212:215], v163 offset:55296
	ds_read_b128 v[216:219], v163 offset:56320
	global_load_lds_dwordx4 v[156:157], off
	s_add_i32 m0, s0, 0x2000
	s_add_u32 s30, s30, 0x80080
	v_lshl_add_u64 v[156:157], v[220:221], 0, s[90:91]
	s_addc_u32 s31, s31, 0
	s_add_i32 s0, s6, s46
	global_load_lds_dwordx4 v[156:157], off
	s_mov_b32 m0, s0
	v_lshl_add_u64 v[156:157], s[30:31], 0, v[136:137]
	global_load_lds_dwordx4 v[156:157], off
	s_add_i32 m0, s0, 0x2000
	v_lshl_add_u64 v[156:157], s[30:31], 0, v[132:133]
	global_load_lds_dwordx4 v[156:157], off
	s_mov_b32 m0, s62
	v_lshl_add_u64 v[156:157], v[222:223], 0, s[90:91]
	global_load_lds_dwordx4 v[156:157], off
	s_mov_b32 m0, s51
	v_lshl_add_u64 v[156:157], v[224:225], 0, s[90:91]
	global_load_lds_dwordx4 v[156:157], off
	s_waitcnt vmcnt(8)
	s_waitcnt lgkmcnt(0)
	s_setprio 1
	s_barrier
	v_mfma_f32_16x16x32_bf16 v[64:67], v[144:147], v[184:187], v[64:67]
	v_mfma_f32_16x16x32_bf16 v[60:63], v[152:155], v[184:187], v[60:63]
	v_mfma_f32_16x16x32_bf16 v[48:51], v[144:147], v[192:195], v[48:51]
	v_mfma_f32_16x16x32_bf16 v[44:47], v[152:155], v[192:195], v[44:47]
	v_mfma_f32_16x16x32_bf16 v[32:35], v[144:147], v[204:207], v[32:35]
	v_mfma_f32_16x16x32_bf16 v[28:31], v[152:155], v[204:207], v[28:31]
	v_mfma_f32_16x16x32_bf16 v[16:19], v[144:147], v[212:215], v[16:19]
	v_mfma_f32_16x16x32_bf16 v[12:15], v[152:155], v[212:215], v[12:15]
	v_mfma_f32_16x16x32_bf16 v[64:67], v[148:151], v[188:191], v[64:67]
	v_mfma_f32_16x16x32_bf16 v[60:63], v[164:167], v[188:191], v[60:63]
	v_mfma_f32_16x16x32_bf16 v[48:51], v[148:151], v[200:203], v[48:51]
	v_mfma_f32_16x16x32_bf16 v[44:47], v[164:167], v[200:203], v[44:47]
	v_mfma_f32_16x16x32_bf16 v[32:35], v[148:151], v[208:211], v[32:35]
	v_mfma_f32_16x16x32_bf16 v[28:31], v[164:167], v[208:211], v[28:31]
	v_mfma_f32_16x16x32_bf16 v[16:19], v[148:151], v[216:219], v[16:19]
	v_mfma_f32_16x16x32_bf16 v[12:15], v[164:167], v[216:219], v[12:15]
	s_setprio 0
	s_setprio 1
	v_mfma_f32_16x16x32_bf16 v[56:59], v[168:171], v[184:187], v[56:59]
	v_mfma_f32_16x16x32_bf16 v[52:55], v[176:179], v[184:187], v[52:55]
	v_mfma_f32_16x16x32_bf16 v[40:43], v[168:171], v[192:195], v[40:43]
	v_mfma_f32_16x16x32_bf16 v[36:39], v[176:179], v[192:195], v[36:39]
	v_mfma_f32_16x16x32_bf16 v[24:27], v[168:171], v[204:207], v[24:27]
	v_mfma_f32_16x16x32_bf16 v[20:23], v[176:179], v[204:207], v[20:23]
	v_mfma_f32_16x16x32_bf16 v[8:11], v[168:171], v[212:215], v[8:11]
	v_mfma_f32_16x16x32_bf16 v[4:7], v[176:179], v[212:215], v[4:7]
	v_mfma_f32_16x16x32_bf16 v[56:59], v[172:175], v[188:191], v[56:59]
	v_mfma_f32_16x16x32_bf16 v[52:55], v[180:183], v[188:191], v[52:55]
	v_mfma_f32_16x16x32_bf16 v[40:43], v[172:175], v[200:203], v[40:43]
	v_mfma_f32_16x16x32_bf16 v[36:39], v[180:183], v[200:203], v[36:39]
	v_mfma_f32_16x16x32_bf16 v[24:27], v[172:175], v[208:211], v[24:27]
	v_mfma_f32_16x16x32_bf16 v[20:23], v[180:183], v[208:211], v[20:23]
	v_mfma_f32_16x16x32_bf16 v[8:11], v[172:175], v[216:219], v[8:11]
	v_mfma_f32_16x16x32_bf16 v[4:7], v[180:183], v[216:219], v[4:7]
	s_barrier
	s_setprio 0
	s_add_i32 s55, s55, 2
	s_add_u32 s36, s36, 0x100
	s_addc_u32 s37, s37, 0
	s_add_u32 s38, s38, 0x100
	s_addc_u32 s39, s39, 0
	s_cmp_gt_u32 s55, 29
	s_cbranch_scc0 .LBB0_297
	s_and_b64 vcc, exec, s[22:23]
	s_cbranch_vccz .LBB0_300
	s_barrier

.LBB0_336:
	s_add_u32 s0, s36, 0xfff80080
	s_addc_u32 s6, s37, -1
	s_add_i32 s49, 0, 0x10000
	s_cmp_eq_u32 s50, 28
	s_cselect_b32 s35, s24, s6
	s_cselect_b32 s34, s25, s0
	v_add_u32_e32 v156, s49, v159
	s_cselect_b32 s31, s33, s39
	s_cselect_b32 s30, s40, s38
	s_add_i32 s0, 0, 0x14000
	ds_read_b128 v[144:147], v156
	ds_read_b128 v[148:151], v156 offset:1024
	ds_read_b128 v[152:155], v156 offset:2048
	ds_read_b128 v[164:167], v156 offset:3072
	v_add_u32_e32 v156, s0, v159
	ds_read_b128 v[168:171], v156
	ds_read_b128 v[172:175], v156 offset:1024
	ds_read_b128 v[176:179], v156 offset:2048
	ds_read_b128 v[180:183], v156 offset:3072
	v_lshl_add_u64 v[156:157], s[36:37], 0, v[140:141]
	s_add_i32 m0, s45, 0xc000
	ds_read_b128 v[184:187], v163
	ds_read_b128 v[188:191], v163 offset:1024
	ds_read_b128 v[192:195], v163 offset:2048
	ds_read_b128 v[200:203], v163 offset:3072
	ds_read_b128 v[204:207], v163 offset:4096
	ds_read_b128 v[208:211], v163 offset:5120
	ds_read_b128 v[212:215], v163 offset:6144
	ds_read_b128 v[216:219], v163 offset:7168
	global_load_lds_dwordx4 v[156:157], off
	s_add_i32 m0, s45, 0xe000
	v_lshl_add_u64 v[156:157], s[36:37], 0, v[142:143]
	global_load_lds_dwordx4 v[156:157], off
	s_waitcnt vmcnt(8)
	s_waitcnt lgkmcnt(0)
	s_setprio 1
	s_barrier
	v_mfma_f32_16x16x32_bf16 v[128:131], v[144:147], v[184:187], v[128:131]
	v_mfma_f32_16x16x32_bf16 v[124:127], v[152:155], v[184:187], v[124:127]
	v_mfma_f32_16x16x32_bf16 v[112:115], v[144:147], v[192:195], v[112:115]
	v_mfma_f32_16x16x32_bf16 v[108:111], v[152:155], v[192:195], v[108:111]
	v_mfma_f32_16x16x32_bf16 v[96:99], v[144:147], v[204:207], v[96:99]
	v_mfma_f32_16x16x32_bf16 v[92:95], v[152:155], v[204:207], v[92:95]
	v_mfma_f32_16x16x32_bf16 v[80:83], v[144:147], v[212:215], v[80:83]
	v_mfma_f32_16x16x32_bf16 v[76:79], v[152:155], v[212:215], v[76:79]
	v_mfma_f32_16x16x32_bf16 v[128:131], v[148:151], v[188:191], v[128:131]
	v_mfma_f32_16x16x32_bf16 v[124:127], v[164:167], v[188:191], v[124:127]
	v_mfma_f32_16x16x32_bf16 v[112:115], v[148:151], v[200:203], v[112:115]
	v_mfma_f32_16x16x32_bf16 v[108:111], v[164:167], v[200:203], v[108:111]
	v_mfma_f32_16x16x32_bf16 v[96:99], v[148:151], v[208:211], v[96:99]
	v_mfma_f32_16x16x32_bf16 v[92:95], v[164:167], v[208:211], v[92:95]
	v_mfma_f32_16x16x32_bf16 v[80:83], v[148:151], v[216:219], v[80:83]
	v_mfma_f32_16x16x32_bf16 v[76:79], v[164:167], v[216:219], v[76:79]
	s_setprio 0
	s_setprio 1
	v_mfma_f32_16x16x32_bf16 v[120:123], v[168:171], v[184:187], v[120:123]
	v_mfma_f32_16x16x32_bf16 v[116:119], v[176:179], v[184:187], v[116:119]
	v_mfma_f32_16x16x32_bf16 v[104:107], v[168:171], v[192:195], v[104:107]
	v_mfma_f32_16x16x32_bf16 v[100:103], v[176:179], v[192:195], v[100:103]
	v_mfma_f32_16x16x32_bf16 v[88:91], v[168:171], v[204:207], v[88:91]
	v_mfma_f32_16x16x32_bf16 v[84:87], v[176:179], v[204:207], v[84:87]
	v_mfma_f32_16x16x32_bf16 v[72:75], v[168:171], v[212:215], v[72:75]
	v_mfma_f32_16x16x32_bf16 v[68:71], v[176:179], v[212:215], v[68:71]
	v_mfma_f32_16x16x32_bf16 v[120:123], v[172:175], v[188:191], v[120:123]
	v_mfma_f32_16x16x32_bf16 v[116:119], v[180:183], v[188:191], v[116:119]
	v_mfma_f32_16x16x32_bf16 v[104:107], v[172:175], v[200:203], v[104:107]
	v_mfma_f32_16x16x32_bf16 v[100:103], v[180:183], v[200:203], v[100:103]
	v_mfma_f32_16x16x32_bf16 v[88:91], v[172:175], v[208:211], v[88:91]
	v_mfma_f32_16x16x32_bf16 v[84:87], v[180:183], v[208:211], v[84:87]
	v_mfma_f32_16x16x32_bf16 v[72:75], v[172:175], v[216:219], v[72:75]
	v_mfma_f32_16x16x32_bf16 v[68:71], v[180:183], v[216:219], v[68:71]
	s_barrier
	s_setprio 0
	s_add_i32 s6, s49, s47
	v_lshl_add_u64 v[156:157], s[30:31], 0, v[136:137]
	s_mov_b32 m0, s6
	ds_read_b128 v[184:187], v163 offset:16384
	ds_read_b128 v[188:191], v163 offset:17408
	ds_read_b128 v[192:195], v163 offset:18432
	ds_read_b128 v[200:203], v163 offset:19456
	ds_read_b128 v[204:207], v163 offset:20480
	ds_read_b128 v[208:211], v163 offset:21504
	ds_read_b128 v[212:215], v163 offset:22528
	ds_read_b128 v[216:219], v163 offset:23552
	global_load_lds_dwordx4 v[156:157], off
	s_add_i32 m0, s6, 0x2000
	s_add_u32 s54, s30, 0x80000
	v_lshl_add_u64 v[220:221], s[30:31], 0, v[132:133]
	s_addc_u32 s55, s31, 0
	s_add_i32 s0, s0, s47
	global_load_lds_dwordx4 v[220:221], off
	v_lshl_add_u64 v[222:223], s[54:55], 0, v[136:137]
	s_mov_b32 m0, s0
	global_load_lds_dwordx4 v[222:223], off
	s_add_i32 m0, s0, 0x2000
	v_lshl_add_u64 v[222:223], s[54:55], 0, v[132:133]
	global_load_lds_dwordx4 v[222:223], off
	s_mov_b32 m0, s45
	v_lshl_add_u64 v[222:223], s[34:35], 0, v[138:139]
	global_load_lds_dwordx4 v[222:223], off
	s_mov_b32 m0, s61
	v_lshl_add_u64 v[224:225], s[34:35], 0, v[134:135]
	global_load_lds_dwordx4 v[224:225], off
	s_waitcnt vmcnt(8)
	s_waitcnt lgkmcnt(0)
	s_setprio 1
	s_barrier
	v_mfma_f32_16x16x32_bf16 v[64:67], v[144:147], v[184:187], v[64:67]
	v_mfma_f32_16x16x32_bf16 v[60:63], v[152:155], v[184:187], v[60:63]
	v_mfma_f32_16x16x32_bf16 v[48:51], v[144:147], v[192:195], v[48:51]
	v_mfma_f32_16x16x32_bf16 v[44:47], v[152:155], v[192:195], v[44:47]
	v_mfma_f32_16x16x32_bf16 v[32:35], v[144:147], v[204:207], v[32:35]
	v_mfma_f32_16x16x32_bf16 v[28:31], v[152:155], v[204:207], v[28:31]
	v_mfma_f32_16x16x32_bf16 v[16:19], v[144:147], v[212:215], v[16:19]
	v_mfma_f32_16x16x32_bf16 v[12:15], v[152:155], v[212:215], v[12:15]
	v_mfma_f32_16x16x32_bf16 v[64:67], v[148:151], v[188:191], v[64:67]
	v_mfma_f32_16x16x32_bf16 v[60:63], v[164:167], v[188:191], v[60:63]
	v_mfma_f32_16x16x32_bf16 v[48:51], v[148:151], v[200:203], v[48:51]
	v_mfma_f32_16x16x32_bf16 v[44:47], v[164:167], v[200:203], v[44:47]
	v_mfma_f32_16x16x32_bf16 v[32:35], v[148:151], v[208:211], v[32:35]
	v_mfma_f32_16x16x32_bf16 v[28:31], v[164:167], v[208:211], v[28:31]
	v_mfma_f32_16x16x32_bf16 v[16:19], v[148:151], v[216:219], v[16:19]
	v_mfma_f32_16x16x32_bf16 v[12:15], v[164:167], v[216:219], v[12:15]
	s_setprio 0
	s_setprio 1
	v_mfma_f32_16x16x32_bf16 v[56:59], v[168:171], v[184:187], v[56:59]
	v_mfma_f32_16x16x32_bf16 v[52:55], v[176:179], v[184:187], v[52:55]
	v_mfma_f32_16x16x32_bf16 v[40:43], v[168:171], v[192:195], v[40:43]
	v_mfma_f32_16x16x32_bf16 v[36:39], v[176:179], v[192:195], v[36:39]
	v_mfma_f32_16x16x32_bf16 v[24:27], v[168:171], v[204:207], v[24:27]
	v_mfma_f32_16x16x32_bf16 v[20:23], v[176:179], v[204:207], v[20:23]
	v_mfma_f32_16x16x32_bf16 v[8:11], v[168:171], v[212:215], v[8:11]
	v_mfma_f32_16x16x32_bf16 v[4:7], v[176:179], v[212:215], v[4:7]
	v_mfma_f32_16x16x32_bf16 v[56:59], v[172:175], v[188:191], v[56:59]
	v_mfma_f32_16x16x32_bf16 v[52:55], v[180:183], v[188:191], v[52:55]
	v_mfma_f32_16x16x32_bf16 v[40:43], v[172:175], v[200:203], v[40:43]
	v_mfma_f32_16x16x32_bf16 v[36:39], v[180:183], v[200:203], v[36:39]
	v_mfma_f32_16x16x32_bf16 v[24:27], v[172:175], v[208:211], v[24:27]
	v_mfma_f32_16x16x32_bf16 v[20:23], v[180:183], v[208:211], v[20:23]
	v_mfma_f32_16x16x32_bf16 v[8:11], v[172:175], v[216:219], v[8:11]
	v_mfma_f32_16x16x32_bf16 v[4:7], v[180:183], v[216:219], v[4:7]
	s_barrier
	s_setprio 0
	s_add_i32 s0, 0, 0x18000
	v_add_u32_e32 v158, s0, v159
	s_add_i32 s6, 0, 0x1c000
	ds_read_b128 v[144:147], v158
	ds_read_b128 v[148:151], v158 offset:1024
	ds_read_b128 v[152:155], v158 offset:2048
	ds_read_b128 v[164:167], v158 offset:3072
	v_add_u32_e32 v158, s6, v159
	ds_read_b128 v[168:171], v158
	ds_read_b128 v[172:175], v158 offset:1024
	ds_read_b128 v[176:179], v158 offset:2048
	ds_read_b128 v[180:183], v158 offset:3072
	s_add_u32 s34, s34, 0x80000
	s_addc_u32 s35, s35, 0
	s_mov_b32 m0, s62
	v_lshl_add_u64 v[226:227], s[34:35], 0, v[138:139]
	ds_read_b128 v[184:187], v163 offset:32768
	ds_read_b128 v[188:191], v163 offset:33792
	ds_read_b128 v[192:195], v163 offset:34816
	ds_read_b128 v[200:203], v163 offset:35840
	ds_read_b128 v[204:207], v163 offset:36864
	ds_read_b128 v[208:211], v163 offset:37888
	ds_read_b128 v[212:215], v163 offset:38912
	ds_read_b128 v[216:219], v163 offset:39936
	global_load_lds_dwordx4 v[226:227], off
	s_mov_b32 m0, s63
	v_lshl_add_u64 v[226:227], s[34:35], 0, v[134:135]
	global_load_lds_dwordx4 v[226:227], off
	s_waitcnt vmcnt(8)
	s_waitcnt lgkmcnt(0)
	s_setprio 1
	s_barrier
	v_mfma_f32_16x16x32_bf16 v[128:131], v[144:147], v[184:187], v[128:131]
	v_mfma_f32_16x16x32_bf16 v[124:127], v[152:155], v[184:187], v[124:127]
	v_mfma_f32_16x16x32_bf16 v[112:115], v[144:147], v[192:195], v[112:115]
	v_mfma_f32_16x16x32_bf16 v[108:111], v[152:155], v[192:195], v[108:111]
	v_mfma_f32_16x16x32_bf16 v[96:99], v[144:147], v[204:207], v[96:99]
	v_mfma_f32_16x16x32_bf16 v[92:95], v[152:155], v[204:207], v[92:95]
	v_mfma_f32_16x16x32_bf16 v[80:83], v[144:147], v[212:215], v[80:83]
	v_mfma_f32_16x16x32_bf16 v[76:79], v[152:155], v[212:215], v[76:79]
	v_mfma_f32_16x16x32_bf16 v[128:131], v[148:151], v[188:191], v[128:131]
	v_mfma_f32_16x16x32_bf16 v[124:127], v[164:167], v[188:191], v[124:127]
	v_mfma_f32_16x16x32_bf16 v[112:115], v[148:151], v[200:203], v[112:115]
	v_mfma_f32_16x16x32_bf16 v[108:111], v[164:167], v[200:203], v[108:111]
	v_mfma_f32_16x16x32_bf16 v[96:99], v[148:151], v[208:211], v[96:99]
	v_mfma_f32_16x16x32_bf16 v[92:95], v[164:167], v[208:211], v[92:95]
	v_mfma_f32_16x16x32_bf16 v[80:83], v[148:151], v[216:219], v[80:83]
	v_mfma_f32_16x16x32_bf16 v[76:79], v[164:167], v[216:219], v[76:79]
	s_setprio 0
	s_setprio 1
	v_mfma_f32_16x16x32_bf16 v[120:123], v[168:171], v[184:187], v[120:123]
	v_mfma_f32_16x16x32_bf16 v[116:119], v[176:179], v[184:187], v[116:119]
	v_mfma_f32_16x16x32_bf16 v[104:107], v[168:171], v[192:195], v[104:107]
	v_mfma_f32_16x16x32_bf16 v[100:103], v[176:179], v[192:195], v[100:103]
	v_mfma_f32_16x16x32_bf16 v[88:91], v[168:171], v[204:207], v[88:91]
	v_mfma_f32_16x16x32_bf16 v[84:87], v[176:179], v[204:207], v[84:87]
	v_mfma_f32_16x16x32_bf16 v[72:75], v[168:171], v[212:215], v[72:75]
	v_mfma_f32_16x16x32_bf16 v[68:71], v[176:179], v[212:215], v[68:71]
	v_mfma_f32_16x16x32_bf16 v[120:123], v[172:175], v[188:191], v[120:123]
	v_mfma_f32_16x16x32_bf16 v[116:119], v[180:183], v[188:191], v[116:119]
	v_mfma_f32_16x16x32_bf16 v[104:107], v[172:175], v[200:203], v[104:107]
	v_mfma_f32_16x16x32_bf16 v[100:103], v[180:183], v[200:203], v[100:103]
	v_mfma_f32_16x16x32_bf16 v[88:91], v[172:175], v[208:211], v[88:91]
	v_mfma_f32_16x16x32_bf16 v[84:87], v[180:183], v[208:211], v[84:87]
	v_mfma_f32_16x16x32_bf16 v[72:75], v[172:175], v[216:219], v[72:75]
	v_mfma_f32_16x16x32_bf16 v[68:71], v[180:183], v[216:219], v[68:71]
	s_barrier
	s_setprio 0
	s_add_i32 s0, s0, s47
	v_lshl_add_u64 v[156:157], v[156:157], 0, s[90:91]
	s_mov_b32 m0, s0
	ds_read_b128 v[184:187], v163 offset:49152
	ds_read_b128 v[188:191], v163 offset:50176
	ds_read_b128 v[192:195], v163 offset:51200
	ds_read_b128 v[200:203], v163 offset:52224
	ds_read_b128 v[204:207], v163 offset:53248
	ds_read_b128 v[208:211], v163 offset:54272
	ds_read_b128 v[212:215], v163 offset:55296
	ds_read_b128 v[216:219], v163 offset:56320
	global_load_lds_dwordx4 v[156:157], off
	s_add_i32 m0, s0, 0x2000
	s_add_u32 s30, s30, 0x80080
	v_lshl_add_u64 v[156:157], v[220:221], 0, s[90:91]
	s_addc_u32 s31, s31, 0
	s_add_i32 s0, s6, s47
	global_load_lds_dwordx4 v[156:157], off
	s_mov_b32 m0, s0
	v_lshl_add_u64 v[156:157], s[30:31], 0, v[136:137]
	global_load_lds_dwordx4 v[156:157], off
	s_add_i32 m0, s0, 0x2000
	v_lshl_add_u64 v[156:157], s[30:31], 0, v[132:133]
	global_load_lds_dwordx4 v[156:157], off
	s_mov_b32 m0, s51
	v_lshl_add_u64 v[156:157], v[222:223], 0, s[90:91]
	global_load_lds_dwordx4 v[156:157], off
	s_mov_b32 m0, s4
	v_lshl_add_u64 v[156:157], v[224:225], 0, s[90:91]
	global_load_lds_dwordx4 v[156:157], off
	s_waitcnt vmcnt(8)
	s_waitcnt lgkmcnt(0)
	s_setprio 1
	s_barrier
	v_mfma_f32_16x16x32_bf16 v[64:67], v[144:147], v[184:187], v[64:67]
	v_mfma_f32_16x16x32_bf16 v[60:63], v[152:155], v[184:187], v[60:63]
	v_mfma_f32_16x16x32_bf16 v[48:51], v[144:147], v[192:195], v[48:51]
	v_mfma_f32_16x16x32_bf16 v[44:47], v[152:155], v[192:195], v[44:47]
	v_mfma_f32_16x16x32_bf16 v[32:35], v[144:147], v[204:207], v[32:35]
	v_mfma_f32_16x16x32_bf16 v[28:31], v[152:155], v[204:207], v[28:31]
	v_mfma_f32_16x16x32_bf16 v[16:19], v[144:147], v[212:215], v[16:19]
	v_mfma_f32_16x16x32_bf16 v[12:15], v[152:155], v[212:215], v[12:15]
	v_mfma_f32_16x16x32_bf16 v[64:67], v[148:151], v[188:191], v[64:67]
	v_mfma_f32_16x16x32_bf16 v[60:63], v[164:167], v[188:191], v[60:63]
	v_mfma_f32_16x16x32_bf16 v[48:51], v[148:151], v[200:203], v[48:51]
	v_mfma_f32_16x16x32_bf16 v[44:47], v[164:167], v[200:203], v[44:47]
	v_mfma_f32_16x16x32_bf16 v[32:35], v[148:151], v[208:211], v[32:35]
	v_mfma_f32_16x16x32_bf16 v[28:31], v[164:167], v[208:211], v[28:31]
	v_mfma_f32_16x16x32_bf16 v[16:19], v[148:151], v[216:219], v[16:19]
	v_mfma_f32_16x16x32_bf16 v[12:15], v[164:167], v[216:219], v[12:15]
	s_setprio 0
	s_setprio 1
	v_mfma_f32_16x16x32_bf16 v[56:59], v[168:171], v[184:187], v[56:59]
	v_mfma_f32_16x16x32_bf16 v[52:55], v[176:179], v[184:187], v[52:55]
	v_mfma_f32_16x16x32_bf16 v[40:43], v[168:171], v[192:195], v[40:43]
	v_mfma_f32_16x16x32_bf16 v[36:39], v[176:179], v[192:195], v[36:39]
	v_mfma_f32_16x16x32_bf16 v[24:27], v[168:171], v[204:207], v[24:27]
	v_mfma_f32_16x16x32_bf16 v[20:23], v[176:179], v[204:207], v[20:23]
	v_mfma_f32_16x16x32_bf16 v[8:11], v[168:171], v[212:215], v[8:11]
	v_mfma_f32_16x16x32_bf16 v[4:7], v[176:179], v[212:215], v[4:7]
	v_mfma_f32_16x16x32_bf16 v[56:59], v[172:175], v[188:191], v[56:59]
	v_mfma_f32_16x16x32_bf16 v[52:55], v[180:183], v[188:191], v[52:55]
	v_mfma_f32_16x16x32_bf16 v[40:43], v[172:175], v[200:203], v[40:43]
	v_mfma_f32_16x16x32_bf16 v[36:39], v[180:183], v[200:203], v[36:39]
	v_mfma_f32_16x16x32_bf16 v[24:27], v[172:175], v[208:211], v[24:27]
	v_mfma_f32_16x16x32_bf16 v[20:23], v[180:183], v[208:211], v[20:23]
	v_mfma_f32_16x16x32_bf16 v[8:11], v[172:175], v[216:219], v[8:11]
	v_mfma_f32_16x16x32_bf16 v[4:7], v[180:183], v[216:219], v[4:7]
	s_barrier
	s_setprio 0
	s_add_i32 s50, s50, 2
	s_add_u32 s36, s36, 0x100
	s_addc_u32 s37, s37, 0
	s_add_u32 s38, s38, 0x100
	s_addc_u32 s39, s39, 0
	s_cmp_gt_u32 s50, 29
	s_cbranch_scc0 .LBB0_336
	s_and_b64 vcc, exec, s[22:23]
	s_cbranch_vccz .LBB0_339
	s_barrier

.LBB0_747:
	s_add_i32 s0, s6, 2
	s_add_u32 s25, s66, 0xfffc0080
	s_addc_u32 s29, s67, -1
	s_add_i32 s33, 0, 0x10000
	s_cmp_eq_u32 s13, s6
	s_cselect_b32 s35, s45, s29
	s_cselect_b32 s34, s44, s25
	v_add_u32_e32 v3, s33, v237
	s_cselect_b32 s31, s61, s24
	s_cselect_b32 s30, s60, s15
	s_add_i32 s6, 0, 0x14000
	ds_read_b128 v[146:149], v3
	ds_read_b128 v[150:153], v3 offset:1024
	ds_read_b128 v[154:157], v3 offset:2048
	ds_read_b128 v[158:161], v3 offset:3072
	v_add_u32_e32 v3, s6, v237
	ds_read_b128 v[162:165], v3
	ds_read_b128 v[166:169], v3 offset:1024
	ds_read_b128 v[170:173], v3 offset:2048
	ds_read_b128 v[174:177], v3 offset:3072
	v_lshl_add_u64 v[4:5], s[66:67], 0, v[142:143]
	s_add_i32 m0, s52, 0xc000
	ds_read_b128 v[178:181], v249
	ds_read_b128 v[182:185], v249 offset:1024
	ds_read_b128 v[186:189], v249 offset:2048
	ds_read_b128 v[190:193], v249 offset:3072
	ds_read_b128 v[200:203], v249 offset:4096
	ds_read_b128 v[204:207], v249 offset:5120
	ds_read_b128 v[208:211], v249 offset:6144
	ds_read_b128 v[212:215], v249 offset:7168
	global_load_lds_dwordx4 v[4:5], off
	s_add_i32 m0, s52, 0xe000
	v_lshl_add_u64 v[4:5], s[66:67], 0, v[144:145]
	global_load_lds_dwordx4 v[4:5], off
	s_waitcnt vmcnt(8)
	s_waitcnt lgkmcnt(0)
	s_setprio 1
	s_barrier
	v_mfma_f32_16x16x32_bf16 v[130:133], v[146:149], v[178:181], v[130:133]
	v_mfma_f32_16x16x32_bf16 v[126:129], v[154:157], v[178:181], v[126:129]
	v_mfma_f32_16x16x32_bf16 v[122:125], v[146:149], v[186:189], v[122:125]
	v_mfma_f32_16x16x32_bf16 v[118:121], v[154:157], v[186:189], v[118:121]
	v_mfma_f32_16x16x32_bf16 v[114:117], v[146:149], v[200:203], v[114:117]
	v_mfma_f32_16x16x32_bf16 v[110:113], v[154:157], v[200:203], v[110:113]
	v_mfma_f32_16x16x32_bf16 v[106:109], v[146:149], v[208:211], v[106:109]
	v_mfma_f32_16x16x32_bf16 v[102:105], v[154:157], v[208:211], v[102:105]
	v_mfma_f32_16x16x32_bf16 v[130:133], v[150:153], v[182:185], v[130:133]
	v_mfma_f32_16x16x32_bf16 v[126:129], v[158:161], v[182:185], v[126:129]
	v_mfma_f32_16x16x32_bf16 v[122:125], v[150:153], v[190:193], v[122:125]
	v_mfma_f32_16x16x32_bf16 v[118:121], v[158:161], v[190:193], v[118:121]
	v_mfma_f32_16x16x32_bf16 v[114:117], v[150:153], v[204:207], v[114:117]
	v_mfma_f32_16x16x32_bf16 v[110:113], v[158:161], v[204:207], v[110:113]
	v_mfma_f32_16x16x32_bf16 v[106:109], v[150:153], v[212:215], v[106:109]
	v_mfma_f32_16x16x32_bf16 v[102:105], v[158:161], v[212:215], v[102:105]
	s_setprio 0
	s_setprio 1
	v_mfma_f32_16x16x32_bf16 v[98:101], v[162:165], v[178:181], v[98:101]
	v_mfma_f32_16x16x32_bf16 v[94:97], v[170:173], v[178:181], v[94:97]
	v_mfma_f32_16x16x32_bf16 v[90:93], v[162:165], v[186:189], v[90:93]
	v_mfma_f32_16x16x32_bf16 v[86:89], v[170:173], v[186:189], v[86:89]
	v_mfma_f32_16x16x32_bf16 v[82:85], v[162:165], v[200:203], v[82:85]
	v_mfma_f32_16x16x32_bf16 v[78:81], v[170:173], v[200:203], v[78:81]
	v_mfma_f32_16x16x32_bf16 v[74:77], v[162:165], v[208:211], v[74:77]
	v_mfma_f32_16x16x32_bf16 v[70:73], v[170:173], v[208:211], v[70:73]
	v_mfma_f32_16x16x32_bf16 v[98:101], v[166:169], v[182:185], v[98:101]
	v_mfma_f32_16x16x32_bf16 v[94:97], v[174:177], v[182:185], v[94:97]
	v_mfma_f32_16x16x32_bf16 v[90:93], v[166:169], v[190:193], v[90:93]
	v_mfma_f32_16x16x32_bf16 v[86:89], v[174:177], v[190:193], v[86:89]
	v_mfma_f32_16x16x32_bf16 v[82:85], v[166:169], v[204:207], v[82:85]
	v_mfma_f32_16x16x32_bf16 v[78:81], v[174:177], v[204:207], v[78:81]
	v_mfma_f32_16x16x32_bf16 v[74:77], v[166:169], v[212:215], v[74:77]
	v_mfma_f32_16x16x32_bf16 v[70:73], v[174:177], v[212:215], v[70:73]
	s_barrier
	s_setprio 0
	s_add_i32 s25, s33, s47
	v_lshl_add_u64 v[194:195], s[30:31], 0, v[136:137]
	s_mov_b32 m0, s25
	ds_read_b128 v[178:181], v249 offset:16384
	ds_read_b128 v[182:185], v249 offset:17408
	ds_read_b128 v[186:189], v249 offset:18432
	ds_read_b128 v[190:193], v249 offset:19456
	ds_read_b128 v[200:203], v249 offset:20480
	ds_read_b128 v[204:207], v249 offset:21504
	ds_read_b128 v[208:211], v249 offset:22528
	ds_read_b128 v[212:215], v249 offset:23552
	global_load_lds_dwordx4 v[194:195], off
	s_add_i32 m0, s25, 0x2000
	s_add_u32 s36, s30, 0x40000
	v_lshl_add_u64 v[216:217], s[30:31], 0, v[140:141]
	s_addc_u32 s37, s31, 0
	s_add_i32 s6, s6, s47
	global_load_lds_dwordx4 v[216:217], off
	v_lshl_add_u64 v[4:5], s[36:37], 0, v[136:137]
	s_mov_b32 m0, s6
	global_load_lds_dwordx4 v[4:5], off
	v_lshl_add_u64 v[4:5], s[36:37], 0, v[140:141]
	s_add_i32 m0, s6, 0x2000
	global_load_lds_dwordx4 v[4:5], off
	s_mov_b32 m0, s52
	v_lshl_add_u64 v[218:219], s[34:35], 0, v[134:135]
	global_load_lds_dwordx4 v[218:219], off
	s_mov_b32 m0, s53
	v_lshl_add_u64 v[220:221], s[34:35], 0, v[138:139]
	global_load_lds_dwordx4 v[220:221], off
	s_waitcnt vmcnt(8)
	s_waitcnt lgkmcnt(0)
	s_setprio 1
	s_barrier
	v_mfma_f32_16x16x32_bf16 v[66:69], v[146:149], v[178:181], v[66:69]
	v_mfma_f32_16x16x32_bf16 v[62:65], v[154:157], v[178:181], v[62:65]
	v_mfma_f32_16x16x32_bf16 v[58:61], v[146:149], v[186:189], v[58:61]
	v_mfma_f32_16x16x32_bf16 v[54:57], v[154:157], v[186:189], v[54:57]
	v_mfma_f32_16x16x32_bf16 v[50:53], v[146:149], v[200:203], v[50:53]
	v_mfma_f32_16x16x32_bf16 v[46:49], v[154:157], v[200:203], v[46:49]
	v_mfma_f32_16x16x32_bf16 v[42:45], v[146:149], v[208:211], v[42:45]
	v_mfma_f32_16x16x32_bf16 v[38:41], v[154:157], v[208:211], v[38:41]
	v_mfma_f32_16x16x32_bf16 v[66:69], v[150:153], v[182:185], v[66:69]
	v_mfma_f32_16x16x32_bf16 v[62:65], v[158:161], v[182:185], v[62:65]
	v_mfma_f32_16x16x32_bf16 v[58:61], v[150:153], v[190:193], v[58:61]
	v_mfma_f32_16x16x32_bf16 v[54:57], v[158:161], v[190:193], v[54:57]
	v_mfma_f32_16x16x32_bf16 v[50:53], v[150:153], v[204:207], v[50:53]
	v_mfma_f32_16x16x32_bf16 v[46:49], v[158:161], v[204:207], v[46:49]
	v_mfma_f32_16x16x32_bf16 v[42:45], v[150:153], v[212:215], v[42:45]
	v_mfma_f32_16x16x32_bf16 v[38:41], v[158:161], v[212:215], v[38:41]
	s_setprio 0
	s_setprio 1
	v_mfma_f32_16x16x32_bf16 v[34:37], v[162:165], v[178:181], v[34:37]
	v_mfma_f32_16x16x32_bf16 v[30:33], v[170:173], v[178:181], v[30:33]
	v_mfma_f32_16x16x32_bf16 v[26:29], v[162:165], v[186:189], v[26:29]
	v_mfma_f32_16x16x32_bf16 v[22:25], v[170:173], v[186:189], v[22:25]
	v_mfma_f32_16x16x32_bf16 v[18:21], v[162:165], v[200:203], v[18:21]
	v_mfma_f32_16x16x32_bf16 v[14:17], v[170:173], v[200:203], v[14:17]
	v_mfma_f32_16x16x32_bf16 v[10:13], v[162:165], v[208:211], v[10:13]
	v_mfma_f32_16x16x32_bf16 v[4:7], v[170:173], v[208:211], v[6:9]
	v_mfma_f32_16x16x32_bf16 v[34:37], v[166:169], v[182:185], v[34:37]
	v_mfma_f32_16x16x32_bf16 v[30:33], v[174:177], v[182:185], v[30:33]
	v_mfma_f32_16x16x32_bf16 v[26:29], v[166:169], v[190:193], v[26:29]
	v_mfma_f32_16x16x32_bf16 v[22:25], v[174:177], v[190:193], v[22:25]
	v_mfma_f32_16x16x32_bf16 v[18:21], v[166:169], v[204:207], v[18:21]
	v_mfma_f32_16x16x32_bf16 v[14:17], v[174:177], v[204:207], v[14:17]
	v_mfma_f32_16x16x32_bf16 v[10:13], v[166:169], v[212:215], v[10:13]
	v_mfma_f32_16x16x32_bf16 v[4:7], v[174:177], v[212:215], v[4:7]
	s_barrier
	s_setprio 0
	s_add_i32 s6, 0, 0x18000
	v_add_u32_e32 v3, s6, v237
	s_add_i32 s25, 0, 0x1c000
	ds_read_b128 v[146:149], v3
	ds_read_b128 v[150:153], v3 offset:1024
	ds_read_b128 v[154:157], v3 offset:2048
	ds_read_b128 v[158:161], v3 offset:3072
	v_add_u32_e32 v3, s25, v237
	ds_read_b128 v[162:165], v3
	ds_read_b128 v[166:169], v3 offset:1024
	ds_read_b128 v[170:173], v3 offset:2048
	ds_read_b128 v[174:177], v3 offset:3072
	s_add_u32 s34, s34, 0x40000
	s_addc_u32 s35, s35, 0
	s_mov_b32 m0, s59
	v_lshl_add_u64 v[8:9], s[34:35], 0, v[134:135]
	ds_read_b128 v[178:181], v249 offset:32768
	ds_read_b128 v[182:185], v249 offset:33792
	ds_read_b128 v[186:189], v249 offset:34816
	ds_read_b128 v[190:193], v249 offset:35840
	ds_read_b128 v[200:203], v249 offset:36864
	ds_read_b128 v[204:207], v249 offset:37888
	ds_read_b128 v[208:211], v249 offset:38912
	ds_read_b128 v[212:215], v249 offset:39936
	global_load_lds_dwordx4 v[8:9], off
	s_mov_b32 m0, s63
	v_lshl_add_u64 v[8:9], s[34:35], 0, v[138:139]
	global_load_lds_dwordx4 v[8:9], off
	s_waitcnt vmcnt(8)
	s_waitcnt lgkmcnt(0)
	s_setprio 1
	s_barrier
	v_mfma_f32_16x16x32_bf16 v[130:133], v[146:149], v[178:181], v[130:133]
	v_mfma_f32_16x16x32_bf16 v[126:129], v[154:157], v[178:181], v[126:129]
	v_mfma_f32_16x16x32_bf16 v[122:125], v[146:149], v[186:189], v[122:125]
	v_mfma_f32_16x16x32_bf16 v[118:121], v[154:157], v[186:189], v[118:121]
	v_mfma_f32_16x16x32_bf16 v[114:117], v[146:149], v[200:203], v[114:117]
	v_mfma_f32_16x16x32_bf16 v[110:113], v[154:157], v[200:203], v[110:113]
	v_mfma_f32_16x16x32_bf16 v[106:109], v[146:149], v[208:211], v[106:109]
	v_mfma_f32_16x16x32_bf16 v[102:105], v[154:157], v[208:211], v[102:105]
	v_mfma_f32_16x16x32_bf16 v[130:133], v[150:153], v[182:185], v[130:133]
	v_mfma_f32_16x16x32_bf16 v[126:129], v[158:161], v[182:185], v[126:129]
	v_mfma_f32_16x16x32_bf16 v[122:125], v[150:153], v[190:193], v[122:125]
	v_mfma_f32_16x16x32_bf16 v[118:121], v[158:161], v[190:193], v[118:121]
	v_mfma_f32_16x16x32_bf16 v[114:117], v[150:153], v[204:207], v[114:117]
	v_mfma_f32_16x16x32_bf16 v[110:113], v[158:161], v[204:207], v[110:113]
	v_mfma_f32_16x16x32_bf16 v[106:109], v[150:153], v[212:215], v[106:109]
	v_mfma_f32_16x16x32_bf16 v[102:105], v[158:161], v[212:215], v[102:105]
	s_setprio 0
	s_setprio 1
	v_mfma_f32_16x16x32_bf16 v[98:101], v[162:165], v[178:181], v[98:101]
	v_mfma_f32_16x16x32_bf16 v[94:97], v[170:173], v[178:181], v[94:97]
	v_mfma_f32_16x16x32_bf16 v[90:93], v[162:165], v[186:189], v[90:93]
	v_mfma_f32_16x16x32_bf16 v[86:89], v[170:173], v[186:189], v[86:89]
	v_mfma_f32_16x16x32_bf16 v[82:85], v[162:165], v[200:203], v[82:85]
	v_mfma_f32_16x16x32_bf16 v[78:81], v[170:173], v[200:203], v[78:81]
	v_mfma_f32_16x16x32_bf16 v[74:77], v[162:165], v[208:211], v[74:77]
	v_mfma_f32_16x16x32_bf16 v[70:73], v[170:173], v[208:211], v[70:73]
	v_mfma_f32_16x16x32_bf16 v[98:101], v[166:169], v[182:185], v[98:101]
	v_mfma_f32_16x16x32_bf16 v[94:97], v[174:177], v[182:185], v[94:97]
	v_mfma_f32_16x16x32_bf16 v[90:93], v[166:169], v[190:193], v[90:93]
	v_mfma_f32_16x16x32_bf16 v[86:89], v[174:177], v[190:193], v[86:89]
	v_mfma_f32_16x16x32_bf16 v[82:85], v[166:169], v[204:207], v[82:85]
	v_mfma_f32_16x16x32_bf16 v[78:81], v[174:177], v[204:207], v[78:81]
	v_mfma_f32_16x16x32_bf16 v[74:77], v[166:169], v[212:215], v[74:77]
	v_mfma_f32_16x16x32_bf16 v[70:73], v[174:177], v[212:215], v[70:73]
	s_barrier
	s_setprio 0
	s_add_i32 s6, s6, s47
	v_lshl_add_u64 v[8:9], v[194:195], 0, s[90:91]
	s_mov_b32 m0, s6
	ds_read_b128 v[178:181], v249 offset:49152
	ds_read_b128 v[182:185], v249 offset:50176
	ds_read_b128 v[186:189], v249 offset:51200
	ds_read_b128 v[190:193], v249 offset:52224
	ds_read_b128 v[200:203], v249 offset:53248
	ds_read_b128 v[204:207], v249 offset:54272
	ds_read_b128 v[208:211], v249 offset:55296
	ds_read_b128 v[212:215], v249 offset:56320
	global_load_lds_dwordx4 v[8:9], off
	s_add_i32 m0, s6, 0x2000
	s_add_u32 s30, s30, 0x40080
	v_lshl_add_u64 v[8:9], v[216:217], 0, s[90:91]
	s_addc_u32 s31, s31, 0
	s_add_i32 s6, s25, s47
	global_load_lds_dwordx4 v[8:9], off
	s_mov_b32 m0, s6
	v_lshl_add_u64 v[8:9], s[30:31], 0, v[136:137]
	global_load_lds_dwordx4 v[8:9], off
	s_add_i32 m0, s6, 0x2000
	v_lshl_add_u64 v[8:9], s[30:31], 0, v[140:141]
	global_load_lds_dwordx4 v[8:9], off
	s_mov_b32 m0, s80
	v_lshl_add_u64 v[8:9], v[218:219], 0, s[90:91]
	global_load_lds_dwordx4 v[8:9], off
	s_mov_b32 m0, s81
	v_lshl_add_u64 v[8:9], v[220:221], 0, s[90:91]
	global_load_lds_dwordx4 v[8:9], off
	s_waitcnt vmcnt(8)
	s_waitcnt lgkmcnt(0)
	s_setprio 1
	s_barrier
	v_mfma_f32_16x16x32_bf16 v[66:69], v[146:149], v[178:181], v[66:69]
	v_mfma_f32_16x16x32_bf16 v[62:65], v[154:157], v[178:181], v[62:65]
	v_mfma_f32_16x16x32_bf16 v[58:61], v[146:149], v[186:189], v[58:61]
	v_mfma_f32_16x16x32_bf16 v[54:57], v[154:157], v[186:189], v[54:57]
	v_mfma_f32_16x16x32_bf16 v[50:53], v[146:149], v[200:203], v[50:53]
	v_mfma_f32_16x16x32_bf16 v[46:49], v[154:157], v[200:203], v[46:49]
	v_mfma_f32_16x16x32_bf16 v[42:45], v[146:149], v[208:211], v[42:45]
	v_mfma_f32_16x16x32_bf16 v[38:41], v[154:157], v[208:211], v[38:41]
	v_mfma_f32_16x16x32_bf16 v[66:69], v[150:153], v[182:185], v[66:69]
	v_mfma_f32_16x16x32_bf16 v[62:65], v[158:161], v[182:185], v[62:65]
	v_mfma_f32_16x16x32_bf16 v[58:61], v[150:153], v[190:193], v[58:61]
	v_mfma_f32_16x16x32_bf16 v[54:57], v[158:161], v[190:193], v[54:57]
	v_mfma_f32_16x16x32_bf16 v[50:53], v[150:153], v[204:207], v[50:53]
	v_mfma_f32_16x16x32_bf16 v[46:49], v[158:161], v[204:207], v[46:49]
	v_mfma_f32_16x16x32_bf16 v[42:45], v[150:153], v[212:215], v[42:45]
	v_mfma_f32_16x16x32_bf16 v[38:41], v[158:161], v[212:215], v[38:41]
	s_setprio 0
	s_setprio 1
	v_mfma_f32_16x16x32_bf16 v[34:37], v[162:165], v[178:181], v[34:37]
	v_mfma_f32_16x16x32_bf16 v[30:33], v[170:173], v[178:181], v[30:33]
	v_mfma_f32_16x16x32_bf16 v[26:29], v[162:165], v[186:189], v[26:29]
	v_mfma_f32_16x16x32_bf16 v[22:25], v[170:173], v[186:189], v[22:25]
	v_mfma_f32_16x16x32_bf16 v[18:21], v[162:165], v[200:203], v[18:21]
	v_mfma_f32_16x16x32_bf16 v[14:17], v[170:173], v[200:203], v[14:17]
	v_mfma_f32_16x16x32_bf16 v[8:11], v[162:165], v[208:211], v[10:13]
	v_mfma_f32_16x16x32_bf16 v[4:7], v[170:173], v[208:211], v[4:7]
	v_mfma_f32_16x16x32_bf16 v[34:37], v[166:169], v[182:185], v[34:37]
	v_mfma_f32_16x16x32_bf16 v[30:33], v[174:177], v[182:185], v[30:33]
	v_mfma_f32_16x16x32_bf16 v[26:29], v[166:169], v[190:193], v[26:29]
	v_mfma_f32_16x16x32_bf16 v[22:25], v[174:177], v[190:193], v[22:25]
	v_mfma_f32_16x16x32_bf16 v[18:21], v[166:169], v[204:207], v[18:21]
	v_mfma_f32_16x16x32_bf16 v[14:17], v[174:177], v[204:207], v[14:17]
	v_mfma_f32_16x16x32_bf16 v[10:13], v[166:169], v[212:215], v[8:11]
	v_mfma_f32_16x16x32_bf16 v[6:9], v[174:177], v[212:215], v[4:7]
	s_barrier
	s_setprio 0
	s_add_u32 s66, s66, 0x100
	s_addc_u32 s67, s67, 0
	s_add_u32 s15, s15, 0x100
	s_addc_u32 s24, s24, 0
	s_cmp_ge_i32 s0, s1
	s_mov_b32 s6, s0
	s_cbranch_scc0 .LBB0_747

.LBB0_967:
	s_add_u32 s0, s36, 0xfff80080
	s_addc_u32 s6, s37, -1
	s_add_i32 s49, 0, 0x10000
	s_cmp_eq_u32 s55, 28
	s_cselect_b32 s35, s65, s6
	s_cselect_b32 s34, s64, s0
	s_cselect_b32 s31, s67, s39
	s_cselect_b32 s30, s66, s38
	s_add_i32 s0, 0, 0x14000
	v_add_u32_e32 v144, s49, v3
	v_add_u32_e32 v160, s0, v3
	ds_read_b128 v[124:127], v144
	ds_read_b128 v[128:131], v144 offset:1024
	ds_read_b128 v[140:143], v144 offset:2048
	ds_read_b128 v[144:147], v144 offset:3072
	ds_read_b128 v[148:151], v160
	ds_read_b128 v[152:155], v160 offset:1024
	ds_read_b128 v[156:159], v160 offset:2048
	ds_read_b128 v[160:163], v160 offset:3072
	v_lshl_add_u64 v[198:199], s[36:37], 0, v[212:213]
	s_add_i32 m0, s4, 0xc000
	ds_read_b128 v[164:167], v250
	ds_read_b128 v[168:171], v250 offset:1024
	ds_read_b128 v[172:175], v250 offset:2048
	ds_read_b128 v[176:179], v250 offset:3072
	ds_read_b128 v[180:183], v250 offset:4096
	ds_read_b128 v[184:187], v250 offset:5120
	ds_read_b128 v[188:191], v250 offset:6144
	ds_read_b128 v[192:195], v250 offset:7168
	global_load_lds_dwordx4 v[198:199], off
	s_add_i32 m0, s4, 0xe000
	v_lshl_add_u64 v[198:199], s[36:37], 0, v[214:215]
	global_load_lds_dwordx4 v[198:199], off
	s_waitcnt vmcnt(8)
	s_waitcnt lgkmcnt(0)
	s_setprio 1
	s_barrier
	v_mfma_f32_16x16x32_bf16 v[136:139], v[124:127], v[164:167], v[136:139]
	v_mfma_f32_16x16x32_bf16 v[132:135], v[140:143], v[164:167], v[132:135]
	v_mfma_f32_16x16x32_bf16 v[112:115], v[124:127], v[172:175], v[112:115]
	v_mfma_f32_16x16x32_bf16 v[108:111], v[140:143], v[172:175], v[108:111]
	v_mfma_f32_16x16x32_bf16 v[96:99], v[124:127], v[180:183], v[96:99]
	v_mfma_f32_16x16x32_bf16 v[92:95], v[140:143], v[180:183], v[92:95]
	v_mfma_f32_16x16x32_bf16 v[80:83], v[124:127], v[188:191], v[80:83]
	v_mfma_f32_16x16x32_bf16 v[76:79], v[140:143], v[188:191], v[76:79]
	v_mfma_f32_16x16x32_bf16 v[136:139], v[128:131], v[168:171], v[136:139]
	v_mfma_f32_16x16x32_bf16 v[132:135], v[144:147], v[168:171], v[132:135]
	v_mfma_f32_16x16x32_bf16 v[112:115], v[128:131], v[176:179], v[112:115]
	v_mfma_f32_16x16x32_bf16 v[108:111], v[144:147], v[176:179], v[108:111]
	v_mfma_f32_16x16x32_bf16 v[96:99], v[128:131], v[184:187], v[96:99]
	v_mfma_f32_16x16x32_bf16 v[92:95], v[144:147], v[184:187], v[92:95]
	v_mfma_f32_16x16x32_bf16 v[80:83], v[128:131], v[192:195], v[80:83]
	v_mfma_f32_16x16x32_bf16 v[76:79], v[144:147], v[192:195], v[76:79]
	s_setprio 0
	s_setprio 1
	v_mfma_f32_16x16x32_bf16 v[120:123], v[148:151], v[164:167], v[120:123]
	v_mfma_f32_16x16x32_bf16 v[116:119], v[156:159], v[164:167], v[116:119]
	v_mfma_f32_16x16x32_bf16 v[104:107], v[148:151], v[172:175], v[104:107]
	v_mfma_f32_16x16x32_bf16 v[100:103], v[156:159], v[172:175], v[100:103]
	v_mfma_f32_16x16x32_bf16 v[88:91], v[148:151], v[180:183], v[88:91]
	v_mfma_f32_16x16x32_bf16 v[84:87], v[156:159], v[180:183], v[84:87]
	v_mfma_f32_16x16x32_bf16 v[72:75], v[148:151], v[188:191], v[72:75]
	v_mfma_f32_16x16x32_bf16 v[68:71], v[156:159], v[188:191], v[68:71]
	v_mfma_f32_16x16x32_bf16 v[120:123], v[152:155], v[168:171], v[120:123]
	v_mfma_f32_16x16x32_bf16 v[116:119], v[160:163], v[168:171], v[116:119]
	v_mfma_f32_16x16x32_bf16 v[104:107], v[152:155], v[176:179], v[104:107]
	v_mfma_f32_16x16x32_bf16 v[100:103], v[160:163], v[176:179], v[100:103]
	v_mfma_f32_16x16x32_bf16 v[88:91], v[152:155], v[184:187], v[88:91]
	v_mfma_f32_16x16x32_bf16 v[84:87], v[160:163], v[184:187], v[84:87]
	v_mfma_f32_16x16x32_bf16 v[72:75], v[152:155], v[192:195], v[72:75]
	v_mfma_f32_16x16x32_bf16 v[68:71], v[160:163], v[192:195], v[68:71]
	s_barrier
	s_setprio 0
	s_add_i32 s6, s49, s1
	v_lshl_add_u64 v[198:199], s[30:31], 0, v[204:205]
	s_mov_b32 m0, s6
	ds_read_b128 v[164:167], v250 offset:16384
	ds_read_b128 v[168:171], v250 offset:17408
	ds_read_b128 v[172:175], v250 offset:18432
	ds_read_b128 v[176:179], v250 offset:19456
	ds_read_b128 v[180:183], v250 offset:20480
	ds_read_b128 v[184:187], v250 offset:21504
	ds_read_b128 v[188:191], v250 offset:22528
	ds_read_b128 v[192:195], v250 offset:23552
	global_load_lds_dwordx4 v[198:199], off
	s_add_i32 m0, s6, 0x2000
	s_add_u32 s68, s30, 0x80000
	v_lshl_add_u64 v[216:217], s[30:31], 0, v[200:201]
	s_addc_u32 s69, s31, 0
	s_add_i32 s0, s0, s1
	global_load_lds_dwordx4 v[216:217], off
	v_lshl_add_u64 v[218:219], s[68:69], 0, v[204:205]
	s_mov_b32 m0, s0
	global_load_lds_dwordx4 v[218:219], off
	s_add_i32 m0, s0, 0x2000
	v_lshl_add_u64 v[218:219], s[68:69], 0, v[200:201]
	global_load_lds_dwordx4 v[218:219], off
	s_mov_b32 m0, s4
	v_lshl_add_u64 v[218:219], s[34:35], 0, v[206:207]
	global_load_lds_dwordx4 v[218:219], off
	s_mov_b32 m0, s24
	v_lshl_add_u64 v[220:221], s[34:35], 0, v[202:203]
	global_load_lds_dwordx4 v[220:221], off
	s_waitcnt vmcnt(8)
	s_waitcnt lgkmcnt(0)
	s_setprio 1
	s_barrier
	v_mfma_f32_16x16x32_bf16 v[64:67], v[124:127], v[164:167], v[64:67]
	v_mfma_f32_16x16x32_bf16 v[60:63], v[140:143], v[164:167], v[60:63]
	v_mfma_f32_16x16x32_bf16 v[48:51], v[124:127], v[172:175], v[48:51]
	v_mfma_f32_16x16x32_bf16 v[44:47], v[140:143], v[172:175], v[44:47]
	v_mfma_f32_16x16x32_bf16 v[32:35], v[124:127], v[180:183], v[32:35]
	v_mfma_f32_16x16x32_bf16 v[28:31], v[140:143], v[180:183], v[28:31]
	v_mfma_f32_16x16x32_bf16 v[16:19], v[124:127], v[188:191], v[16:19]
	v_mfma_f32_16x16x32_bf16 v[12:15], v[140:143], v[188:191], v[12:15]
	v_mfma_f32_16x16x32_bf16 v[64:67], v[128:131], v[168:171], v[64:67]
	v_mfma_f32_16x16x32_bf16 v[60:63], v[144:147], v[168:171], v[60:63]
	v_mfma_f32_16x16x32_bf16 v[48:51], v[128:131], v[176:179], v[48:51]
	v_mfma_f32_16x16x32_bf16 v[44:47], v[144:147], v[176:179], v[44:47]
	v_mfma_f32_16x16x32_bf16 v[32:35], v[128:131], v[184:187], v[32:35]
	v_mfma_f32_16x16x32_bf16 v[28:31], v[144:147], v[184:187], v[28:31]
	v_mfma_f32_16x16x32_bf16 v[16:19], v[128:131], v[192:195], v[16:19]
	v_mfma_f32_16x16x32_bf16 v[12:15], v[144:147], v[192:195], v[12:15]
	s_setprio 0
	s_setprio 1
	v_mfma_f32_16x16x32_bf16 v[56:59], v[148:151], v[164:167], v[56:59]
	v_mfma_f32_16x16x32_bf16 v[52:55], v[156:159], v[164:167], v[52:55]
	v_mfma_f32_16x16x32_bf16 v[40:43], v[148:151], v[172:175], v[40:43]
	v_mfma_f32_16x16x32_bf16 v[36:39], v[156:159], v[172:175], v[36:39]
	v_mfma_f32_16x16x32_bf16 v[24:27], v[148:151], v[180:183], v[24:27]
	v_mfma_f32_16x16x32_bf16 v[20:23], v[156:159], v[180:183], v[20:23]
	v_mfma_f32_16x16x32_bf16 v[8:11], v[148:151], v[188:191], v[8:11]
	v_mfma_f32_16x16x32_bf16 v[4:7], v[156:159], v[188:191], v[4:7]
	v_mfma_f32_16x16x32_bf16 v[56:59], v[152:155], v[168:171], v[56:59]
	v_mfma_f32_16x16x32_bf16 v[52:55], v[160:163], v[168:171], v[52:55]
	v_mfma_f32_16x16x32_bf16 v[40:43], v[152:155], v[176:179], v[40:43]
	v_mfma_f32_16x16x32_bf16 v[36:39], v[160:163], v[176:179], v[36:39]
	v_mfma_f32_16x16x32_bf16 v[24:27], v[152:155], v[184:187], v[24:27]
	v_mfma_f32_16x16x32_bf16 v[20:23], v[160:163], v[184:187], v[20:23]
	v_mfma_f32_16x16x32_bf16 v[8:11], v[152:155], v[192:195], v[8:11]
	v_mfma_f32_16x16x32_bf16 v[4:7], v[160:163], v[192:195], v[4:7]
	s_barrier
	s_setprio 0
	s_add_i32 s0, 0, 0x18000
	s_add_i32 s6, 0, 0x1c000
	v_add_u32_e32 v144, s0, v3
	v_add_u32_e32 v160, s6, v3
	ds_read_b128 v[124:127], v144
	ds_read_b128 v[128:131], v144 offset:1024
	ds_read_b128 v[140:143], v144 offset:2048
	ds_read_b128 v[144:147], v144 offset:3072
	ds_read_b128 v[148:151], v160
	ds_read_b128 v[152:155], v160 offset:1024
	ds_read_b128 v[156:159], v160 offset:2048
	ds_read_b128 v[160:163], v160 offset:3072
	s_add_u32 s34, s34, 0x80000
	s_addc_u32 s35, s35, 0
	s_mov_b32 m0, s25
	v_lshl_add_u64 v[222:223], s[34:35], 0, v[206:207]
	ds_read_b128 v[164:167], v250 offset:32768
	ds_read_b128 v[168:171], v250 offset:33792
	ds_read_b128 v[172:175], v250 offset:34816
	ds_read_b128 v[176:179], v250 offset:35840
	ds_read_b128 v[180:183], v250 offset:36864
	ds_read_b128 v[184:187], v250 offset:37888
	ds_read_b128 v[188:191], v250 offset:38912
	ds_read_b128 v[192:195], v250 offset:39936
	global_load_lds_dwordx4 v[222:223], off
	s_mov_b32 m0, s29
	v_lshl_add_u64 v[222:223], s[34:35], 0, v[202:203]
	global_load_lds_dwordx4 v[222:223], off
	s_waitcnt vmcnt(8)
	s_waitcnt lgkmcnt(0)
	s_setprio 1
	s_barrier
	v_mfma_f32_16x16x32_bf16 v[136:139], v[124:127], v[164:167], v[136:139]
	v_mfma_f32_16x16x32_bf16 v[132:135], v[140:143], v[164:167], v[132:135]
	v_mfma_f32_16x16x32_bf16 v[112:115], v[124:127], v[172:175], v[112:115]
	v_mfma_f32_16x16x32_bf16 v[108:111], v[140:143], v[172:175], v[108:111]
	v_mfma_f32_16x16x32_bf16 v[96:99], v[124:127], v[180:183], v[96:99]
	v_mfma_f32_16x16x32_bf16 v[92:95], v[140:143], v[180:183], v[92:95]
	v_mfma_f32_16x16x32_bf16 v[80:83], v[124:127], v[188:191], v[80:83]
	v_mfma_f32_16x16x32_bf16 v[76:79], v[140:143], v[188:191], v[76:79]
	v_mfma_f32_16x16x32_bf16 v[136:139], v[128:131], v[168:171], v[136:139]
	v_mfma_f32_16x16x32_bf16 v[132:135], v[144:147], v[168:171], v[132:135]
	v_mfma_f32_16x16x32_bf16 v[112:115], v[128:131], v[176:179], v[112:115]
	v_mfma_f32_16x16x32_bf16 v[108:111], v[144:147], v[176:179], v[108:111]
	v_mfma_f32_16x16x32_bf16 v[96:99], v[128:131], v[184:187], v[96:99]
	v_mfma_f32_16x16x32_bf16 v[92:95], v[144:147], v[184:187], v[92:95]
	v_mfma_f32_16x16x32_bf16 v[80:83], v[128:131], v[192:195], v[80:83]
	v_mfma_f32_16x16x32_bf16 v[76:79], v[144:147], v[192:195], v[76:79]
	s_setprio 0
	s_setprio 1
	v_mfma_f32_16x16x32_bf16 v[120:123], v[148:151], v[164:167], v[120:123]
	v_mfma_f32_16x16x32_bf16 v[116:119], v[156:159], v[164:167], v[116:119]
	v_mfma_f32_16x16x32_bf16 v[104:107], v[148:151], v[172:175], v[104:107]
	v_mfma_f32_16x16x32_bf16 v[100:103], v[156:159], v[172:175], v[100:103]
	v_mfma_f32_16x16x32_bf16 v[88:91], v[148:151], v[180:183], v[88:91]
	v_mfma_f32_16x16x32_bf16 v[84:87], v[156:159], v[180:183], v[84:87]
	v_mfma_f32_16x16x32_bf16 v[72:75], v[148:151], v[188:191], v[72:75]
	v_mfma_f32_16x16x32_bf16 v[68:71], v[156:159], v[188:191], v[68:71]
	v_mfma_f32_16x16x32_bf16 v[120:123], v[152:155], v[168:171], v[120:123]
	v_mfma_f32_16x16x32_bf16 v[116:119], v[160:163], v[168:171], v[116:119]
	v_mfma_f32_16x16x32_bf16 v[104:107], v[152:155], v[176:179], v[104:107]
	v_mfma_f32_16x16x32_bf16 v[100:103], v[160:163], v[176:179], v[100:103]
	v_mfma_f32_16x16x32_bf16 v[88:91], v[152:155], v[184:187], v[88:91]
	v_mfma_f32_16x16x32_bf16 v[84:87], v[160:163], v[184:187], v[84:87]
	v_mfma_f32_16x16x32_bf16 v[72:75], v[152:155], v[192:195], v[72:75]
	v_mfma_f32_16x16x32_bf16 v[68:71], v[160:163], v[192:195], v[68:71]
	s_barrier
	s_setprio 0
	s_add_i32 s0, s0, s1
	v_lshl_add_u64 v[198:199], v[198:199], 0, s[90:91]
	s_mov_b32 m0, s0
	ds_read_b128 v[164:167], v250 offset:49152
	ds_read_b128 v[168:171], v250 offset:50176
	ds_read_b128 v[172:175], v250 offset:51200
	ds_read_b128 v[176:179], v250 offset:52224
	ds_read_b128 v[180:183], v250 offset:53248
	ds_read_b128 v[184:187], v250 offset:54272
	ds_read_b128 v[188:191], v250 offset:55296
	ds_read_b128 v[192:195], v250 offset:56320
	global_load_lds_dwordx4 v[198:199], off
	s_add_i32 m0, s0, 0x2000
	s_add_u32 s30, s30, 0x80080
	v_lshl_add_u64 v[198:199], v[216:217], 0, s[90:91]
	s_addc_u32 s31, s31, 0
	s_add_i32 s0, s6, s1
	global_load_lds_dwordx4 v[198:199], off
	s_mov_b32 m0, s0
	v_lshl_add_u64 v[198:199], s[30:31], 0, v[204:205]
	global_load_lds_dwordx4 v[198:199], off
	s_add_i32 m0, s0, 0x2000
	v_lshl_add_u64 v[198:199], s[30:31], 0, v[200:201]
	global_load_lds_dwordx4 v[198:199], off
	s_mov_b32 m0, s33
	v_lshl_add_u64 v[198:199], v[218:219], 0, s[90:91]
	global_load_lds_dwordx4 v[198:199], off
	s_mov_b32 m0, s40
	v_lshl_add_u64 v[198:199], v[220:221], 0, s[90:91]
	global_load_lds_dwordx4 v[198:199], off
	s_waitcnt vmcnt(8)
	s_waitcnt lgkmcnt(0)
	s_setprio 1
	s_barrier
	v_mfma_f32_16x16x32_bf16 v[64:67], v[124:127], v[164:167], v[64:67]
	v_mfma_f32_16x16x32_bf16 v[60:63], v[140:143], v[164:167], v[60:63]
	v_mfma_f32_16x16x32_bf16 v[48:51], v[124:127], v[172:175], v[48:51]
	v_mfma_f32_16x16x32_bf16 v[44:47], v[140:143], v[172:175], v[44:47]
	v_mfma_f32_16x16x32_bf16 v[32:35], v[124:127], v[180:183], v[32:35]
	v_mfma_f32_16x16x32_bf16 v[28:31], v[140:143], v[180:183], v[28:31]
	v_mfma_f32_16x16x32_bf16 v[16:19], v[124:127], v[188:191], v[16:19]
	v_mfma_f32_16x16x32_bf16 v[12:15], v[140:143], v[188:191], v[12:15]
	v_mfma_f32_16x16x32_bf16 v[64:67], v[128:131], v[168:171], v[64:67]
	v_mfma_f32_16x16x32_bf16 v[60:63], v[144:147], v[168:171], v[60:63]
	v_mfma_f32_16x16x32_bf16 v[48:51], v[128:131], v[176:179], v[48:51]
	v_mfma_f32_16x16x32_bf16 v[44:47], v[144:147], v[176:179], v[44:47]
	v_mfma_f32_16x16x32_bf16 v[32:35], v[128:131], v[184:187], v[32:35]
	v_mfma_f32_16x16x32_bf16 v[28:31], v[144:147], v[184:187], v[28:31]
	v_mfma_f32_16x16x32_bf16 v[16:19], v[128:131], v[192:195], v[16:19]
	v_mfma_f32_16x16x32_bf16 v[12:15], v[144:147], v[192:195], v[12:15]
	s_setprio 0
	s_setprio 1
	v_mfma_f32_16x16x32_bf16 v[56:59], v[148:151], v[164:167], v[56:59]
	v_mfma_f32_16x16x32_bf16 v[52:55], v[156:159], v[164:167], v[52:55]
	v_mfma_f32_16x16x32_bf16 v[40:43], v[148:151], v[172:175], v[40:43]
	v_mfma_f32_16x16x32_bf16 v[36:39], v[156:159], v[172:175], v[36:39]
	v_mfma_f32_16x16x32_bf16 v[24:27], v[148:151], v[180:183], v[24:27]
	v_mfma_f32_16x16x32_bf16 v[20:23], v[156:159], v[180:183], v[20:23]
	v_mfma_f32_16x16x32_bf16 v[8:11], v[148:151], v[188:191], v[8:11]
	v_mfma_f32_16x16x32_bf16 v[4:7], v[156:159], v[188:191], v[4:7]
	v_mfma_f32_16x16x32_bf16 v[56:59], v[152:155], v[168:171], v[56:59]
	v_mfma_f32_16x16x32_bf16 v[52:55], v[160:163], v[168:171], v[52:55]
	v_mfma_f32_16x16x32_bf16 v[40:43], v[152:155], v[176:179], v[40:43]
	v_mfma_f32_16x16x32_bf16 v[36:39], v[160:163], v[176:179], v[36:39]
	v_mfma_f32_16x16x32_bf16 v[24:27], v[152:155], v[184:187], v[24:27]
	v_mfma_f32_16x16x32_bf16 v[20:23], v[160:163], v[184:187], v[20:23]
	v_mfma_f32_16x16x32_bf16 v[8:11], v[152:155], v[192:195], v[8:11]
	v_mfma_f32_16x16x32_bf16 v[4:7], v[160:163], v[192:195], v[4:7]
	s_barrier
	s_setprio 0
	s_add_i32 s55, s55, 2
	s_add_u32 s36, s36, 0x100
	s_addc_u32 s37, s37, 0
	s_add_u32 s38, s38, 0x100
	s_addc_u32 s39, s39, 0
	s_cmp_gt_u32 s55, 29
	s_cbranch_scc0 .LBB0_967
	s_and_b64 vcc, exec, s[44:45]
	s_cbranch_vccz .LBB0_970
	s_barrier

.LBB0_1017:
	s_add_u32 s0, s68, s30
	s_addc_u32 s6, s69, 0
	s_add_u32 s31, s0, 0x100
	s_addc_u32 s38, s6, 0
	s_and_b64 s[34:35], s[36:37], exec
	s_cselect_b32 vcc_hi, s65, s38
	s_cselect_b32 vcc_lo, s64, s31
	s_add_u32 s30, s74, s30
	s_addc_u32 s31, s75, 0
	s_add_u32 s34, s30, 0x100
	s_addc_u32 s35, s31, 0
	s_add_i32 s78, 0, 0x10000
	s_and_b64 s[30:31], s[36:37], exec
	s_cselect_b32 s53, s67, s35
	s_cselect_b32 s52, s66, s34
	s_add_i32 s37, 0, 0x14000
	s_add_u32 s34, s0, 0x80080
	s_addc_u32 s35, s6, 0
	s_add_i32 s73, s78, s1
	s_add_i32 m0, s4, 0xc000
	s_add_i32 s83, s4, 0xe000
	s_add_i32 s6, s73, 0x2000
	s_add_u32 s30, s52, 0x80000
	v_add_u32_e32 v144, s78, v3
	v_add_u32_e32 v160, s37, v3
	s_addc_u32 s31, s53, 0
	s_add_i32 s49, s37, s1
	ds_read_b128 v[132:135], v144
	ds_read_b128 v[136:139], v144 offset:1024
	ds_read_b128 v[140:143], v144 offset:2048
	ds_read_b128 v[144:147], v144 offset:3072
	ds_read_b128 v[148:151], v160
	ds_read_b128 v[152:155], v160 offset:1024
	ds_read_b128 v[156:159], v160 offset:2048
	ds_read_b128 v[160:163], v160 offset:3072
	s_add_i32 s63, s49, 0x2000
	s_add_i32 s54, 0, 0x18000
	s_add_i32 s61, 0, 0x1c000
	s_add_u32 s38, vcc_lo, 0x80000
	s_addc_u32 s39, vcc_hi, 0
	s_add_i32 s0, s54, s1
	s_add_i32 s45, s0, 0x2000
	s_add_u32 s36, s52, 0x80080
	s_addc_u32 s37, s53, 0
	s_add_i32 s82, s61, s1
	s_add_i32 s78, s82, 0x2000
	v_lshl_add_u64 v[198:199], s[34:35], 0, v[206:207]
	ds_read_b128 v[164:167], v236
	ds_read_b128 v[168:171], v236 offset:1024
	ds_read_b128 v[172:175], v236 offset:2048
	ds_read_b128 v[176:179], v236 offset:3072
	ds_read_b128 v[180:183], v236 offset:4096
	ds_read_b128 v[184:187], v236 offset:5120
	ds_read_b128 v[188:191], v236 offset:6144
	ds_read_b128 v[192:195], v236 offset:7168
	global_load_lds_dwordx4 v[198:199], off
	s_mov_b32 m0, s83
	v_lshl_add_u64 v[198:199], s[34:35], 0, v[202:203]
	global_load_lds_dwordx4 v[198:199], off
	s_waitcnt vmcnt(8)
	s_waitcnt lgkmcnt(0)
	s_setprio 1
	s_barrier
	v_mfma_f32_16x16x32_bf16 v[128:131], v[132:135], v[164:167], v[128:131]
	v_mfma_f32_16x16x32_bf16 v[124:127], v[140:143], v[164:167], v[124:127]
	v_mfma_f32_16x16x32_bf16 v[112:115], v[132:135], v[172:175], v[112:115]
	v_mfma_f32_16x16x32_bf16 v[108:111], v[140:143], v[172:175], v[108:111]
	v_mfma_f32_16x16x32_bf16 v[96:99], v[132:135], v[180:183], v[96:99]
	v_mfma_f32_16x16x32_bf16 v[92:95], v[140:143], v[180:183], v[92:95]
	v_mfma_f32_16x16x32_bf16 v[80:83], v[132:135], v[188:191], v[80:83]
	v_mfma_f32_16x16x32_bf16 v[76:79], v[140:143], v[188:191], v[76:79]
	v_mfma_f32_16x16x32_bf16 v[128:131], v[136:139], v[168:171], v[128:131]
	v_mfma_f32_16x16x32_bf16 v[124:127], v[144:147], v[168:171], v[124:127]
	v_mfma_f32_16x16x32_bf16 v[112:115], v[136:139], v[176:179], v[112:115]
	v_mfma_f32_16x16x32_bf16 v[108:111], v[144:147], v[176:179], v[108:111]
	v_mfma_f32_16x16x32_bf16 v[96:99], v[136:139], v[184:187], v[96:99]
	v_mfma_f32_16x16x32_bf16 v[92:95], v[144:147], v[184:187], v[92:95]
	v_mfma_f32_16x16x32_bf16 v[80:83], v[136:139], v[192:195], v[80:83]
	v_mfma_f32_16x16x32_bf16 v[76:79], v[144:147], v[192:195], v[76:79]
	s_setprio 0
	s_setprio 1
	v_mfma_f32_16x16x32_bf16 v[120:123], v[148:151], v[164:167], v[120:123]
	v_mfma_f32_16x16x32_bf16 v[116:119], v[156:159], v[164:167], v[116:119]
	v_mfma_f32_16x16x32_bf16 v[104:107], v[148:151], v[172:175], v[104:107]
	v_mfma_f32_16x16x32_bf16 v[100:103], v[156:159], v[172:175], v[100:103]
	v_mfma_f32_16x16x32_bf16 v[88:91], v[148:151], v[180:183], v[88:91]
	v_mfma_f32_16x16x32_bf16 v[84:87], v[156:159], v[180:183], v[84:87]
	v_mfma_f32_16x16x32_bf16 v[72:75], v[148:151], v[188:191], v[72:75]
	v_mfma_f32_16x16x32_bf16 v[68:71], v[156:159], v[188:191], v[68:71]
	v_mfma_f32_16x16x32_bf16 v[120:123], v[152:155], v[168:171], v[120:123]
	v_mfma_f32_16x16x32_bf16 v[116:119], v[160:163], v[168:171], v[116:119]
	v_mfma_f32_16x16x32_bf16 v[104:107], v[152:155], v[176:179], v[104:107]
	v_mfma_f32_16x16x32_bf16 v[100:103], v[160:163], v[176:179], v[100:103]
	v_mfma_f32_16x16x32_bf16 v[88:91], v[152:155], v[184:187], v[88:91]
	v_mfma_f32_16x16x32_bf16 v[84:87], v[160:163], v[184:187], v[84:87]
	v_mfma_f32_16x16x32_bf16 v[72:75], v[152:155], v[192:195], v[72:75]
	v_mfma_f32_16x16x32_bf16 v[68:71], v[160:163], v[192:195], v[68:71]
	s_barrier
	s_setprio 0
	s_mov_b32 m0, s73
	v_lshl_add_u64 v[198:199], s[52:53], 0, v[204:205]
	ds_read_b128 v[164:167], v236 offset:16384
	ds_read_b128 v[168:171], v236 offset:17408
	ds_read_b128 v[172:175], v236 offset:18432
	ds_read_b128 v[176:179], v236 offset:19456
	ds_read_b128 v[180:183], v236 offset:20480
	ds_read_b128 v[184:187], v236 offset:21504
	ds_read_b128 v[188:191], v236 offset:22528
	ds_read_b128 v[192:195], v236 offset:23552
	global_load_lds_dwordx4 v[198:199], off
	v_lshl_add_u64 v[212:213], s[52:53], 0, v[200:201]
	s_mov_b32 m0, s6
	v_lshl_add_u64 v[214:215], s[30:31], 0, v[204:205]
	global_load_lds_dwordx4 v[212:213], off
	s_mov_b32 m0, s49
	global_load_lds_dwordx4 v[214:215], off
	s_mov_b32 m0, s63
	v_lshl_add_u64 v[214:215], s[30:31], 0, v[200:201]
	global_load_lds_dwordx4 v[214:215], off
	s_mov_b32 m0, s4
	v_lshl_add_u64 v[214:215], vcc, 0, v[206:207]
	global_load_lds_dwordx4 v[214:215], off
	s_mov_b32 m0, s24
	v_lshl_add_u64 v[216:217], vcc, 0, v[202:203]
	global_load_lds_dwordx4 v[216:217], off
	s_waitcnt vmcnt(8)
	s_waitcnt lgkmcnt(0)
	s_setprio 1
	s_barrier
	v_mfma_f32_16x16x32_bf16 v[64:67], v[132:135], v[164:167], v[64:67]
	v_mfma_f32_16x16x32_bf16 v[60:63], v[140:143], v[164:167], v[60:63]
	v_mfma_f32_16x16x32_bf16 v[48:51], v[132:135], v[172:175], v[48:51]
	v_mfma_f32_16x16x32_bf16 v[44:47], v[140:143], v[172:175], v[44:47]
	v_mfma_f32_16x16x32_bf16 v[32:35], v[132:135], v[180:183], v[32:35]
	v_mfma_f32_16x16x32_bf16 v[28:31], v[140:143], v[180:183], v[28:31]
	v_mfma_f32_16x16x32_bf16 v[16:19], v[132:135], v[188:191], v[16:19]
	v_mfma_f32_16x16x32_bf16 v[12:15], v[140:143], v[188:191], v[12:15]
	v_mfma_f32_16x16x32_bf16 v[64:67], v[136:139], v[168:171], v[64:67]
	v_mfma_f32_16x16x32_bf16 v[60:63], v[144:147], v[168:171], v[60:63]
	v_mfma_f32_16x16x32_bf16 v[48:51], v[136:139], v[176:179], v[48:51]
	v_mfma_f32_16x16x32_bf16 v[44:47], v[144:147], v[176:179], v[44:47]
	v_mfma_f32_16x16x32_bf16 v[32:35], v[136:139], v[184:187], v[32:35]
	v_mfma_f32_16x16x32_bf16 v[28:31], v[144:147], v[184:187], v[28:31]
	v_mfma_f32_16x16x32_bf16 v[16:19], v[136:139], v[192:195], v[16:19]
	v_mfma_f32_16x16x32_bf16 v[12:15], v[144:147], v[192:195], v[12:15]
	s_setprio 0
	s_setprio 1
	v_mfma_f32_16x16x32_bf16 v[56:59], v[148:151], v[164:167], v[56:59]
	v_mfma_f32_16x16x32_bf16 v[52:55], v[156:159], v[164:167], v[52:55]
	v_mfma_f32_16x16x32_bf16 v[40:43], v[148:151], v[172:175], v[40:43]
	v_mfma_f32_16x16x32_bf16 v[36:39], v[156:159], v[172:175], v[36:39]
	v_mfma_f32_16x16x32_bf16 v[24:27], v[148:151], v[180:183], v[24:27]
	v_mfma_f32_16x16x32_bf16 v[20:23], v[156:159], v[180:183], v[20:23]
	v_mfma_f32_16x16x32_bf16 v[8:11], v[148:151], v[188:191], v[8:11]
	v_mfma_f32_16x16x32_bf16 v[4:7], v[156:159], v[188:191], v[4:7]
	v_mfma_f32_16x16x32_bf16 v[56:59], v[152:155], v[168:171], v[56:59]
	v_mfma_f32_16x16x32_bf16 v[52:55], v[160:163], v[168:171], v[52:55]
	v_mfma_f32_16x16x32_bf16 v[40:43], v[152:155], v[176:179], v[40:43]
	v_mfma_f32_16x16x32_bf16 v[36:39], v[160:163], v[176:179], v[36:39]
	v_mfma_f32_16x16x32_bf16 v[24:27], v[152:155], v[184:187], v[24:27]
	v_mfma_f32_16x16x32_bf16 v[20:23], v[160:163], v[184:187], v[20:23]
	v_mfma_f32_16x16x32_bf16 v[8:11], v[152:155], v[192:195], v[8:11]
	v_mfma_f32_16x16x32_bf16 v[4:7], v[160:163], v[192:195], v[4:7]
	s_barrier
	s_setprio 0
	v_add_u32_e32 v144, s54, v3
	v_add_u32_e32 v160, s61, v3
	ds_read_b128 v[132:135], v144
	ds_read_b128 v[136:139], v144 offset:1024
	ds_read_b128 v[140:143], v144 offset:2048
	ds_read_b128 v[144:147], v144 offset:3072
	ds_read_b128 v[148:151], v160
	ds_read_b128 v[152:155], v160 offset:1024
	ds_read_b128 v[156:159], v160 offset:2048
	ds_read_b128 v[160:163], v160 offset:3072
	s_mov_b32 m0, s25
	v_lshl_add_u64 v[218:219], s[38:39], 0, v[206:207]
	ds_read_b128 v[164:167], v236 offset:32768
	ds_read_b128 v[168:171], v236 offset:33792
	ds_read_b128 v[172:175], v236 offset:34816
	ds_read_b128 v[176:179], v236 offset:35840
	ds_read_b128 v[180:183], v236 offset:36864
	ds_read_b128 v[184:187], v236 offset:37888
	ds_read_b128 v[188:191], v236 offset:38912
	ds_read_b128 v[192:195], v236 offset:39936
	global_load_lds_dwordx4 v[218:219], off
	s_mov_b32 m0, s33
	v_lshl_add_u64 v[218:219], s[38:39], 0, v[202:203]
	global_load_lds_dwordx4 v[218:219], off
	s_waitcnt vmcnt(8)
	s_waitcnt lgkmcnt(0)
	s_setprio 1
	s_barrier
	v_mfma_f32_16x16x32_bf16 v[128:131], v[132:135], v[164:167], v[128:131]
	v_mfma_f32_16x16x32_bf16 v[124:127], v[140:143], v[164:167], v[124:127]
	v_mfma_f32_16x16x32_bf16 v[112:115], v[132:135], v[172:175], v[112:115]
	v_mfma_f32_16x16x32_bf16 v[108:111], v[140:143], v[172:175], v[108:111]
	v_mfma_f32_16x16x32_bf16 v[96:99], v[132:135], v[180:183], v[96:99]
	v_mfma_f32_16x16x32_bf16 v[92:95], v[140:143], v[180:183], v[92:95]
	v_mfma_f32_16x16x32_bf16 v[80:83], v[132:135], v[188:191], v[80:83]
	v_mfma_f32_16x16x32_bf16 v[76:79], v[140:143], v[188:191], v[76:79]
	v_mfma_f32_16x16x32_bf16 v[128:131], v[136:139], v[168:171], v[128:131]
	v_mfma_f32_16x16x32_bf16 v[124:127], v[144:147], v[168:171], v[124:127]
	v_mfma_f32_16x16x32_bf16 v[112:115], v[136:139], v[176:179], v[112:115]
	v_mfma_f32_16x16x32_bf16 v[108:111], v[144:147], v[176:179], v[108:111]
	v_mfma_f32_16x16x32_bf16 v[96:99], v[136:139], v[184:187], v[96:99]
	v_mfma_f32_16x16x32_bf16 v[92:95], v[144:147], v[184:187], v[92:95]
	v_mfma_f32_16x16x32_bf16 v[80:83], v[136:139], v[192:195], v[80:83]
	v_mfma_f32_16x16x32_bf16 v[76:79], v[144:147], v[192:195], v[76:79]
	s_setprio 0
	s_setprio 1
	v_mfma_f32_16x16x32_bf16 v[120:123], v[148:151], v[164:167], v[120:123]
	v_mfma_f32_16x16x32_bf16 v[116:119], v[156:159], v[164:167], v[116:119]
	v_mfma_f32_16x16x32_bf16 v[104:107], v[148:151], v[172:175], v[104:107]
	v_mfma_f32_16x16x32_bf16 v[100:103], v[156:159], v[172:175], v[100:103]
	v_mfma_f32_16x16x32_bf16 v[88:91], v[148:151], v[180:183], v[88:91]
	v_mfma_f32_16x16x32_bf16 v[84:87], v[156:159], v[180:183], v[84:87]
	v_mfma_f32_16x16x32_bf16 v[72:75], v[148:151], v[188:191], v[72:75]
	v_mfma_f32_16x16x32_bf16 v[68:71], v[156:159], v[188:191], v[68:71]
	v_mfma_f32_16x16x32_bf16 v[120:123], v[152:155], v[168:171], v[120:123]
	v_mfma_f32_16x16x32_bf16 v[116:119], v[160:163], v[168:171], v[116:119]
	v_mfma_f32_16x16x32_bf16 v[104:107], v[152:155], v[176:179], v[104:107]
	v_mfma_f32_16x16x32_bf16 v[100:103], v[160:163], v[176:179], v[100:103]
	v_mfma_f32_16x16x32_bf16 v[88:91], v[152:155], v[184:187], v[88:91]
	v_mfma_f32_16x16x32_bf16 v[84:87], v[160:163], v[184:187], v[84:87]
	v_mfma_f32_16x16x32_bf16 v[72:75], v[152:155], v[192:195], v[72:75]
	v_mfma_f32_16x16x32_bf16 v[68:71], v[160:163], v[192:195], v[68:71]
	s_barrier
	s_setprio 0
	s_mov_b32 m0, s0
	v_lshl_add_u64 v[198:199], v[198:199], 0, s[90:91]
	ds_read_b128 v[164:167], v236 offset:49152
	ds_read_b128 v[168:171], v236 offset:50176
	ds_read_b128 v[172:175], v236 offset:51200
	ds_read_b128 v[176:179], v236 offset:52224
	ds_read_b128 v[180:183], v236 offset:53248
	ds_read_b128 v[184:187], v236 offset:54272
	ds_read_b128 v[188:191], v236 offset:55296
	ds_read_b128 v[192:195], v236 offset:56320
	global_load_lds_dwordx4 v[198:199], off
	s_mov_b32 m0, s45
	v_lshl_add_u64 v[198:199], v[212:213], 0, s[90:91]
	global_load_lds_dwordx4 v[198:199], off
	s_mov_b32 m0, s82
	v_lshl_add_u64 v[198:199], s[36:37], 0, v[204:205]
	global_load_lds_dwordx4 v[198:199], off
	s_mov_b32 m0, s78
	v_lshl_add_u64 v[198:199], s[36:37], 0, v[200:201]
	global_load_lds_dwordx4 v[198:199], off
	s_mov_b32 m0, s40
	v_lshl_add_u64 v[198:199], v[214:215], 0, s[90:91]
	global_load_lds_dwordx4 v[198:199], off
	s_mov_b32 m0, s50
	v_lshl_add_u64 v[198:199], v[216:217], 0, s[90:91]
	global_load_lds_dwordx4 v[198:199], off
	s_waitcnt vmcnt(8)
	s_waitcnt lgkmcnt(0)
	s_setprio 1
	s_barrier
	v_mfma_f32_16x16x32_bf16 v[64:67], v[132:135], v[164:167], v[64:67]
	v_mfma_f32_16x16x32_bf16 v[60:63], v[140:143], v[164:167], v[60:63]
	v_mfma_f32_16x16x32_bf16 v[48:51], v[132:135], v[172:175], v[48:51]
	v_mfma_f32_16x16x32_bf16 v[44:47], v[140:143], v[172:175], v[44:47]
	v_mfma_f32_16x16x32_bf16 v[32:35], v[132:135], v[180:183], v[32:35]
	v_mfma_f32_16x16x32_bf16 v[28:31], v[140:143], v[180:183], v[28:31]
	v_mfma_f32_16x16x32_bf16 v[16:19], v[132:135], v[188:191], v[16:19]
	v_mfma_f32_16x16x32_bf16 v[12:15], v[140:143], v[188:191], v[12:15]
	v_mfma_f32_16x16x32_bf16 v[64:67], v[136:139], v[168:171], v[64:67]
	v_mfma_f32_16x16x32_bf16 v[60:63], v[144:147], v[168:171], v[60:63]
	v_mfma_f32_16x16x32_bf16 v[48:51], v[136:139], v[176:179], v[48:51]
	v_mfma_f32_16x16x32_bf16 v[44:47], v[144:147], v[176:179], v[44:47]
	v_mfma_f32_16x16x32_bf16 v[32:35], v[136:139], v[184:187], v[32:35]
	v_mfma_f32_16x16x32_bf16 v[28:31], v[144:147], v[184:187], v[28:31]
	v_mfma_f32_16x16x32_bf16 v[16:19], v[136:139], v[192:195], v[16:19]
	v_mfma_f32_16x16x32_bf16 v[12:15], v[144:147], v[192:195], v[12:15]
	s_setprio 0
	s_setprio 1
	v_mfma_f32_16x16x32_bf16 v[56:59], v[148:151], v[164:167], v[56:59]
	v_mfma_f32_16x16x32_bf16 v[52:55], v[156:159], v[164:167], v[52:55]
	v_mfma_f32_16x16x32_bf16 v[40:43], v[148:151], v[172:175], v[40:43]
	v_mfma_f32_16x16x32_bf16 v[36:39], v[156:159], v[172:175], v[36:39]
	v_mfma_f32_16x16x32_bf16 v[24:27], v[148:151], v[180:183], v[24:27]
	v_mfma_f32_16x16x32_bf16 v[20:23], v[156:159], v[180:183], v[20:23]
	v_mfma_f32_16x16x32_bf16 v[8:11], v[148:151], v[188:191], v[8:11]
	v_mfma_f32_16x16x32_bf16 v[4:7], v[156:159], v[188:191], v[4:7]
	v_mfma_f32_16x16x32_bf16 v[56:59], v[152:155], v[168:171], v[56:59]
	v_mfma_f32_16x16x32_bf16 v[52:55], v[160:163], v[168:171], v[52:55]
	v_mfma_f32_16x16x32_bf16 v[40:43], v[152:155], v[176:179], v[40:43]
	v_mfma_f32_16x16x32_bf16 v[36:39], v[160:163], v[176:179], v[36:39]
	v_mfma_f32_16x16x32_bf16 v[24:27], v[152:155], v[184:187], v[24:27]
	v_mfma_f32_16x16x32_bf16 v[20:23], v[160:163], v[184:187], v[20:23]
	v_mfma_f32_16x16x32_bf16 v[8:11], v[152:155], v[192:195], v[8:11]
	v_mfma_f32_16x16x32_bf16 v[4:7], v[160:163], v[192:195], v[4:7]
	s_barrier
	s_setprio 0
	s_movk_i32 s30, 0x100
	s_andn2_b64 vcc, exec, s[80:81]
	s_mov_b64 s[36:37], -1
	s_mov_b64 s[80:81], 0
	s_cbranch_vccz .LBB0_1017
	s_and_b64 vcc, exec, s[42:43]
	s_cbranch_vccz .LBB0_1020
	s_barrier

.LBB0_1137:
	s_add_u32 s0, s36, 0xfff80080
	s_addc_u32 s6, s37, -1
	s_add_i32 s49, 0, 0x10000
	s_cmp_eq_u32 s66, 28
	s_cselect_b32 s35, s29, s6
	s_cselect_b32 s34, s64, s0
	v_add_u32_e32 v156, s49, v157
	s_cselect_b32 s31, s23, s39
	s_cselect_b32 s30, s65, s38
	s_add_i32 s0, 0, 0x14000
	ds_read_b128 v[144:147], v156
	ds_read_b128 v[148:151], v156 offset:1024
	ds_read_b128 v[152:155], v156 offset:2048
	ds_read_b128 v[162:165], v156 offset:3072
	v_add_u32_e32 v156, s0, v157
	ds_read_b128 v[166:169], v156
	ds_read_b128 v[170:173], v156 offset:1024
	ds_read_b128 v[174:177], v156 offset:2048
	ds_read_b128 v[178:181], v156 offset:3072
	v_lshl_add_u64 v[194:195], s[36:37], 0, v[140:141]
	s_add_i32 m0, s33, 0xc000
	ds_read_b128 v[182:185], v161
	ds_read_b128 v[186:189], v161 offset:1024
	ds_read_b128 v[190:193], v161 offset:2048
	ds_read_b128 v[200:203], v161 offset:3072
	ds_read_b128 v[204:207], v161 offset:4096
	ds_read_b128 v[208:211], v161 offset:5120
	ds_read_b128 v[212:215], v161 offset:6144
	ds_read_b128 v[216:219], v161 offset:7168
	global_load_lds_dwordx4 v[194:195], off
	s_add_i32 m0, s33, 0xe000
	v_lshl_add_u64 v[194:195], s[36:37], 0, v[142:143]
	global_load_lds_dwordx4 v[194:195], off
	s_waitcnt vmcnt(8)
	s_waitcnt lgkmcnt(0)
	s_setprio 1
	s_barrier
	v_mfma_f32_16x16x32_bf16 v[128:131], v[144:147], v[182:185], v[128:131]
	v_mfma_f32_16x16x32_bf16 v[124:127], v[152:155], v[182:185], v[124:127]
	v_mfma_f32_16x16x32_bf16 v[112:115], v[144:147], v[190:193], v[112:115]
	v_mfma_f32_16x16x32_bf16 v[108:111], v[152:155], v[190:193], v[108:111]
	v_mfma_f32_16x16x32_bf16 v[96:99], v[144:147], v[204:207], v[96:99]
	v_mfma_f32_16x16x32_bf16 v[92:95], v[152:155], v[204:207], v[92:95]
	v_mfma_f32_16x16x32_bf16 v[80:83], v[144:147], v[212:215], v[80:83]
	v_mfma_f32_16x16x32_bf16 v[76:79], v[152:155], v[212:215], v[76:79]
	v_mfma_f32_16x16x32_bf16 v[128:131], v[148:151], v[186:189], v[128:131]
	v_mfma_f32_16x16x32_bf16 v[124:127], v[162:165], v[186:189], v[124:127]
	v_mfma_f32_16x16x32_bf16 v[112:115], v[148:151], v[200:203], v[112:115]
	v_mfma_f32_16x16x32_bf16 v[108:111], v[162:165], v[200:203], v[108:111]
	v_mfma_f32_16x16x32_bf16 v[96:99], v[148:151], v[208:211], v[96:99]
	v_mfma_f32_16x16x32_bf16 v[92:95], v[162:165], v[208:211], v[92:95]
	v_mfma_f32_16x16x32_bf16 v[80:83], v[148:151], v[216:219], v[80:83]
	v_mfma_f32_16x16x32_bf16 v[76:79], v[162:165], v[216:219], v[76:79]
	s_setprio 0
	s_setprio 1
	v_mfma_f32_16x16x32_bf16 v[120:123], v[166:169], v[182:185], v[120:123]
	v_mfma_f32_16x16x32_bf16 v[116:119], v[174:177], v[182:185], v[116:119]
	v_mfma_f32_16x16x32_bf16 v[104:107], v[166:169], v[190:193], v[104:107]
	v_mfma_f32_16x16x32_bf16 v[100:103], v[174:177], v[190:193], v[100:103]
	v_mfma_f32_16x16x32_bf16 v[88:91], v[166:169], v[204:207], v[88:91]
	v_mfma_f32_16x16x32_bf16 v[84:87], v[174:177], v[204:207], v[84:87]
	v_mfma_f32_16x16x32_bf16 v[72:75], v[166:169], v[212:215], v[72:75]
	v_mfma_f32_16x16x32_bf16 v[68:71], v[174:177], v[212:215], v[68:71]
	v_mfma_f32_16x16x32_bf16 v[120:123], v[170:173], v[186:189], v[120:123]
	v_mfma_f32_16x16x32_bf16 v[116:119], v[178:181], v[186:189], v[116:119]
	v_mfma_f32_16x16x32_bf16 v[104:107], v[170:173], v[200:203], v[104:107]
	v_mfma_f32_16x16x32_bf16 v[100:103], v[178:181], v[200:203], v[100:103]
	v_mfma_f32_16x16x32_bf16 v[88:91], v[170:173], v[208:211], v[88:91]
	v_mfma_f32_16x16x32_bf16 v[84:87], v[178:181], v[208:211], v[84:87]
	v_mfma_f32_16x16x32_bf16 v[72:75], v[170:173], v[216:219], v[72:75]
	v_mfma_f32_16x16x32_bf16 v[68:71], v[178:181], v[216:219], v[68:71]
	s_barrier
	s_setprio 0
	s_add_i32 s6, s49, s25
	v_lshl_add_u64 v[194:195], s[30:31], 0, v[136:137]
	s_mov_b32 m0, s6
	ds_read_b128 v[182:185], v161 offset:16384
	ds_read_b128 v[186:189], v161 offset:17408
	ds_read_b128 v[190:193], v161 offset:18432
	ds_read_b128 v[200:203], v161 offset:19456
	ds_read_b128 v[204:207], v161 offset:20480
	ds_read_b128 v[208:211], v161 offset:21504
	ds_read_b128 v[212:215], v161 offset:22528
	ds_read_b128 v[216:219], v161 offset:23552
	global_load_lds_dwordx4 v[194:195], off
	s_add_i32 m0, s6, 0x2000
	s_add_u32 s68, s30, 0x80000
	v_lshl_add_u64 v[198:199], s[30:31], 0, v[132:133]
	s_addc_u32 s69, s31, 0
	s_add_i32 s0, s0, s25
	global_load_lds_dwordx4 v[198:199], off
	v_lshl_add_u64 v[220:221], s[68:69], 0, v[136:137]
	s_mov_b32 m0, s0
	global_load_lds_dwordx4 v[220:221], off
	s_add_i32 m0, s0, 0x2000
	v_lshl_add_u64 v[220:221], s[68:69], 0, v[132:133]
	global_load_lds_dwordx4 v[220:221], off
	s_mov_b32 m0, s33
	v_lshl_add_u64 v[220:221], s[34:35], 0, v[138:139]
	global_load_lds_dwordx4 v[220:221], off
	s_mov_b32 m0, s40
	v_lshl_add_u64 v[222:223], s[34:35], 0, v[134:135]
	global_load_lds_dwordx4 v[222:223], off
	s_waitcnt vmcnt(8)
	s_waitcnt lgkmcnt(0)
	s_setprio 1
	s_barrier
	v_mfma_f32_16x16x32_bf16 v[64:67], v[144:147], v[182:185], v[64:67]
	v_mfma_f32_16x16x32_bf16 v[60:63], v[152:155], v[182:185], v[60:63]
	v_mfma_f32_16x16x32_bf16 v[48:51], v[144:147], v[190:193], v[48:51]
	v_mfma_f32_16x16x32_bf16 v[44:47], v[152:155], v[190:193], v[44:47]
	v_mfma_f32_16x16x32_bf16 v[32:35], v[144:147], v[204:207], v[32:35]
	v_mfma_f32_16x16x32_bf16 v[28:31], v[152:155], v[204:207], v[28:31]
	v_mfma_f32_16x16x32_bf16 v[16:19], v[144:147], v[212:215], v[16:19]
	v_mfma_f32_16x16x32_bf16 v[12:15], v[152:155], v[212:215], v[12:15]
	v_mfma_f32_16x16x32_bf16 v[64:67], v[148:151], v[186:189], v[64:67]
	v_mfma_f32_16x16x32_bf16 v[60:63], v[162:165], v[186:189], v[60:63]
	v_mfma_f32_16x16x32_bf16 v[48:51], v[148:151], v[200:203], v[48:51]
	v_mfma_f32_16x16x32_bf16 v[44:47], v[162:165], v[200:203], v[44:47]
	v_mfma_f32_16x16x32_bf16 v[32:35], v[148:151], v[208:211], v[32:35]
	v_mfma_f32_16x16x32_bf16 v[28:31], v[162:165], v[208:211], v[28:31]
	v_mfma_f32_16x16x32_bf16 v[16:19], v[148:151], v[216:219], v[16:19]
	v_mfma_f32_16x16x32_bf16 v[12:15], v[162:165], v[216:219], v[12:15]
	s_setprio 0
	s_setprio 1
	v_mfma_f32_16x16x32_bf16 v[56:59], v[166:169], v[182:185], v[56:59]
	v_mfma_f32_16x16x32_bf16 v[52:55], v[174:177], v[182:185], v[52:55]
	v_mfma_f32_16x16x32_bf16 v[40:43], v[166:169], v[190:193], v[40:43]
	v_mfma_f32_16x16x32_bf16 v[36:39], v[174:177], v[190:193], v[36:39]
	v_mfma_f32_16x16x32_bf16 v[24:27], v[166:169], v[204:207], v[24:27]
	v_mfma_f32_16x16x32_bf16 v[20:23], v[174:177], v[204:207], v[20:23]
	v_mfma_f32_16x16x32_bf16 v[8:11], v[166:169], v[212:215], v[8:11]
	v_mfma_f32_16x16x32_bf16 v[4:7], v[174:177], v[212:215], v[4:7]
	v_mfma_f32_16x16x32_bf16 v[56:59], v[170:173], v[186:189], v[56:59]
	v_mfma_f32_16x16x32_bf16 v[52:55], v[178:181], v[186:189], v[52:55]
	v_mfma_f32_16x16x32_bf16 v[40:43], v[170:173], v[200:203], v[40:43]
	v_mfma_f32_16x16x32_bf16 v[36:39], v[178:181], v[200:203], v[36:39]
	v_mfma_f32_16x16x32_bf16 v[24:27], v[170:173], v[208:211], v[24:27]
	v_mfma_f32_16x16x32_bf16 v[20:23], v[178:181], v[208:211], v[20:23]
	v_mfma_f32_16x16x32_bf16 v[8:11], v[170:173], v[216:219], v[8:11]
	v_mfma_f32_16x16x32_bf16 v[4:7], v[178:181], v[216:219], v[4:7]
	s_barrier
	s_setprio 0
	s_add_i32 s0, 0, 0x18000
	v_add_u32_e32 v156, s0, v157
	s_add_i32 s6, 0, 0x1c000
	ds_read_b128 v[144:147], v156
	ds_read_b128 v[148:151], v156 offset:1024
	ds_read_b128 v[152:155], v156 offset:2048
	ds_read_b128 v[162:165], v156 offset:3072
	v_add_u32_e32 v156, s6, v157
	ds_read_b128 v[166:169], v156
	ds_read_b128 v[170:173], v156 offset:1024
	ds_read_b128 v[174:177], v156 offset:2048
	ds_read_b128 v[178:181], v156 offset:3072
	s_add_u32 s34, s34, 0x80000
	s_addc_u32 s35, s35, 0
	s_mov_b32 m0, s50
	v_lshl_add_u64 v[224:225], s[34:35], 0, v[138:139]
	ds_read_b128 v[182:185], v161 offset:32768
	ds_read_b128 v[186:189], v161 offset:33792
	ds_read_b128 v[190:193], v161 offset:34816
	ds_read_b128 v[200:203], v161 offset:35840
	ds_read_b128 v[204:207], v161 offset:36864
	ds_read_b128 v[208:211], v161 offset:37888
	ds_read_b128 v[212:215], v161 offset:38912
	ds_read_b128 v[216:219], v161 offset:39936
	global_load_lds_dwordx4 v[224:225], off
	s_mov_b32 m0, s51
	v_lshl_add_u64 v[224:225], s[34:35], 0, v[134:135]
	global_load_lds_dwordx4 v[224:225], off
	s_waitcnt vmcnt(8)
	s_waitcnt lgkmcnt(0)
	s_setprio 1
	s_barrier
	v_mfma_f32_16x16x32_bf16 v[128:131], v[144:147], v[182:185], v[128:131]
	v_mfma_f32_16x16x32_bf16 v[124:127], v[152:155], v[182:185], v[124:127]
	v_mfma_f32_16x16x32_bf16 v[112:115], v[144:147], v[190:193], v[112:115]
	v_mfma_f32_16x16x32_bf16 v[108:111], v[152:155], v[190:193], v[108:111]
	v_mfma_f32_16x16x32_bf16 v[96:99], v[144:147], v[204:207], v[96:99]
	v_mfma_f32_16x16x32_bf16 v[92:95], v[152:155], v[204:207], v[92:95]
	v_mfma_f32_16x16x32_bf16 v[80:83], v[144:147], v[212:215], v[80:83]
	v_mfma_f32_16x16x32_bf16 v[76:79], v[152:155], v[212:215], v[76:79]
	v_mfma_f32_16x16x32_bf16 v[128:131], v[148:151], v[186:189], v[128:131]
	v_mfma_f32_16x16x32_bf16 v[124:127], v[162:165], v[186:189], v[124:127]
	v_mfma_f32_16x16x32_bf16 v[112:115], v[148:151], v[200:203], v[112:115]
	v_mfma_f32_16x16x32_bf16 v[108:111], v[162:165], v[200:203], v[108:111]
	v_mfma_f32_16x16x32_bf16 v[96:99], v[148:151], v[208:211], v[96:99]
	v_mfma_f32_16x16x32_bf16 v[92:95], v[162:165], v[208:211], v[92:95]
	v_mfma_f32_16x16x32_bf16 v[80:83], v[148:151], v[216:219], v[80:83]
	v_mfma_f32_16x16x32_bf16 v[76:79], v[162:165], v[216:219], v[76:79]
	s_setprio 0
	s_setprio 1
	v_mfma_f32_16x16x32_bf16 v[120:123], v[166:169], v[182:185], v[120:123]
	v_mfma_f32_16x16x32_bf16 v[116:119], v[174:177], v[182:185], v[116:119]
	v_mfma_f32_16x16x32_bf16 v[104:107], v[166:169], v[190:193], v[104:107]
	v_mfma_f32_16x16x32_bf16 v[100:103], v[174:177], v[190:193], v[100:103]
	v_mfma_f32_16x16x32_bf16 v[88:91], v[166:169], v[204:207], v[88:91]
	v_mfma_f32_16x16x32_bf16 v[84:87], v[174:177], v[204:207], v[84:87]
	v_mfma_f32_16x16x32_bf16 v[72:75], v[166:169], v[212:215], v[72:75]
	v_mfma_f32_16x16x32_bf16 v[68:71], v[174:177], v[212:215], v[68:71]
	v_mfma_f32_16x16x32_bf16 v[120:123], v[170:173], v[186:189], v[120:123]
	v_mfma_f32_16x16x32_bf16 v[116:119], v[178:181], v[186:189], v[116:119]
	v_mfma_f32_16x16x32_bf16 v[104:107], v[170:173], v[200:203], v[104:107]
	v_mfma_f32_16x16x32_bf16 v[100:103], v[178:181], v[200:203], v[100:103]
	v_mfma_f32_16x16x32_bf16 v[88:91], v[170:173], v[208:211], v[88:91]
	v_mfma_f32_16x16x32_bf16 v[84:87], v[178:181], v[208:211], v[84:87]
	v_mfma_f32_16x16x32_bf16 v[72:75], v[170:173], v[216:219], v[72:75]
	v_mfma_f32_16x16x32_bf16 v[68:71], v[178:181], v[216:219], v[68:71]
	s_barrier
	s_setprio 0
	s_add_i32 s0, s0, s25
	v_lshl_add_u64 v[194:195], v[194:195], 0, s[90:91]
	s_mov_b32 m0, s0
	ds_read_b128 v[182:185], v161 offset:49152
	ds_read_b128 v[186:189], v161 offset:50176
	ds_read_b128 v[190:193], v161 offset:51200
	ds_read_b128 v[200:203], v161 offset:52224
	ds_read_b128 v[204:207], v161 offset:53248
	ds_read_b128 v[208:211], v161 offset:54272
	ds_read_b128 v[212:215], v161 offset:55296
	ds_read_b128 v[216:219], v161 offset:56320
	global_load_lds_dwordx4 v[194:195], off
	s_add_i32 m0, s0, 0x2000
	s_add_u32 s30, s30, 0x80080
	v_lshl_add_u64 v[194:195], v[198:199], 0, s[90:91]
	s_addc_u32 s31, s31, 0
	s_add_i32 s0, s6, s25
	global_load_lds_dwordx4 v[194:195], off
	s_mov_b32 m0, s0
	v_lshl_add_u64 v[194:195], s[30:31], 0, v[136:137]
	global_load_lds_dwordx4 v[194:195], off
	s_add_i32 m0, s0, 0x2000
	v_lshl_add_u64 v[194:195], s[30:31], 0, v[132:133]
	global_load_lds_dwordx4 v[194:195], off
	s_mov_b32 m0, s55
	v_lshl_add_u64 v[194:195], v[220:221], 0, s[90:91]
	global_load_lds_dwordx4 v[194:195], off
	s_mov_b32 m0, s60
	v_lshl_add_u64 v[194:195], v[222:223], 0, s[90:91]
	global_load_lds_dwordx4 v[194:195], off
	s_waitcnt vmcnt(8)
	s_waitcnt lgkmcnt(0)
	s_setprio 1
	s_barrier
	v_mfma_f32_16x16x32_bf16 v[64:67], v[144:147], v[182:185], v[64:67]
	v_mfma_f32_16x16x32_bf16 v[60:63], v[152:155], v[182:185], v[60:63]
	v_mfma_f32_16x16x32_bf16 v[48:51], v[144:147], v[190:193], v[48:51]
	v_mfma_f32_16x16x32_bf16 v[44:47], v[152:155], v[190:193], v[44:47]
	v_mfma_f32_16x16x32_bf16 v[32:35], v[144:147], v[204:207], v[32:35]
	v_mfma_f32_16x16x32_bf16 v[28:31], v[152:155], v[204:207], v[28:31]
	v_mfma_f32_16x16x32_bf16 v[16:19], v[144:147], v[212:215], v[16:19]
	v_mfma_f32_16x16x32_bf16 v[12:15], v[152:155], v[212:215], v[12:15]
	v_mfma_f32_16x16x32_bf16 v[64:67], v[148:151], v[186:189], v[64:67]
	v_mfma_f32_16x16x32_bf16 v[60:63], v[162:165], v[186:189], v[60:63]
	v_mfma_f32_16x16x32_bf16 v[48:51], v[148:151], v[200:203], v[48:51]
	v_mfma_f32_16x16x32_bf16 v[44:47], v[162:165], v[200:203], v[44:47]
	v_mfma_f32_16x16x32_bf16 v[32:35], v[148:151], v[208:211], v[32:35]
	v_mfma_f32_16x16x32_bf16 v[28:31], v[162:165], v[208:211], v[28:31]
	v_mfma_f32_16x16x32_bf16 v[16:19], v[148:151], v[216:219], v[16:19]
	v_mfma_f32_16x16x32_bf16 v[12:15], v[162:165], v[216:219], v[12:15]
	s_setprio 0
	s_setprio 1
	v_mfma_f32_16x16x32_bf16 v[56:59], v[166:169], v[182:185], v[56:59]
	v_mfma_f32_16x16x32_bf16 v[52:55], v[174:177], v[182:185], v[52:55]
	v_mfma_f32_16x16x32_bf16 v[40:43], v[166:169], v[190:193], v[40:43]
	v_mfma_f32_16x16x32_bf16 v[36:39], v[174:177], v[190:193], v[36:39]
	v_mfma_f32_16x16x32_bf16 v[24:27], v[166:169], v[204:207], v[24:27]
	v_mfma_f32_16x16x32_bf16 v[20:23], v[174:177], v[204:207], v[20:23]
	v_mfma_f32_16x16x32_bf16 v[8:11], v[166:169], v[212:215], v[8:11]
	v_mfma_f32_16x16x32_bf16 v[4:7], v[174:177], v[212:215], v[4:7]
	v_mfma_f32_16x16x32_bf16 v[56:59], v[170:173], v[186:189], v[56:59]
	v_mfma_f32_16x16x32_bf16 v[52:55], v[178:181], v[186:189], v[52:55]
	v_mfma_f32_16x16x32_bf16 v[40:43], v[170:173], v[200:203], v[40:43]
	v_mfma_f32_16x16x32_bf16 v[36:39], v[178:181], v[200:203], v[36:39]
	v_mfma_f32_16x16x32_bf16 v[24:27], v[170:173], v[208:211], v[24:27]
	v_mfma_f32_16x16x32_bf16 v[20:23], v[178:181], v[208:211], v[20:23]
	v_mfma_f32_16x16x32_bf16 v[8:11], v[170:173], v[216:219], v[8:11]
	v_mfma_f32_16x16x32_bf16 v[4:7], v[178:181], v[216:219], v[4:7]
	s_barrier
	s_setprio 0
	s_add_i32 s66, s66, 2
	s_add_u32 s36, s36, 0x100
	s_addc_u32 s37, s37, 0
	s_add_u32 s38, s38, 0x100
	s_addc_u32 s39, s39, 0
	s_cmp_gt_u32 s66, 29
	s_cbranch_scc0 .LBB0_1137
	s_and_b64 vcc, exec, s[20:21]
	s_cbranch_vccz .LBB0_1140
	s_barrier

.LBB0_1167:
	s_add_u32 s0, s36, 0xfff80080
	s_addc_u32 s6, s37, -1
	s_add_i32 s49, 0, 0x10000
	s_cmp_eq_u32 s67, 28
	s_cselect_b32 s35, s43, s6
	s_cselect_b32 s34, s65, s0
	v_add_u32_e32 v156, s49, v157
	s_cselect_b32 s31, s29, s39
	s_cselect_b32 s30, s66, s38
	s_add_i32 s0, 0, 0x14000
	ds_read_b128 v[144:147], v156
	ds_read_b128 v[148:151], v156 offset:1024
	ds_read_b128 v[152:155], v156 offset:2048
	ds_read_b128 v[162:165], v156 offset:3072
	v_add_u32_e32 v156, s0, v157
	ds_read_b128 v[166:169], v156
	ds_read_b128 v[170:173], v156 offset:1024
	ds_read_b128 v[174:177], v156 offset:2048
	ds_read_b128 v[178:181], v156 offset:3072
	v_lshl_add_u64 v[194:195], s[36:37], 0, v[140:141]
	s_add_i32 m0, s25, 0xc000
	ds_read_b128 v[182:185], v161
	ds_read_b128 v[186:189], v161 offset:1024
	ds_read_b128 v[190:193], v161 offset:2048
	ds_read_b128 v[200:203], v161 offset:3072
	ds_read_b128 v[204:207], v161 offset:4096
	ds_read_b128 v[208:211], v161 offset:5120
	ds_read_b128 v[212:215], v161 offset:6144
	ds_read_b128 v[216:219], v161 offset:7168
	global_load_lds_dwordx4 v[194:195], off
	s_add_i32 m0, s25, 0xe000
	v_lshl_add_u64 v[194:195], s[36:37], 0, v[142:143]
	global_load_lds_dwordx4 v[194:195], off
	s_waitcnt vmcnt(8)
	s_waitcnt lgkmcnt(0)
	s_setprio 1
	s_barrier
	v_mfma_f32_16x16x32_bf16 v[128:131], v[144:147], v[182:185], v[128:131]
	v_mfma_f32_16x16x32_bf16 v[124:127], v[152:155], v[182:185], v[124:127]
	v_mfma_f32_16x16x32_bf16 v[112:115], v[144:147], v[190:193], v[112:115]
	v_mfma_f32_16x16x32_bf16 v[108:111], v[152:155], v[190:193], v[108:111]
	v_mfma_f32_16x16x32_bf16 v[96:99], v[144:147], v[204:207], v[96:99]
	v_mfma_f32_16x16x32_bf16 v[92:95], v[152:155], v[204:207], v[92:95]
	v_mfma_f32_16x16x32_bf16 v[80:83], v[144:147], v[212:215], v[80:83]
	v_mfma_f32_16x16x32_bf16 v[76:79], v[152:155], v[212:215], v[76:79]
	v_mfma_f32_16x16x32_bf16 v[128:131], v[148:151], v[186:189], v[128:131]
	v_mfma_f32_16x16x32_bf16 v[124:127], v[162:165], v[186:189], v[124:127]
	v_mfma_f32_16x16x32_bf16 v[112:115], v[148:151], v[200:203], v[112:115]
	v_mfma_f32_16x16x32_bf16 v[108:111], v[162:165], v[200:203], v[108:111]
	v_mfma_f32_16x16x32_bf16 v[96:99], v[148:151], v[208:211], v[96:99]
	v_mfma_f32_16x16x32_bf16 v[92:95], v[162:165], v[208:211], v[92:95]
	v_mfma_f32_16x16x32_bf16 v[80:83], v[148:151], v[216:219], v[80:83]
	v_mfma_f32_16x16x32_bf16 v[76:79], v[162:165], v[216:219], v[76:79]
	s_setprio 0
	s_setprio 1
	v_mfma_f32_16x16x32_bf16 v[120:123], v[166:169], v[182:185], v[120:123]
	v_mfma_f32_16x16x32_bf16 v[116:119], v[174:177], v[182:185], v[116:119]
	v_mfma_f32_16x16x32_bf16 v[104:107], v[166:169], v[190:193], v[104:107]
	v_mfma_f32_16x16x32_bf16 v[100:103], v[174:177], v[190:193], v[100:103]
	v_mfma_f32_16x16x32_bf16 v[88:91], v[166:169], v[204:207], v[88:91]
	v_mfma_f32_16x16x32_bf16 v[84:87], v[174:177], v[204:207], v[84:87]
	v_mfma_f32_16x16x32_bf16 v[72:75], v[166:169], v[212:215], v[72:75]
	v_mfma_f32_16x16x32_bf16 v[68:71], v[174:177], v[212:215], v[68:71]
	v_mfma_f32_16x16x32_bf16 v[120:123], v[170:173], v[186:189], v[120:123]
	v_mfma_f32_16x16x32_bf16 v[116:119], v[178:181], v[186:189], v[116:119]
	v_mfma_f32_16x16x32_bf16 v[104:107], v[170:173], v[200:203], v[104:107]
	v_mfma_f32_16x16x32_bf16 v[100:103], v[178:181], v[200:203], v[100:103]
	v_mfma_f32_16x16x32_bf16 v[88:91], v[170:173], v[208:211], v[88:91]
	v_mfma_f32_16x16x32_bf16 v[84:87], v[178:181], v[208:211], v[84:87]
	v_mfma_f32_16x16x32_bf16 v[72:75], v[170:173], v[216:219], v[72:75]
	v_mfma_f32_16x16x32_bf16 v[68:71], v[178:181], v[216:219], v[68:71]
	s_barrier
	s_setprio 0
	s_add_i32 s6, s49, s1
	v_lshl_add_u64 v[194:195], s[30:31], 0, v[136:137]
	s_mov_b32 m0, s6
	ds_read_b128 v[182:185], v161 offset:16384
	ds_read_b128 v[186:189], v161 offset:17408
	ds_read_b128 v[190:193], v161 offset:18432
	ds_read_b128 v[200:203], v161 offset:19456
	ds_read_b128 v[204:207], v161 offset:20480
	ds_read_b128 v[208:211], v161 offset:21504
	ds_read_b128 v[212:215], v161 offset:22528
	ds_read_b128 v[216:219], v161 offset:23552
	global_load_lds_dwordx4 v[194:195], off
	s_add_i32 m0, s6, 0x2000
	s_add_u32 s68, s30, 0x80000
	v_lshl_add_u64 v[198:199], s[30:31], 0, v[132:133]
	s_addc_u32 s69, s31, 0
	s_add_i32 s0, s0, s1
	global_load_lds_dwordx4 v[198:199], off
	v_lshl_add_u64 v[220:221], s[68:69], 0, v[136:137]
	s_mov_b32 m0, s0
	global_load_lds_dwordx4 v[220:221], off
	s_add_i32 m0, s0, 0x2000
	v_lshl_add_u64 v[220:221], s[68:69], 0, v[132:133]
	global_load_lds_dwordx4 v[220:221], off
	s_mov_b32 m0, s25
	v_lshl_add_u64 v[220:221], s[34:35], 0, v[138:139]
	global_load_lds_dwordx4 v[220:221], off
	s_mov_b32 m0, s33
	v_lshl_add_u64 v[222:223], s[34:35], 0, v[134:135]
	global_load_lds_dwordx4 v[222:223], off
	s_waitcnt vmcnt(8)
	s_waitcnt lgkmcnt(0)
	s_setprio 1
	s_barrier
	v_mfma_f32_16x16x32_bf16 v[64:67], v[144:147], v[182:185], v[64:67]
	v_mfma_f32_16x16x32_bf16 v[60:63], v[152:155], v[182:185], v[60:63]
	v_mfma_f32_16x16x32_bf16 v[48:51], v[144:147], v[190:193], v[48:51]
	v_mfma_f32_16x16x32_bf16 v[44:47], v[152:155], v[190:193], v[44:47]
	v_mfma_f32_16x16x32_bf16 v[32:35], v[144:147], v[204:207], v[32:35]
	v_mfma_f32_16x16x32_bf16 v[28:31], v[152:155], v[204:207], v[28:31]
	v_mfma_f32_16x16x32_bf16 v[16:19], v[144:147], v[212:215], v[16:19]
	v_mfma_f32_16x16x32_bf16 v[12:15], v[152:155], v[212:215], v[12:15]
	v_mfma_f32_16x16x32_bf16 v[64:67], v[148:151], v[186:189], v[64:67]
	v_mfma_f32_16x16x32_bf16 v[60:63], v[162:165], v[186:189], v[60:63]
	v_mfma_f32_16x16x32_bf16 v[48:51], v[148:151], v[200:203], v[48:51]
	v_mfma_f32_16x16x32_bf16 v[44:47], v[162:165], v[200:203], v[44:47]
	v_mfma_f32_16x16x32_bf16 v[32:35], v[148:151], v[208:211], v[32:35]
	v_mfma_f32_16x16x32_bf16 v[28:31], v[162:165], v[208:211], v[28:31]
	v_mfma_f32_16x16x32_bf16 v[16:19], v[148:151], v[216:219], v[16:19]
	v_mfma_f32_16x16x32_bf16 v[12:15], v[162:165], v[216:219], v[12:15]
	s_setprio 0
	s_setprio 1
	v_mfma_f32_16x16x32_bf16 v[56:59], v[166:169], v[182:185], v[56:59]
	v_mfma_f32_16x16x32_bf16 v[52:55], v[174:177], v[182:185], v[52:55]
	v_mfma_f32_16x16x32_bf16 v[40:43], v[166:169], v[190:193], v[40:43]
	v_mfma_f32_16x16x32_bf16 v[36:39], v[174:177], v[190:193], v[36:39]
	v_mfma_f32_16x16x32_bf16 v[24:27], v[166:169], v[204:207], v[24:27]
	v_mfma_f32_16x16x32_bf16 v[20:23], v[174:177], v[204:207], v[20:23]
	v_mfma_f32_16x16x32_bf16 v[8:11], v[166:169], v[212:215], v[8:11]
	v_mfma_f32_16x16x32_bf16 v[4:7], v[174:177], v[212:215], v[4:7]
	v_mfma_f32_16x16x32_bf16 v[56:59], v[170:173], v[186:189], v[56:59]
	v_mfma_f32_16x16x32_bf16 v[52:55], v[178:181], v[186:189], v[52:55]
	v_mfma_f32_16x16x32_bf16 v[40:43], v[170:173], v[200:203], v[40:43]
	v_mfma_f32_16x16x32_bf16 v[36:39], v[178:181], v[200:203], v[36:39]
	v_mfma_f32_16x16x32_bf16 v[24:27], v[170:173], v[208:211], v[24:27]
	v_mfma_f32_16x16x32_bf16 v[20:23], v[178:181], v[208:211], v[20:23]
	v_mfma_f32_16x16x32_bf16 v[8:11], v[170:173], v[216:219], v[8:11]
	v_mfma_f32_16x16x32_bf16 v[4:7], v[178:181], v[216:219], v[4:7]
	s_barrier
	s_setprio 0
	s_add_i32 s0, 0, 0x18000
	v_add_u32_e32 v156, s0, v157
	s_add_i32 s6, 0, 0x1c000
	ds_read_b128 v[144:147], v156
	ds_read_b128 v[148:151], v156 offset:1024
	ds_read_b128 v[152:155], v156 offset:2048
	ds_read_b128 v[162:165], v156 offset:3072
	v_add_u32_e32 v156, s6, v157
	ds_read_b128 v[166:169], v156
	ds_read_b128 v[170:173], v156 offset:1024
	ds_read_b128 v[174:177], v156 offset:2048
	ds_read_b128 v[178:181], v156 offset:3072
	s_add_u32 s34, s34, 0x80000
	s_addc_u32 s35, s35, 0
	s_mov_b32 m0, s40
	v_lshl_add_u64 v[224:225], s[34:35], 0, v[138:139]
	ds_read_b128 v[182:185], v161 offset:32768
	ds_read_b128 v[186:189], v161 offset:33792
	ds_read_b128 v[190:193], v161 offset:34816
	ds_read_b128 v[200:203], v161 offset:35840
	ds_read_b128 v[204:207], v161 offset:36864
	ds_read_b128 v[208:211], v161 offset:37888
	ds_read_b128 v[212:215], v161 offset:38912
	ds_read_b128 v[216:219], v161 offset:39936
	global_load_lds_dwordx4 v[224:225], off
	s_mov_b32 m0, s50
	v_lshl_add_u64 v[224:225], s[34:35], 0, v[134:135]
	global_load_lds_dwordx4 v[224:225], off
	s_waitcnt vmcnt(8)
	s_waitcnt lgkmcnt(0)
	s_setprio 1
	s_barrier
	v_mfma_f32_16x16x32_bf16 v[128:131], v[144:147], v[182:185], v[128:131]
	v_mfma_f32_16x16x32_bf16 v[124:127], v[152:155], v[182:185], v[124:127]
	v_mfma_f32_16x16x32_bf16 v[112:115], v[144:147], v[190:193], v[112:115]
	v_mfma_f32_16x16x32_bf16 v[108:111], v[152:155], v[190:193], v[108:111]
	v_mfma_f32_16x16x32_bf16 v[96:99], v[144:147], v[204:207], v[96:99]
	v_mfma_f32_16x16x32_bf16 v[92:95], v[152:155], v[204:207], v[92:95]
	v_mfma_f32_16x16x32_bf16 v[80:83], v[144:147], v[212:215], v[80:83]
	v_mfma_f32_16x16x32_bf16 v[76:79], v[152:155], v[212:215], v[76:79]
	v_mfma_f32_16x16x32_bf16 v[128:131], v[148:151], v[186:189], v[128:131]
	v_mfma_f32_16x16x32_bf16 v[124:127], v[162:165], v[186:189], v[124:127]
	v_mfma_f32_16x16x32_bf16 v[112:115], v[148:151], v[200:203], v[112:115]
	v_mfma_f32_16x16x32_bf16 v[108:111], v[162:165], v[200:203], v[108:111]
	v_mfma_f32_16x16x32_bf16 v[96:99], v[148:151], v[208:211], v[96:99]
	v_mfma_f32_16x16x32_bf16 v[92:95], v[162:165], v[208:211], v[92:95]
	v_mfma_f32_16x16x32_bf16 v[80:83], v[148:151], v[216:219], v[80:83]
	v_mfma_f32_16x16x32_bf16 v[76:79], v[162:165], v[216:219], v[76:79]
	s_setprio 0
	s_setprio 1
	v_mfma_f32_16x16x32_bf16 v[120:123], v[166:169], v[182:185], v[120:123]
	v_mfma_f32_16x16x32_bf16 v[116:119], v[174:177], v[182:185], v[116:119]
	v_mfma_f32_16x16x32_bf16 v[104:107], v[166:169], v[190:193], v[104:107]
	v_mfma_f32_16x16x32_bf16 v[100:103], v[174:177], v[190:193], v[100:103]
	v_mfma_f32_16x16x32_bf16 v[88:91], v[166:169], v[204:207], v[88:91]
	v_mfma_f32_16x16x32_bf16 v[84:87], v[174:177], v[204:207], v[84:87]
	v_mfma_f32_16x16x32_bf16 v[72:75], v[166:169], v[212:215], v[72:75]
	v_mfma_f32_16x16x32_bf16 v[68:71], v[174:177], v[212:215], v[68:71]
	v_mfma_f32_16x16x32_bf16 v[120:123], v[170:173], v[186:189], v[120:123]
	v_mfma_f32_16x16x32_bf16 v[116:119], v[178:181], v[186:189], v[116:119]
	v_mfma_f32_16x16x32_bf16 v[104:107], v[170:173], v[200:203], v[104:107]
	v_mfma_f32_16x16x32_bf16 v[100:103], v[178:181], v[200:203], v[100:103]
	v_mfma_f32_16x16x32_bf16 v[88:91], v[170:173], v[208:211], v[88:91]
	v_mfma_f32_16x16x32_bf16 v[84:87], v[178:181], v[208:211], v[84:87]
	v_mfma_f32_16x16x32_bf16 v[72:75], v[170:173], v[216:219], v[72:75]
	v_mfma_f32_16x16x32_bf16 v[68:71], v[178:181], v[216:219], v[68:71]
	s_barrier
	s_setprio 0
	s_add_i32 s0, s0, s1
	v_lshl_add_u64 v[194:195], v[194:195], 0, s[90:91]
	s_mov_b32 m0, s0
	ds_read_b128 v[182:185], v161 offset:49152
	ds_read_b128 v[186:189], v161 offset:50176
	ds_read_b128 v[190:193], v161 offset:51200
	ds_read_b128 v[200:203], v161 offset:52224
	ds_read_b128 v[204:207], v161 offset:53248
	ds_read_b128 v[208:211], v161 offset:54272
	ds_read_b128 v[212:215], v161 offset:55296
	ds_read_b128 v[216:219], v161 offset:56320
	global_load_lds_dwordx4 v[194:195], off
	s_add_i32 m0, s0, 0x2000
	s_add_u32 s30, s30, 0x80080
	v_lshl_add_u64 v[194:195], v[198:199], 0, s[90:91]
	s_addc_u32 s31, s31, 0
	s_add_i32 s0, s6, s1
	global_load_lds_dwordx4 v[194:195], off
	s_mov_b32 m0, s0
	v_lshl_add_u64 v[194:195], s[30:31], 0, v[136:137]
	global_load_lds_dwordx4 v[194:195], off
	s_add_i32 m0, s0, 0x2000
	v_lshl_add_u64 v[194:195], s[30:31], 0, v[132:133]
	global_load_lds_dwordx4 v[194:195], off
	s_mov_b32 m0, s51
	v_lshl_add_u64 v[194:195], v[220:221], 0, s[90:91]
	global_load_lds_dwordx4 v[194:195], off
	s_mov_b32 m0, s55
	v_lshl_add_u64 v[194:195], v[222:223], 0, s[90:91]
	global_load_lds_dwordx4 v[194:195], off
	s_waitcnt vmcnt(8)
	s_waitcnt lgkmcnt(0)
	s_setprio 1
	s_barrier
	v_mfma_f32_16x16x32_bf16 v[64:67], v[144:147], v[182:185], v[64:67]
	v_mfma_f32_16x16x32_bf16 v[60:63], v[152:155], v[182:185], v[60:63]
	v_mfma_f32_16x16x32_bf16 v[48:51], v[144:147], v[190:193], v[48:51]
	v_mfma_f32_16x16x32_bf16 v[44:47], v[152:155], v[190:193], v[44:47]
	v_mfma_f32_16x16x32_bf16 v[32:35], v[144:147], v[204:207], v[32:35]
	v_mfma_f32_16x16x32_bf16 v[28:31], v[152:155], v[204:207], v[28:31]
	v_mfma_f32_16x16x32_bf16 v[16:19], v[144:147], v[212:215], v[16:19]
	v_mfma_f32_16x16x32_bf16 v[12:15], v[152:155], v[212:215], v[12:15]
	v_mfma_f32_16x16x32_bf16 v[64:67], v[148:151], v[186:189], v[64:67]
	v_mfma_f32_16x16x32_bf16 v[60:63], v[162:165], v[186:189], v[60:63]
	v_mfma_f32_16x16x32_bf16 v[48:51], v[148:151], v[200:203], v[48:51]
	v_mfma_f32_16x16x32_bf16 v[44:47], v[162:165], v[200:203], v[44:47]
	v_mfma_f32_16x16x32_bf16 v[32:35], v[148:151], v[208:211], v[32:35]
	v_mfma_f32_16x16x32_bf16 v[28:31], v[162:165], v[208:211], v[28:31]
	v_mfma_f32_16x16x32_bf16 v[16:19], v[148:151], v[216:219], v[16:19]
	v_mfma_f32_16x16x32_bf16 v[12:15], v[162:165], v[216:219], v[12:15]
	s_setprio 0
	s_setprio 1
	v_mfma_f32_16x16x32_bf16 v[56:59], v[166:169], v[182:185], v[56:59]
	v_mfma_f32_16x16x32_bf16 v[52:55], v[174:177], v[182:185], v[52:55]
	v_mfma_f32_16x16x32_bf16 v[40:43], v[166:169], v[190:193], v[40:43]
	v_mfma_f32_16x16x32_bf16 v[36:39], v[174:177], v[190:193], v[36:39]
	v_mfma_f32_16x16x32_bf16 v[24:27], v[166:169], v[204:207], v[24:27]
	v_mfma_f32_16x16x32_bf16 v[20:23], v[174:177], v[204:207], v[20:23]
	v_mfma_f32_16x16x32_bf16 v[8:11], v[166:169], v[212:215], v[8:11]
	v_mfma_f32_16x16x32_bf16 v[4:7], v[174:177], v[212:215], v[4:7]
	v_mfma_f32_16x16x32_bf16 v[56:59], v[170:173], v[186:189], v[56:59]
	v_mfma_f32_16x16x32_bf16 v[52:55], v[178:181], v[186:189], v[52:55]
	v_mfma_f32_16x16x32_bf16 v[40:43], v[170:173], v[200:203], v[40:43]
	v_mfma_f32_16x16x32_bf16 v[36:39], v[178:181], v[200:203], v[36:39]
	v_mfma_f32_16x16x32_bf16 v[24:27], v[170:173], v[208:211], v[24:27]
	v_mfma_f32_16x16x32_bf16 v[20:23], v[178:181], v[208:211], v[20:23]
	v_mfma_f32_16x16x32_bf16 v[8:11], v[170:173], v[216:219], v[8:11]
	v_mfma_f32_16x16x32_bf16 v[4:7], v[178:181], v[216:219], v[4:7]
	s_barrier
	s_setprio 0
	s_add_i32 s67, s67, 2
	s_add_u32 s36, s36, 0x100
	s_addc_u32 s37, s37, 0
	s_add_u32 s38, s38, 0x100
	s_addc_u32 s39, s39, 0
	s_cmp_gt_u32 s67, 29
	s_cbranch_scc0 .LBB0_1167
	s_and_b64 vcc, exec, s[20:21]
	s_cbranch_vccz .LBB0_1170
	s_barrier

.LBB0_1186:
	s_add_u32 s0, s64, s30
	s_addc_u32 s6, s65, 0
	s_add_u32 s31, s0, 0x100
	s_addc_u32 s38, s6, 0
	s_and_b64 s[34:35], s[36:37], exec
	s_cselect_b32 s69, s29, s38
	s_cselect_b32 s68, s77, s31
	s_add_u32 s30, s62, s30
	s_addc_u32 s31, s63, 0
	s_add_u32 s34, s30, 0x100
	s_addc_u32 s35, s31, 0
	s_add_i32 s82, 0, 0x10000
	s_and_b64 s[30:31], s[36:37], exec
	s_cselect_b32 s53, s23, s35
	s_cselect_b32 s52, s78, s34
	s_add_i32 s37, 0, 0x14000
	s_add_u32 s34, s0, 0x10080
	s_addc_u32 s35, s6, 0
	s_add_i32 s84, s82, s4
	s_add_i32 m0, s46, 0xc000
	s_add_i32 s85, s46, 0xe000
	s_add_i32 s6, s84, 0x2000
	v_add_u32_e32 v140, s82, v142
	s_add_u32 s30, s52, 0x10000
	ds_read_b128 v[146:149], v140
	ds_read_b128 v[150:153], v140 offset:1024
	ds_read_b128 v[154:157], v140 offset:2048
	ds_read_b128 v[158:161], v140 offset:3072
	v_add_u32_e32 v140, s37, v142
	s_addc_u32 s31, s53, 0
	s_add_i32 s49, s37, s4
	ds_read_b128 v[162:165], v140
	ds_read_b128 v[166:169], v140 offset:1024
	ds_read_b128 v[170:173], v140 offset:2048
	ds_read_b128 v[174:177], v140 offset:3072
	s_add_i32 s81, s49, 0x2000
	s_add_i32 s54, 0, 0x18000
	s_add_i32 s73, 0, 0x1c000
	s_add_u32 s38, s68, 0x10000
	s_addc_u32 s39, s69, 0
	s_add_i32 s0, s54, s4
	s_add_i32 s80, s0, 0x2000
	s_add_u32 s36, s52, 0x10080
	s_addc_u32 s37, s53, 0
	s_add_i32 s83, s73, s4
	s_add_i32 s82, s83, 0x2000
	v_lshl_add_u64 v[140:141], s[34:35], 0, v[138:139]
	ds_read_b128 v[178:181], v144
	ds_read_b128 v[182:185], v144 offset:1024
	ds_read_b128 v[186:189], v144 offset:2048
	ds_read_b128 v[190:193], v144 offset:3072
	ds_read_b128 v[200:203], v144 offset:4096
	ds_read_b128 v[204:207], v144 offset:5120
	ds_read_b128 v[208:211], v144 offset:6144
	ds_read_b128 v[212:215], v144 offset:7168
	global_load_lds_dwordx4 v[140:141], off
	s_mov_b32 m0, s85
	v_lshl_add_u64 v[140:141], s[34:35], 0, v[134:135]
	global_load_lds_dwordx4 v[140:141], off
	s_waitcnt vmcnt(8)
	s_waitcnt lgkmcnt(0)
	s_setprio 1
	s_barrier
	v_mfma_f32_16x16x32_bf16 v[128:131], v[146:149], v[178:181], v[128:131]
	v_mfma_f32_16x16x32_bf16 v[124:127], v[154:157], v[178:181], v[124:127]
	v_mfma_f32_16x16x32_bf16 v[120:123], v[146:149], v[186:189], v[120:123]
	v_mfma_f32_16x16x32_bf16 v[112:115], v[154:157], v[186:189], v[112:115]
	v_mfma_f32_16x16x32_bf16 v[104:107], v[146:149], v[200:203], v[104:107]
	v_mfma_f32_16x16x32_bf16 v[96:99], v[154:157], v[200:203], v[96:99]
	v_mfma_f32_16x16x32_bf16 v[88:91], v[146:149], v[208:211], v[88:91]
	v_mfma_f32_16x16x32_bf16 v[80:83], v[154:157], v[208:211], v[80:83]
	v_mfma_f32_16x16x32_bf16 v[128:131], v[150:153], v[182:185], v[128:131]
	v_mfma_f32_16x16x32_bf16 v[124:127], v[158:161], v[182:185], v[124:127]
	v_mfma_f32_16x16x32_bf16 v[120:123], v[150:153], v[190:193], v[120:123]
	v_mfma_f32_16x16x32_bf16 v[112:115], v[158:161], v[190:193], v[112:115]
	v_mfma_f32_16x16x32_bf16 v[104:107], v[150:153], v[204:207], v[104:107]
	v_mfma_f32_16x16x32_bf16 v[96:99], v[158:161], v[204:207], v[96:99]
	v_mfma_f32_16x16x32_bf16 v[88:91], v[150:153], v[212:215], v[88:91]
	v_mfma_f32_16x16x32_bf16 v[80:83], v[158:161], v[212:215], v[80:83]
	s_setprio 0
	s_setprio 1
	v_mfma_f32_16x16x32_bf16 v[116:119], v[162:165], v[178:181], v[116:119]
	v_mfma_f32_16x16x32_bf16 v[108:111], v[170:173], v[178:181], v[108:111]
	v_mfma_f32_16x16x32_bf16 v[100:103], v[162:165], v[186:189], v[100:103]
	v_mfma_f32_16x16x32_bf16 v[92:95], v[170:173], v[186:189], v[92:95]
	v_mfma_f32_16x16x32_bf16 v[84:87], v[162:165], v[200:203], v[84:87]
	v_mfma_f32_16x16x32_bf16 v[76:79], v[170:173], v[200:203], v[76:79]
	v_mfma_f32_16x16x32_bf16 v[72:75], v[162:165], v[208:211], v[72:75]
	v_mfma_f32_16x16x32_bf16 v[68:71], v[170:173], v[208:211], v[68:71]
	v_mfma_f32_16x16x32_bf16 v[116:119], v[166:169], v[182:185], v[116:119]
	v_mfma_f32_16x16x32_bf16 v[108:111], v[174:177], v[182:185], v[108:111]
	v_mfma_f32_16x16x32_bf16 v[100:103], v[166:169], v[190:193], v[100:103]
	v_mfma_f32_16x16x32_bf16 v[92:95], v[174:177], v[190:193], v[92:95]
	v_mfma_f32_16x16x32_bf16 v[84:87], v[166:169], v[204:207], v[84:87]
	v_mfma_f32_16x16x32_bf16 v[76:79], v[174:177], v[204:207], v[76:79]
	v_mfma_f32_16x16x32_bf16 v[72:75], v[166:169], v[212:215], v[72:75]
	v_mfma_f32_16x16x32_bf16 v[68:71], v[174:177], v[212:215], v[68:71]
	s_barrier
	s_setprio 0
	s_mov_b32 m0, s84
	v_lshl_add_u64 v[140:141], s[52:53], 0, v[136:137]
	ds_read_b128 v[178:181], v144 offset:16384
	ds_read_b128 v[182:185], v144 offset:17408
	ds_read_b128 v[186:189], v144 offset:18432
	ds_read_b128 v[190:193], v144 offset:19456
	ds_read_b128 v[200:203], v144 offset:20480
	ds_read_b128 v[204:207], v144 offset:21504
	ds_read_b128 v[208:211], v144 offset:22528
	ds_read_b128 v[212:215], v144 offset:23552
	global_load_lds_dwordx4 v[140:141], off
	v_lshl_add_u64 v[194:195], s[52:53], 0, v[132:133]
	s_mov_b32 m0, s6
	v_lshl_add_u64 v[198:199], s[30:31], 0, v[136:137]
	global_load_lds_dwordx4 v[194:195], off
	s_mov_b32 m0, s49
	global_load_lds_dwordx4 v[198:199], off
	s_mov_b32 m0, s81
	v_lshl_add_u64 v[198:199], s[30:31], 0, v[132:133]
	global_load_lds_dwordx4 v[198:199], off
	s_mov_b32 m0, s46
	v_lshl_add_u64 v[198:199], s[68:69], 0, v[138:139]
	global_load_lds_dwordx4 v[198:199], off
	s_mov_b32 m0, s47
	v_lshl_add_u64 v[216:217], s[68:69], 0, v[134:135]
	global_load_lds_dwordx4 v[216:217], off
	s_waitcnt vmcnt(8)
	s_waitcnt lgkmcnt(0)
	s_setprio 1
	s_barrier
	v_mfma_f32_16x16x32_bf16 v[64:67], v[146:149], v[178:181], v[64:67]
	v_mfma_f32_16x16x32_bf16 v[60:63], v[154:157], v[178:181], v[60:63]
	v_mfma_f32_16x16x32_bf16 v[56:59], v[146:149], v[186:189], v[56:59]
	v_mfma_f32_16x16x32_bf16 v[48:51], v[154:157], v[186:189], v[48:51]
	v_mfma_f32_16x16x32_bf16 v[40:43], v[146:149], v[200:203], v[40:43]
	v_mfma_f32_16x16x32_bf16 v[32:35], v[154:157], v[200:203], v[32:35]
	v_mfma_f32_16x16x32_bf16 v[24:27], v[146:149], v[208:211], v[24:27]
	v_mfma_f32_16x16x32_bf16 v[16:19], v[154:157], v[208:211], v[16:19]
	v_mfma_f32_16x16x32_bf16 v[64:67], v[150:153], v[182:185], v[64:67]
	v_mfma_f32_16x16x32_bf16 v[60:63], v[158:161], v[182:185], v[60:63]
	v_mfma_f32_16x16x32_bf16 v[56:59], v[150:153], v[190:193], v[56:59]
	v_mfma_f32_16x16x32_bf16 v[48:51], v[158:161], v[190:193], v[48:51]
	v_mfma_f32_16x16x32_bf16 v[40:43], v[150:153], v[204:207], v[40:43]
	v_mfma_f32_16x16x32_bf16 v[32:35], v[158:161], v[204:207], v[32:35]
	v_mfma_f32_16x16x32_bf16 v[24:27], v[150:153], v[212:215], v[24:27]
	v_mfma_f32_16x16x32_bf16 v[16:19], v[158:161], v[212:215], v[16:19]
	s_setprio 0
	s_setprio 1
	v_mfma_f32_16x16x32_bf16 v[52:55], v[162:165], v[178:181], v[52:55]
	v_mfma_f32_16x16x32_bf16 v[44:47], v[170:173], v[178:181], v[44:47]
	v_mfma_f32_16x16x32_bf16 v[36:39], v[162:165], v[186:189], v[36:39]
	v_mfma_f32_16x16x32_bf16 v[28:31], v[170:173], v[186:189], v[28:31]
	v_mfma_f32_16x16x32_bf16 v[20:23], v[162:165], v[200:203], v[20:23]
	v_mfma_f32_16x16x32_bf16 v[12:15], v[170:173], v[200:203], v[12:15]
	v_mfma_f32_16x16x32_bf16 v[8:11], v[162:165], v[208:211], v[8:11]
	v_mfma_f32_16x16x32_bf16 v[4:7], v[170:173], v[208:211], v[4:7]
	v_mfma_f32_16x16x32_bf16 v[52:55], v[166:169], v[182:185], v[52:55]
	v_mfma_f32_16x16x32_bf16 v[44:47], v[174:177], v[182:185], v[44:47]
	v_mfma_f32_16x16x32_bf16 v[36:39], v[166:169], v[190:193], v[36:39]
	v_mfma_f32_16x16x32_bf16 v[28:31], v[174:177], v[190:193], v[28:31]
	v_mfma_f32_16x16x32_bf16 v[20:23], v[166:169], v[204:207], v[20:23]
	v_mfma_f32_16x16x32_bf16 v[12:15], v[174:177], v[204:207], v[12:15]
	v_mfma_f32_16x16x32_bf16 v[8:11], v[166:169], v[212:215], v[8:11]
	v_mfma_f32_16x16x32_bf16 v[4:7], v[174:177], v[212:215], v[4:7]
	s_barrier
	s_setprio 0
	v_add_u32_e32 v145, s54, v142
	ds_read_b128 v[146:149], v145
	ds_read_b128 v[150:153], v145 offset:1024
	ds_read_b128 v[154:157], v145 offset:2048
	ds_read_b128 v[158:161], v145 offset:3072
	v_add_u32_e32 v145, s73, v142
	ds_read_b128 v[162:165], v145
	ds_read_b128 v[166:169], v145 offset:1024
	ds_read_b128 v[170:173], v145 offset:2048
	ds_read_b128 v[174:177], v145 offset:3072
	s_mov_b32 m0, s50
	v_lshl_add_u64 v[218:219], s[38:39], 0, v[138:139]
	ds_read_b128 v[178:181], v144 offset:32768
	ds_read_b128 v[182:185], v144 offset:33792
	ds_read_b128 v[186:189], v144 offset:34816
	ds_read_b128 v[190:193], v144 offset:35840
	ds_read_b128 v[200:203], v144 offset:36864
	ds_read_b128 v[204:207], v144 offset:37888
	ds_read_b128 v[208:211], v144 offset:38912
	ds_read_b128 v[212:215], v144 offset:39936
	global_load_lds_dwordx4 v[218:219], off
	s_mov_b32 m0, s51
	v_lshl_add_u64 v[218:219], s[38:39], 0, v[134:135]
	global_load_lds_dwordx4 v[218:219], off
	s_waitcnt vmcnt(8)
	s_waitcnt lgkmcnt(0)
	s_setprio 1
	s_barrier
	v_mfma_f32_16x16x32_bf16 v[128:131], v[146:149], v[178:181], v[128:131]
	v_mfma_f32_16x16x32_bf16 v[124:127], v[154:157], v[178:181], v[124:127]
	v_mfma_f32_16x16x32_bf16 v[120:123], v[146:149], v[186:189], v[120:123]
	v_mfma_f32_16x16x32_bf16 v[112:115], v[154:157], v[186:189], v[112:115]
	v_mfma_f32_16x16x32_bf16 v[104:107], v[146:149], v[200:203], v[104:107]
	v_mfma_f32_16x16x32_bf16 v[96:99], v[154:157], v[200:203], v[96:99]
	v_mfma_f32_16x16x32_bf16 v[88:91], v[146:149], v[208:211], v[88:91]
	v_mfma_f32_16x16x32_bf16 v[80:83], v[154:157], v[208:211], v[80:83]
	v_mfma_f32_16x16x32_bf16 v[128:131], v[150:153], v[182:185], v[128:131]
	v_mfma_f32_16x16x32_bf16 v[124:127], v[158:161], v[182:185], v[124:127]
	v_mfma_f32_16x16x32_bf16 v[120:123], v[150:153], v[190:193], v[120:123]
	v_mfma_f32_16x16x32_bf16 v[112:115], v[158:161], v[190:193], v[112:115]
	v_mfma_f32_16x16x32_bf16 v[104:107], v[150:153], v[204:207], v[104:107]
	v_mfma_f32_16x16x32_bf16 v[96:99], v[158:161], v[204:207], v[96:99]
	v_mfma_f32_16x16x32_bf16 v[88:91], v[150:153], v[212:215], v[88:91]
	v_mfma_f32_16x16x32_bf16 v[80:83], v[158:161], v[212:215], v[80:83]
	s_setprio 0
	s_setprio 1
	v_mfma_f32_16x16x32_bf16 v[116:119], v[162:165], v[178:181], v[116:119]
	v_mfma_f32_16x16x32_bf16 v[108:111], v[170:173], v[178:181], v[108:111]
	v_mfma_f32_16x16x32_bf16 v[100:103], v[162:165], v[186:189], v[100:103]
	v_mfma_f32_16x16x32_bf16 v[92:95], v[170:173], v[186:189], v[92:95]
	v_mfma_f32_16x16x32_bf16 v[84:87], v[162:165], v[200:203], v[84:87]
	v_mfma_f32_16x16x32_bf16 v[76:79], v[170:173], v[200:203], v[76:79]
	v_mfma_f32_16x16x32_bf16 v[72:75], v[162:165], v[208:211], v[72:75]
	v_mfma_f32_16x16x32_bf16 v[68:71], v[170:173], v[208:211], v[68:71]
	v_mfma_f32_16x16x32_bf16 v[116:119], v[166:169], v[182:185], v[116:119]
	v_mfma_f32_16x16x32_bf16 v[108:111], v[174:177], v[182:185], v[108:111]
	v_mfma_f32_16x16x32_bf16 v[100:103], v[166:169], v[190:193], v[100:103]
	v_mfma_f32_16x16x32_bf16 v[92:95], v[174:177], v[190:193], v[92:95]
	v_mfma_f32_16x16x32_bf16 v[84:87], v[166:169], v[204:207], v[84:87]
	v_mfma_f32_16x16x32_bf16 v[76:79], v[174:177], v[204:207], v[76:79]
	v_mfma_f32_16x16x32_bf16 v[72:75], v[166:169], v[212:215], v[72:75]
	v_mfma_f32_16x16x32_bf16 v[68:71], v[174:177], v[212:215], v[68:71]
	s_barrier
	s_setprio 0
	s_mov_b32 m0, s0
	v_lshl_add_u64 v[140:141], v[140:141], 0, s[90:91]
	ds_read_b128 v[178:181], v144 offset:49152
	ds_read_b128 v[182:185], v144 offset:50176
	ds_read_b128 v[186:189], v144 offset:51200
	ds_read_b128 v[190:193], v144 offset:52224
	ds_read_b128 v[200:203], v144 offset:53248
	ds_read_b128 v[204:207], v144 offset:54272
	ds_read_b128 v[208:211], v144 offset:55296
	ds_read_b128 v[212:215], v144 offset:56320
	global_load_lds_dwordx4 v[140:141], off
	s_mov_b32 m0, s80
	v_lshl_add_u64 v[140:141], v[194:195], 0, s[90:91]
	global_load_lds_dwordx4 v[140:141], off
	s_mov_b32 m0, s83
	v_lshl_add_u64 v[140:141], s[36:37], 0, v[136:137]
	global_load_lds_dwordx4 v[140:141], off
	s_mov_b32 m0, s82
	v_lshl_add_u64 v[140:141], s[36:37], 0, v[132:133]
	global_load_lds_dwordx4 v[140:141], off
	s_mov_b32 m0, s61
	v_lshl_add_u64 v[140:141], v[198:199], 0, s[90:91]
	global_load_lds_dwordx4 v[140:141], off
	s_mov_b32 m0, s74
	v_lshl_add_u64 v[140:141], v[216:217], 0, s[90:91]
	global_load_lds_dwordx4 v[140:141], off
	s_waitcnt vmcnt(8)
	s_waitcnt lgkmcnt(0)
	s_setprio 1
	s_barrier
	v_mfma_f32_16x16x32_bf16 v[64:67], v[146:149], v[178:181], v[64:67]
	v_mfma_f32_16x16x32_bf16 v[60:63], v[154:157], v[178:181], v[60:63]
	v_mfma_f32_16x16x32_bf16 v[56:59], v[146:149], v[186:189], v[56:59]
	v_mfma_f32_16x16x32_bf16 v[48:51], v[154:157], v[186:189], v[48:51]
	v_mfma_f32_16x16x32_bf16 v[40:43], v[146:149], v[200:203], v[40:43]
	v_mfma_f32_16x16x32_bf16 v[32:35], v[154:157], v[200:203], v[32:35]
	v_mfma_f32_16x16x32_bf16 v[24:27], v[146:149], v[208:211], v[24:27]
	v_mfma_f32_16x16x32_bf16 v[16:19], v[154:157], v[208:211], v[16:19]
	v_mfma_f32_16x16x32_bf16 v[64:67], v[150:153], v[182:185], v[64:67]
	v_mfma_f32_16x16x32_bf16 v[60:63], v[158:161], v[182:185], v[60:63]
	v_mfma_f32_16x16x32_bf16 v[56:59], v[150:153], v[190:193], v[56:59]
	v_mfma_f32_16x16x32_bf16 v[48:51], v[158:161], v[190:193], v[48:51]
	v_mfma_f32_16x16x32_bf16 v[40:43], v[150:153], v[204:207], v[40:43]
	v_mfma_f32_16x16x32_bf16 v[32:35], v[158:161], v[204:207], v[32:35]
	v_mfma_f32_16x16x32_bf16 v[24:27], v[150:153], v[212:215], v[24:27]
	v_mfma_f32_16x16x32_bf16 v[16:19], v[158:161], v[212:215], v[16:19]
	s_setprio 0
	s_setprio 1
	v_mfma_f32_16x16x32_bf16 v[52:55], v[162:165], v[178:181], v[52:55]
	v_mfma_f32_16x16x32_bf16 v[44:47], v[170:173], v[178:181], v[44:47]
	v_mfma_f32_16x16x32_bf16 v[36:39], v[162:165], v[186:189], v[36:39]
	v_mfma_f32_16x16x32_bf16 v[28:31], v[170:173], v[186:189], v[28:31]
	v_mfma_f32_16x16x32_bf16 v[20:23], v[162:165], v[200:203], v[20:23]
	v_mfma_f32_16x16x32_bf16 v[12:15], v[170:173], v[200:203], v[12:15]
	v_mfma_f32_16x16x32_bf16 v[8:11], v[162:165], v[208:211], v[8:11]
	v_mfma_f32_16x16x32_bf16 v[4:7], v[170:173], v[208:211], v[4:7]
	v_mfma_f32_16x16x32_bf16 v[52:55], v[166:169], v[182:185], v[52:55]
	v_mfma_f32_16x16x32_bf16 v[44:47], v[174:177], v[182:185], v[44:47]
	v_mfma_f32_16x16x32_bf16 v[36:39], v[166:169], v[190:193], v[36:39]
	v_mfma_f32_16x16x32_bf16 v[28:31], v[174:177], v[190:193], v[28:31]
	v_mfma_f32_16x16x32_bf16 v[20:23], v[166:169], v[204:207], v[20:23]
	v_mfma_f32_16x16x32_bf16 v[12:15], v[174:177], v[204:207], v[12:15]
	v_mfma_f32_16x16x32_bf16 v[8:11], v[166:169], v[212:215], v[8:11]
	v_mfma_f32_16x16x32_bf16 v[4:7], v[174:177], v[212:215], v[4:7]
	s_barrier
	s_setprio 0
	s_movk_i32 s30, 0x100
	s_andn2_b64 vcc, exec, s[66:67]
	s_mov_b64 s[36:37], -1
	s_mov_b64 s[66:67], 0
	s_cbranch_vccz .LBB0_1186
	s_and_b64 vcc, exec, s[20:21]
	s_cbranch_vccz .LBB0_1189
	s_barrier

.LBB0_1273:
	s_add_i32 s74, s30, 2
	s_add_u32 s62, s36, 0x100
	s_addc_u32 s63, s37, 0
	s_add_i32 s0, 0, 0x10000
	s_cmp_eq_u32 s29, s30
	s_cselect_b32 s35, s43, s63
	s_cselect_b32 s34, s42, s62
	s_cselect_b32 s31, s45, s72
	s_cselect_b32 s30, s44, s69
	s_add_i32 s6, 0, 0x14000
	v_add_u32_e32 v144, s0, v3
	v_add_u32_e32 v160, s6, v3
	ds_read_b128 v[124:127], v144
	ds_read_b128 v[128:131], v144 offset:1024
	ds_read_b128 v[140:143], v144 offset:2048
	ds_read_b128 v[144:147], v144 offset:3072
	ds_read_b128 v[148:151], v160
	ds_read_b128 v[152:155], v160 offset:1024
	ds_read_b128 v[156:159], v160 offset:2048
	ds_read_b128 v[160:163], v160 offset:3072
	v_lshl_add_u64 v[198:199], s[36:37], 0, v[212:213]
	s_add_i32 m0, s33, 0xc000
	ds_read_b128 v[164:167], v250
	ds_read_b128 v[168:171], v250 offset:1024
	ds_read_b128 v[172:175], v250 offset:2048
	ds_read_b128 v[176:179], v250 offset:3072
	ds_read_b128 v[180:183], v250 offset:4096
	ds_read_b128 v[184:187], v250 offset:5120
	ds_read_b128 v[188:191], v250 offset:6144
	ds_read_b128 v[192:195], v250 offset:7168
	global_load_lds_dwordx4 v[198:199], off
	s_add_i32 m0, s33, 0xe000
	v_lshl_add_u64 v[198:199], s[36:37], 0, v[214:215]
	global_load_lds_dwordx4 v[198:199], off
	s_waitcnt vmcnt(8)
	s_waitcnt lgkmcnt(0)
	s_setprio 1
	s_barrier
	v_mfma_f32_16x16x32_bf16 v[136:139], v[124:127], v[164:167], v[136:139]
	v_mfma_f32_16x16x32_bf16 v[132:135], v[140:143], v[164:167], v[132:135]
	v_mfma_f32_16x16x32_bf16 v[112:115], v[124:127], v[172:175], v[112:115]
	v_mfma_f32_16x16x32_bf16 v[108:111], v[140:143], v[172:175], v[108:111]
	v_mfma_f32_16x16x32_bf16 v[96:99], v[124:127], v[180:183], v[96:99]
	v_mfma_f32_16x16x32_bf16 v[92:95], v[140:143], v[180:183], v[92:95]
	v_mfma_f32_16x16x32_bf16 v[80:83], v[124:127], v[188:191], v[80:83]
	v_mfma_f32_16x16x32_bf16 v[76:79], v[140:143], v[188:191], v[76:79]
	v_mfma_f32_16x16x32_bf16 v[136:139], v[128:131], v[168:171], v[136:139]
	v_mfma_f32_16x16x32_bf16 v[132:135], v[144:147], v[168:171], v[132:135]
	v_mfma_f32_16x16x32_bf16 v[112:115], v[128:131], v[176:179], v[112:115]
	v_mfma_f32_16x16x32_bf16 v[108:111], v[144:147], v[176:179], v[108:111]
	v_mfma_f32_16x16x32_bf16 v[96:99], v[128:131], v[184:187], v[96:99]
	v_mfma_f32_16x16x32_bf16 v[92:95], v[144:147], v[184:187], v[92:95]
	v_mfma_f32_16x16x32_bf16 v[80:83], v[128:131], v[192:195], v[80:83]
	v_mfma_f32_16x16x32_bf16 v[76:79], v[144:147], v[192:195], v[76:79]
	s_setprio 0
	s_setprio 1
	v_mfma_f32_16x16x32_bf16 v[120:123], v[148:151], v[164:167], v[120:123]
	v_mfma_f32_16x16x32_bf16 v[116:119], v[156:159], v[164:167], v[116:119]
	v_mfma_f32_16x16x32_bf16 v[104:107], v[148:151], v[172:175], v[104:107]
	v_mfma_f32_16x16x32_bf16 v[100:103], v[156:159], v[172:175], v[100:103]
	v_mfma_f32_16x16x32_bf16 v[88:91], v[148:151], v[180:183], v[88:91]
	v_mfma_f32_16x16x32_bf16 v[84:87], v[156:159], v[180:183], v[84:87]
	v_mfma_f32_16x16x32_bf16 v[72:75], v[148:151], v[188:191], v[72:75]
	v_mfma_f32_16x16x32_bf16 v[68:71], v[156:159], v[188:191], v[68:71]
	v_mfma_f32_16x16x32_bf16 v[120:123], v[152:155], v[168:171], v[120:123]
	v_mfma_f32_16x16x32_bf16 v[116:119], v[160:163], v[168:171], v[116:119]
	v_mfma_f32_16x16x32_bf16 v[104:107], v[152:155], v[176:179], v[104:107]
	v_mfma_f32_16x16x32_bf16 v[100:103], v[160:163], v[176:179], v[100:103]
	v_mfma_f32_16x16x32_bf16 v[88:91], v[152:155], v[184:187], v[88:91]
	v_mfma_f32_16x16x32_bf16 v[84:87], v[160:163], v[184:187], v[84:87]
	v_mfma_f32_16x16x32_bf16 v[72:75], v[152:155], v[192:195], v[72:75]
	v_mfma_f32_16x16x32_bf16 v[68:71], v[160:163], v[192:195], v[68:71]
	s_barrier
	s_setprio 0
	s_add_i32 s0, s0, s27
	v_lshl_add_u64 v[198:199], s[30:31], 0, v[202:203]
	s_mov_b32 m0, s0
	ds_read_b128 v[164:167], v250 offset:16384
	ds_read_b128 v[168:171], v250 offset:17408
	ds_read_b128 v[172:175], v250 offset:18432
	ds_read_b128 v[176:179], v250 offset:19456
	ds_read_b128 v[180:183], v250 offset:20480
	ds_read_b128 v[184:187], v250 offset:21504
	ds_read_b128 v[188:191], v250 offset:22528
	ds_read_b128 v[192:195], v250 offset:23552
	global_load_lds_dwordx4 v[198:199], off
	s_add_i32 m0, s0, 0x2000
	s_add_u32 s36, s30, 0x204000
	v_lshl_add_u64 v[216:217], s[30:31], 0, v[206:207]
	s_addc_u32 s37, s31, 0
	s_add_i32 s0, s6, s27
	global_load_lds_dwordx4 v[216:217], off
	v_lshl_add_u64 v[218:219], s[36:37], 0, v[202:203]
	s_mov_b32 m0, s0
	global_load_lds_dwordx4 v[218:219], off
	s_add_i32 m0, s0, 0x2000
	v_lshl_add_u64 v[218:219], s[36:37], 0, v[206:207]
	global_load_lds_dwordx4 v[218:219], off
	s_mov_b32 m0, s33
	v_lshl_add_u64 v[218:219], s[34:35], 0, v[200:201]
	global_load_lds_dwordx4 v[218:219], off
	s_mov_b32 m0, s38
	v_lshl_add_u64 v[220:221], s[34:35], 0, v[204:205]
	global_load_lds_dwordx4 v[220:221], off
	s_waitcnt vmcnt(8)
	s_waitcnt lgkmcnt(0)
	s_setprio 1
	s_barrier
	v_mfma_f32_16x16x32_bf16 v[64:67], v[124:127], v[164:167], v[64:67]
	v_mfma_f32_16x16x32_bf16 v[60:63], v[140:143], v[164:167], v[60:63]
	v_mfma_f32_16x16x32_bf16 v[48:51], v[124:127], v[172:175], v[48:51]
	v_mfma_f32_16x16x32_bf16 v[44:47], v[140:143], v[172:175], v[44:47]
	v_mfma_f32_16x16x32_bf16 v[32:35], v[124:127], v[180:183], v[32:35]
	v_mfma_f32_16x16x32_bf16 v[28:31], v[140:143], v[180:183], v[28:31]
	v_mfma_f32_16x16x32_bf16 v[16:19], v[124:127], v[188:191], v[16:19]
	v_mfma_f32_16x16x32_bf16 v[12:15], v[140:143], v[188:191], v[12:15]
	v_mfma_f32_16x16x32_bf16 v[64:67], v[128:131], v[168:171], v[64:67]
	v_mfma_f32_16x16x32_bf16 v[60:63], v[144:147], v[168:171], v[60:63]
	v_mfma_f32_16x16x32_bf16 v[48:51], v[128:131], v[176:179], v[48:51]
	v_mfma_f32_16x16x32_bf16 v[44:47], v[144:147], v[176:179], v[44:47]
	v_mfma_f32_16x16x32_bf16 v[32:35], v[128:131], v[184:187], v[32:35]
	v_mfma_f32_16x16x32_bf16 v[28:31], v[144:147], v[184:187], v[28:31]
	v_mfma_f32_16x16x32_bf16 v[16:19], v[128:131], v[192:195], v[16:19]
	v_mfma_f32_16x16x32_bf16 v[12:15], v[144:147], v[192:195], v[12:15]
	s_setprio 0
	s_setprio 1
	v_mfma_f32_16x16x32_bf16 v[56:59], v[148:151], v[164:167], v[56:59]
	v_mfma_f32_16x16x32_bf16 v[52:55], v[156:159], v[164:167], v[52:55]
	v_mfma_f32_16x16x32_bf16 v[40:43], v[148:151], v[172:175], v[40:43]
	v_mfma_f32_16x16x32_bf16 v[36:39], v[156:159], v[172:175], v[36:39]
	v_mfma_f32_16x16x32_bf16 v[24:27], v[148:151], v[180:183], v[24:27]
	v_mfma_f32_16x16x32_bf16 v[20:23], v[156:159], v[180:183], v[20:23]
	v_mfma_f32_16x16x32_bf16 v[8:11], v[148:151], v[188:191], v[8:11]
	v_mfma_f32_16x16x32_bf16 v[4:7], v[156:159], v[188:191], v[4:7]
	v_mfma_f32_16x16x32_bf16 v[56:59], v[152:155], v[168:171], v[56:59]
	v_mfma_f32_16x16x32_bf16 v[52:55], v[160:163], v[168:171], v[52:55]
	v_mfma_f32_16x16x32_bf16 v[40:43], v[152:155], v[176:179], v[40:43]
	v_mfma_f32_16x16x32_bf16 v[36:39], v[160:163], v[176:179], v[36:39]
	v_mfma_f32_16x16x32_bf16 v[24:27], v[152:155], v[184:187], v[24:27]
	v_mfma_f32_16x16x32_bf16 v[20:23], v[160:163], v[184:187], v[20:23]
	v_mfma_f32_16x16x32_bf16 v[8:11], v[152:155], v[192:195], v[8:11]
	v_mfma_f32_16x16x32_bf16 v[4:7], v[160:163], v[192:195], v[4:7]
	s_barrier
	s_setprio 0
	s_add_i32 s0, 0, 0x18000
	s_add_i32 s6, 0, 0x1c000
	v_add_u32_e32 v144, s0, v3
	v_add_u32_e32 v160, s6, v3
	ds_read_b128 v[124:127], v144
	ds_read_b128 v[128:131], v144 offset:1024
	ds_read_b128 v[140:143], v144 offset:2048
	ds_read_b128 v[144:147], v144 offset:3072
	ds_read_b128 v[148:151], v160
	ds_read_b128 v[152:155], v160 offset:1024
	ds_read_b128 v[156:159], v160 offset:2048
	ds_read_b128 v[160:163], v160 offset:3072
	s_add_u32 s34, s34, 0x204000
	s_addc_u32 s35, s35, 0
	s_mov_b32 m0, s39
	v_lshl_add_u64 v[222:223], s[34:35], 0, v[200:201]
	ds_read_b128 v[164:167], v250 offset:32768
	ds_read_b128 v[168:171], v250 offset:33792
	ds_read_b128 v[172:175], v250 offset:34816
	ds_read_b128 v[176:179], v250 offset:35840
	ds_read_b128 v[180:183], v250 offset:36864
	ds_read_b128 v[184:187], v250 offset:37888
	ds_read_b128 v[188:191], v250 offset:38912
	ds_read_b128 v[192:195], v250 offset:39936
	global_load_lds_dwordx4 v[222:223], off
	s_mov_b32 m0, s40
	v_lshl_add_u64 v[222:223], s[34:35], 0, v[204:205]
	global_load_lds_dwordx4 v[222:223], off
	s_waitcnt vmcnt(8)
	s_waitcnt lgkmcnt(0)
	s_setprio 1
	s_barrier
	v_mfma_f32_16x16x32_bf16 v[136:139], v[124:127], v[164:167], v[136:139]
	v_mfma_f32_16x16x32_bf16 v[132:135], v[140:143], v[164:167], v[132:135]
	v_mfma_f32_16x16x32_bf16 v[112:115], v[124:127], v[172:175], v[112:115]
	v_mfma_f32_16x16x32_bf16 v[108:111], v[140:143], v[172:175], v[108:111]
	v_mfma_f32_16x16x32_bf16 v[96:99], v[124:127], v[180:183], v[96:99]
	v_mfma_f32_16x16x32_bf16 v[92:95], v[140:143], v[180:183], v[92:95]
	v_mfma_f32_16x16x32_bf16 v[80:83], v[124:127], v[188:191], v[80:83]
	v_mfma_f32_16x16x32_bf16 v[76:79], v[140:143], v[188:191], v[76:79]
	v_mfma_f32_16x16x32_bf16 v[136:139], v[128:131], v[168:171], v[136:139]
	v_mfma_f32_16x16x32_bf16 v[132:135], v[144:147], v[168:171], v[132:135]
	v_mfma_f32_16x16x32_bf16 v[112:115], v[128:131], v[176:179], v[112:115]
	v_mfma_f32_16x16x32_bf16 v[108:111], v[144:147], v[176:179], v[108:111]
	v_mfma_f32_16x16x32_bf16 v[96:99], v[128:131], v[184:187], v[96:99]
	v_mfma_f32_16x16x32_bf16 v[92:95], v[144:147], v[184:187], v[92:95]
	v_mfma_f32_16x16x32_bf16 v[80:83], v[128:131], v[192:195], v[80:83]
	v_mfma_f32_16x16x32_bf16 v[76:79], v[144:147], v[192:195], v[76:79]
	s_setprio 0
	s_setprio 1
	v_mfma_f32_16x16x32_bf16 v[120:123], v[148:151], v[164:167], v[120:123]
	v_mfma_f32_16x16x32_bf16 v[116:119], v[156:159], v[164:167], v[116:119]
	v_mfma_f32_16x16x32_bf16 v[104:107], v[148:151], v[172:175], v[104:107]
	v_mfma_f32_16x16x32_bf16 v[100:103], v[156:159], v[172:175], v[100:103]
	v_mfma_f32_16x16x32_bf16 v[88:91], v[148:151], v[180:183], v[88:91]
	v_mfma_f32_16x16x32_bf16 v[84:87], v[156:159], v[180:183], v[84:87]
	v_mfma_f32_16x16x32_bf16 v[72:75], v[148:151], v[188:191], v[72:75]
	v_mfma_f32_16x16x32_bf16 v[68:71], v[156:159], v[188:191], v[68:71]
	v_mfma_f32_16x16x32_bf16 v[120:123], v[152:155], v[168:171], v[120:123]
	v_mfma_f32_16x16x32_bf16 v[116:119], v[160:163], v[168:171], v[116:119]
	v_mfma_f32_16x16x32_bf16 v[104:107], v[152:155], v[176:179], v[104:107]
	v_mfma_f32_16x16x32_bf16 v[100:103], v[160:163], v[176:179], v[100:103]
	v_mfma_f32_16x16x32_bf16 v[88:91], v[152:155], v[184:187], v[88:91]
	v_mfma_f32_16x16x32_bf16 v[84:87], v[160:163], v[184:187], v[84:87]
	v_mfma_f32_16x16x32_bf16 v[72:75], v[152:155], v[192:195], v[72:75]
	v_mfma_f32_16x16x32_bf16 v[68:71], v[160:163], v[192:195], v[68:71]
	s_barrier
	s_setprio 0
	s_add_i32 s0, s0, s27
	v_lshl_add_u64 v[198:199], v[198:199], 0, s[90:91]
	s_mov_b32 m0, s0
	ds_read_b128 v[164:167], v250 offset:49152
	ds_read_b128 v[168:171], v250 offset:50176
	ds_read_b128 v[172:175], v250 offset:51200
	ds_read_b128 v[176:179], v250 offset:52224
	ds_read_b128 v[180:183], v250 offset:53248
	ds_read_b128 v[184:187], v250 offset:54272
	ds_read_b128 v[188:191], v250 offset:55296
	ds_read_b128 v[192:195], v250 offset:56320
	global_load_lds_dwordx4 v[198:199], off
	s_add_i32 m0, s0, 0x2000
	s_add_u32 s30, s30, 0x204080
	v_lshl_add_u64 v[198:199], v[216:217], 0, s[90:91]
	s_addc_u32 s31, s31, 0
	s_add_i32 s0, s6, s27
	global_load_lds_dwordx4 v[198:199], off
	s_mov_b32 m0, s0
	v_lshl_add_u64 v[198:199], s[30:31], 0, v[202:203]
	global_load_lds_dwordx4 v[198:199], off
	s_add_i32 m0, s0, 0x2000
	v_lshl_add_u64 v[198:199], s[30:31], 0, v[206:207]
	global_load_lds_dwordx4 v[198:199], off
	s_mov_b32 m0, s50
	v_lshl_add_u64 v[198:199], v[218:219], 0, s[90:91]
	global_load_lds_dwordx4 v[198:199], off
	s_mov_b32 m0, s51
	v_lshl_add_u64 v[198:199], v[220:221], 0, s[90:91]
	global_load_lds_dwordx4 v[198:199], off
	s_waitcnt vmcnt(8)
	s_waitcnt lgkmcnt(0)
	s_setprio 1
	s_barrier
	v_mfma_f32_16x16x32_bf16 v[64:67], v[124:127], v[164:167], v[64:67]
	v_mfma_f32_16x16x32_bf16 v[60:63], v[140:143], v[164:167], v[60:63]
	v_mfma_f32_16x16x32_bf16 v[48:51], v[124:127], v[172:175], v[48:51]
	v_mfma_f32_16x16x32_bf16 v[44:47], v[140:143], v[172:175], v[44:47]
	v_mfma_f32_16x16x32_bf16 v[32:35], v[124:127], v[180:183], v[32:35]
	v_mfma_f32_16x16x32_bf16 v[28:31], v[140:143], v[180:183], v[28:31]
	v_mfma_f32_16x16x32_bf16 v[16:19], v[124:127], v[188:191], v[16:19]
	v_mfma_f32_16x16x32_bf16 v[12:15], v[140:143], v[188:191], v[12:15]
	v_mfma_f32_16x16x32_bf16 v[64:67], v[128:131], v[168:171], v[64:67]
	v_mfma_f32_16x16x32_bf16 v[60:63], v[144:147], v[168:171], v[60:63]
	v_mfma_f32_16x16x32_bf16 v[48:51], v[128:131], v[176:179], v[48:51]
	v_mfma_f32_16x16x32_bf16 v[44:47], v[144:147], v[176:179], v[44:47]
	v_mfma_f32_16x16x32_bf16 v[32:35], v[128:131], v[184:187], v[32:35]
	v_mfma_f32_16x16x32_bf16 v[28:31], v[144:147], v[184:187], v[28:31]
	v_mfma_f32_16x16x32_bf16 v[16:19], v[128:131], v[192:195], v[16:19]
	v_mfma_f32_16x16x32_bf16 v[12:15], v[144:147], v[192:195], v[12:15]
	s_setprio 0
	s_setprio 1
	v_mfma_f32_16x16x32_bf16 v[56:59], v[148:151], v[164:167], v[56:59]
	v_mfma_f32_16x16x32_bf16 v[52:55], v[156:159], v[164:167], v[52:55]
	v_mfma_f32_16x16x32_bf16 v[40:43], v[148:151], v[172:175], v[40:43]
	v_mfma_f32_16x16x32_bf16 v[36:39], v[156:159], v[172:175], v[36:39]
	v_mfma_f32_16x16x32_bf16 v[24:27], v[148:151], v[180:183], v[24:27]
	v_mfma_f32_16x16x32_bf16 v[20:23], v[156:159], v[180:183], v[20:23]
	v_mfma_f32_16x16x32_bf16 v[8:11], v[148:151], v[188:191], v[8:11]
	v_mfma_f32_16x16x32_bf16 v[4:7], v[156:159], v[188:191], v[4:7]
	v_mfma_f32_16x16x32_bf16 v[56:59], v[152:155], v[168:171], v[56:59]
	v_mfma_f32_16x16x32_bf16 v[52:55], v[160:163], v[168:171], v[52:55]
	v_mfma_f32_16x16x32_bf16 v[40:43], v[152:155], v[176:179], v[40:43]
	v_mfma_f32_16x16x32_bf16 v[36:39], v[160:163], v[176:179], v[36:39]
	v_mfma_f32_16x16x32_bf16 v[24:27], v[152:155], v[184:187], v[24:27]
	v_mfma_f32_16x16x32_bf16 v[20:23], v[160:163], v[184:187], v[20:23]
	v_mfma_f32_16x16x32_bf16 v[8:11], v[152:155], v[192:195], v[8:11]
	v_mfma_f32_16x16x32_bf16 v[4:7], v[160:163], v[192:195], v[4:7]
	s_barrier
	s_setprio 0
	s_add_u32 s69, s69, 0x100
	s_addc_u32 s72, s72, 0
	s_cmp_ge_i32 s74, s61
	s_mov_b64 s[36:37], s[62:63]
	s_mov_b32 s30, s74
	s_cbranch_scc0 .LBB0_1273
	s_and_b64 vcc, exec, s[22:23]
	s_cbranch_vccz .LBB0_1276
	s_barrier

.LBB0_1395:
	s_add_u32 s0, s36, 0xfff80080
	s_addc_u32 s6, s37, -1
	s_add_i32 s49, 0, 0x10000
	s_cmp_eq_u32 s67, 28
	s_cselect_b32 s35, s25, s6
	s_cselect_b32 s34, s33, s0
	s_cselect_b32 s31, s43, s39
	s_cselect_b32 s30, s45, s38
	s_add_i32 s0, 0, 0x14000
	v_add_u32_e32 v144, s49, v3
	v_add_u32_e32 v176, s0, v3
	ds_read_b128 v[132:135], v144
	ds_read_b128 v[136:139], v144 offset:1024
	ds_read_b128 v[140:143], v144 offset:2048
	ds_read_b128 v[144:147], v144 offset:3072
	ds_read_b128 v[164:167], v176
	ds_read_b128 v[168:171], v176 offset:1024
	ds_read_b128 v[172:175], v176 offset:2048
	ds_read_b128 v[176:179], v176 offset:3072
	v_lshl_add_u64 v[198:199], s[36:37], 0, v[160:161]
	s_add_i32 m0, s47, 0xc000
	ds_read_b128 v[180:183], v190
	ds_read_b128 v[184:187], v190 offset:1024
	ds_read_b128 v[192:195], v190 offset:2048
	ds_read_b128 v[200:203], v190 offset:3072
	ds_read_b128 v[204:207], v190 offset:4096
	ds_read_b128 v[208:211], v190 offset:5120
	ds_read_b128 v[212:215], v190 offset:6144
	ds_read_b128 v[216:219], v190 offset:7168
	global_load_lds_dwordx4 v[198:199], off
	s_add_i32 m0, s47, 0xe000
	v_lshl_add_u64 v[198:199], s[36:37], 0, v[162:163]
	global_load_lds_dwordx4 v[198:199], off
	s_waitcnt vmcnt(8)
	s_waitcnt lgkmcnt(0)
	s_setprio 1
	s_barrier
	v_mfma_f32_16x16x32_bf16 v[128:131], v[132:135], v[180:183], v[128:131]
	v_mfma_f32_16x16x32_bf16 v[124:127], v[140:143], v[180:183], v[124:127]
	v_mfma_f32_16x16x32_bf16 v[112:115], v[132:135], v[192:195], v[112:115]
	v_mfma_f32_16x16x32_bf16 v[108:111], v[140:143], v[192:195], v[108:111]
	v_mfma_f32_16x16x32_bf16 v[96:99], v[132:135], v[204:207], v[96:99]
	v_mfma_f32_16x16x32_bf16 v[92:95], v[140:143], v[204:207], v[92:95]
	v_mfma_f32_16x16x32_bf16 v[80:83], v[132:135], v[212:215], v[80:83]
	v_mfma_f32_16x16x32_bf16 v[76:79], v[140:143], v[212:215], v[76:79]
	v_mfma_f32_16x16x32_bf16 v[128:131], v[136:139], v[184:187], v[128:131]
	v_mfma_f32_16x16x32_bf16 v[124:127], v[144:147], v[184:187], v[124:127]
	v_mfma_f32_16x16x32_bf16 v[112:115], v[136:139], v[200:203], v[112:115]
	v_mfma_f32_16x16x32_bf16 v[108:111], v[144:147], v[200:203], v[108:111]
	v_mfma_f32_16x16x32_bf16 v[96:99], v[136:139], v[208:211], v[96:99]
	v_mfma_f32_16x16x32_bf16 v[92:95], v[144:147], v[208:211], v[92:95]
	v_mfma_f32_16x16x32_bf16 v[80:83], v[136:139], v[216:219], v[80:83]
	v_mfma_f32_16x16x32_bf16 v[76:79], v[144:147], v[216:219], v[76:79]
	s_setprio 0
	s_setprio 1
	v_mfma_f32_16x16x32_bf16 v[120:123], v[164:167], v[180:183], v[120:123]
	v_mfma_f32_16x16x32_bf16 v[116:119], v[172:175], v[180:183], v[116:119]
	v_mfma_f32_16x16x32_bf16 v[104:107], v[164:167], v[192:195], v[104:107]
	v_mfma_f32_16x16x32_bf16 v[100:103], v[172:175], v[192:195], v[100:103]
	v_mfma_f32_16x16x32_bf16 v[88:91], v[164:167], v[204:207], v[88:91]
	v_mfma_f32_16x16x32_bf16 v[84:87], v[172:175], v[204:207], v[84:87]
	v_mfma_f32_16x16x32_bf16 v[72:75], v[164:167], v[212:215], v[72:75]
	v_mfma_f32_16x16x32_bf16 v[68:71], v[172:175], v[212:215], v[68:71]
	v_mfma_f32_16x16x32_bf16 v[120:123], v[168:171], v[184:187], v[120:123]
	v_mfma_f32_16x16x32_bf16 v[116:119], v[176:179], v[184:187], v[116:119]
	v_mfma_f32_16x16x32_bf16 v[104:107], v[168:171], v[200:203], v[104:107]
	v_mfma_f32_16x16x32_bf16 v[100:103], v[176:179], v[200:203], v[100:103]
	v_mfma_f32_16x16x32_bf16 v[88:91], v[168:171], v[208:211], v[88:91]
	v_mfma_f32_16x16x32_bf16 v[84:87], v[176:179], v[208:211], v[84:87]
	v_mfma_f32_16x16x32_bf16 v[72:75], v[168:171], v[216:219], v[72:75]
	v_mfma_f32_16x16x32_bf16 v[68:71], v[176:179], v[216:219], v[68:71]
	s_barrier
	s_setprio 0
	s_add_i32 s6, s49, s4
	v_lshl_add_u64 v[198:199], s[30:31], 0, v[152:153]
	s_mov_b32 m0, s6
	ds_read_b128 v[180:183], v190 offset:16384
	ds_read_b128 v[184:187], v190 offset:17408
	ds_read_b128 v[192:195], v190 offset:18432
	ds_read_b128 v[200:203], v190 offset:19456
	ds_read_b128 v[204:207], v190 offset:20480
	ds_read_b128 v[208:211], v190 offset:21504
	ds_read_b128 v[212:215], v190 offset:22528
	ds_read_b128 v[216:219], v190 offset:23552
	global_load_lds_dwordx4 v[198:199], off
	s_add_i32 m0, s6, 0x2000
	s_add_u32 s68, s30, 0x80000
	v_lshl_add_u64 v[220:221], s[30:31], 0, v[148:149]
	s_addc_u32 s69, s31, 0
	s_add_i32 s0, s0, s4
	global_load_lds_dwordx4 v[220:221], off
	v_lshl_add_u64 v[222:223], s[68:69], 0, v[152:153]
	s_mov_b32 m0, s0
	global_load_lds_dwordx4 v[222:223], off
	s_add_i32 m0, s0, 0x2000
	v_lshl_add_u64 v[222:223], s[68:69], 0, v[148:149]
	global_load_lds_dwordx4 v[222:223], off
	s_mov_b32 m0, s47
	v_lshl_add_u64 v[222:223], s[34:35], 0, v[154:155]
	global_load_lds_dwordx4 v[222:223], off
	s_mov_b32 m0, s52
	v_lshl_add_u64 v[224:225], s[34:35], 0, v[150:151]
	global_load_lds_dwordx4 v[224:225], off
	s_waitcnt vmcnt(8)
	s_waitcnt lgkmcnt(0)
	s_setprio 1
	s_barrier
	v_mfma_f32_16x16x32_bf16 v[64:67], v[132:135], v[180:183], v[64:67]
	v_mfma_f32_16x16x32_bf16 v[60:63], v[140:143], v[180:183], v[60:63]
	v_mfma_f32_16x16x32_bf16 v[48:51], v[132:135], v[192:195], v[48:51]
	v_mfma_f32_16x16x32_bf16 v[44:47], v[140:143], v[192:195], v[44:47]
	v_mfma_f32_16x16x32_bf16 v[32:35], v[132:135], v[204:207], v[32:35]
	v_mfma_f32_16x16x32_bf16 v[28:31], v[140:143], v[204:207], v[28:31]
	v_mfma_f32_16x16x32_bf16 v[16:19], v[132:135], v[212:215], v[16:19]
	v_mfma_f32_16x16x32_bf16 v[12:15], v[140:143], v[212:215], v[12:15]
	v_mfma_f32_16x16x32_bf16 v[64:67], v[136:139], v[184:187], v[64:67]
	v_mfma_f32_16x16x32_bf16 v[60:63], v[144:147], v[184:187], v[60:63]
	v_mfma_f32_16x16x32_bf16 v[48:51], v[136:139], v[200:203], v[48:51]
	v_mfma_f32_16x16x32_bf16 v[44:47], v[144:147], v[200:203], v[44:47]
	v_mfma_f32_16x16x32_bf16 v[32:35], v[136:139], v[208:211], v[32:35]
	v_mfma_f32_16x16x32_bf16 v[28:31], v[144:147], v[208:211], v[28:31]
	v_mfma_f32_16x16x32_bf16 v[16:19], v[136:139], v[216:219], v[16:19]
	v_mfma_f32_16x16x32_bf16 v[12:15], v[144:147], v[216:219], v[12:15]
	s_setprio 0
	s_setprio 1
	v_mfma_f32_16x16x32_bf16 v[56:59], v[164:167], v[180:183], v[56:59]
	v_mfma_f32_16x16x32_bf16 v[52:55], v[172:175], v[180:183], v[52:55]
	v_mfma_f32_16x16x32_bf16 v[40:43], v[164:167], v[192:195], v[40:43]
	v_mfma_f32_16x16x32_bf16 v[36:39], v[172:175], v[192:195], v[36:39]
	v_mfma_f32_16x16x32_bf16 v[24:27], v[164:167], v[204:207], v[24:27]
	v_mfma_f32_16x16x32_bf16 v[20:23], v[172:175], v[204:207], v[20:23]
	v_mfma_f32_16x16x32_bf16 v[8:11], v[164:167], v[212:215], v[8:11]
	v_mfma_f32_16x16x32_bf16 v[4:7], v[172:175], v[212:215], v[4:7]
	v_mfma_f32_16x16x32_bf16 v[56:59], v[168:171], v[184:187], v[56:59]
	v_mfma_f32_16x16x32_bf16 v[52:55], v[176:179], v[184:187], v[52:55]
	v_mfma_f32_16x16x32_bf16 v[40:43], v[168:171], v[200:203], v[40:43]
	v_mfma_f32_16x16x32_bf16 v[36:39], v[176:179], v[200:203], v[36:39]
	v_mfma_f32_16x16x32_bf16 v[24:27], v[168:171], v[208:211], v[24:27]
	v_mfma_f32_16x16x32_bf16 v[20:23], v[176:179], v[208:211], v[20:23]
	v_mfma_f32_16x16x32_bf16 v[8:11], v[168:171], v[216:219], v[8:11]
	v_mfma_f32_16x16x32_bf16 v[4:7], v[176:179], v[216:219], v[4:7]
	s_barrier
	s_setprio 0
	s_add_i32 s0, 0, 0x18000
	s_add_i32 s6, 0, 0x1c000
	v_add_u32_e32 v144, s0, v3
	v_add_u32_e32 v176, s6, v3
	ds_read_b128 v[132:135], v144
	ds_read_b128 v[136:139], v144 offset:1024
	ds_read_b128 v[140:143], v144 offset:2048
	ds_read_b128 v[144:147], v144 offset:3072
	ds_read_b128 v[164:167], v176
	ds_read_b128 v[168:171], v176 offset:1024
	ds_read_b128 v[172:175], v176 offset:2048
	ds_read_b128 v[176:179], v176 offset:3072
	s_add_u32 s34, s34, 0x80000
	s_addc_u32 s35, s35, 0
	s_mov_b32 m0, s53
	v_lshl_add_u64 v[226:227], s[34:35], 0, v[154:155]
	ds_read_b128 v[180:183], v190 offset:32768
	ds_read_b128 v[184:187], v190 offset:33792
	ds_read_b128 v[192:195], v190 offset:34816
	ds_read_b128 v[200:203], v190 offset:35840
	ds_read_b128 v[204:207], v190 offset:36864
	ds_read_b128 v[208:211], v190 offset:37888
	ds_read_b128 v[212:215], v190 offset:38912
	ds_read_b128 v[216:219], v190 offset:39936
	global_load_lds_dwordx4 v[226:227], off
	s_mov_b32 m0, s59
	v_lshl_add_u64 v[226:227], s[34:35], 0, v[150:151]
	global_load_lds_dwordx4 v[226:227], off
	s_waitcnt vmcnt(8)
	s_waitcnt lgkmcnt(0)
	s_setprio 1
	s_barrier
	v_mfma_f32_16x16x32_bf16 v[128:131], v[132:135], v[180:183], v[128:131]
	v_mfma_f32_16x16x32_bf16 v[124:127], v[140:143], v[180:183], v[124:127]
	v_mfma_f32_16x16x32_bf16 v[112:115], v[132:135], v[192:195], v[112:115]
	v_mfma_f32_16x16x32_bf16 v[108:111], v[140:143], v[192:195], v[108:111]
	v_mfma_f32_16x16x32_bf16 v[96:99], v[132:135], v[204:207], v[96:99]
	v_mfma_f32_16x16x32_bf16 v[92:95], v[140:143], v[204:207], v[92:95]
	v_mfma_f32_16x16x32_bf16 v[80:83], v[132:135], v[212:215], v[80:83]
	v_mfma_f32_16x16x32_bf16 v[76:79], v[140:143], v[212:215], v[76:79]
	v_mfma_f32_16x16x32_bf16 v[128:131], v[136:139], v[184:187], v[128:131]
	v_mfma_f32_16x16x32_bf16 v[124:127], v[144:147], v[184:187], v[124:127]
	v_mfma_f32_16x16x32_bf16 v[112:115], v[136:139], v[200:203], v[112:115]
	v_mfma_f32_16x16x32_bf16 v[108:111], v[144:147], v[200:203], v[108:111]
	v_mfma_f32_16x16x32_bf16 v[96:99], v[136:139], v[208:211], v[96:99]
	v_mfma_f32_16x16x32_bf16 v[92:95], v[144:147], v[208:211], v[92:95]
	v_mfma_f32_16x16x32_bf16 v[80:83], v[136:139], v[216:219], v[80:83]
	v_mfma_f32_16x16x32_bf16 v[76:79], v[144:147], v[216:219], v[76:79]
	s_setprio 0
	s_setprio 1
	v_mfma_f32_16x16x32_bf16 v[120:123], v[164:167], v[180:183], v[120:123]
	v_mfma_f32_16x16x32_bf16 v[116:119], v[172:175], v[180:183], v[116:119]
	v_mfma_f32_16x16x32_bf16 v[104:107], v[164:167], v[192:195], v[104:107]
	v_mfma_f32_16x16x32_bf16 v[100:103], v[172:175], v[192:195], v[100:103]
	v_mfma_f32_16x16x32_bf16 v[88:91], v[164:167], v[204:207], v[88:91]
	v_mfma_f32_16x16x32_bf16 v[84:87], v[172:175], v[204:207], v[84:87]
	v_mfma_f32_16x16x32_bf16 v[72:75], v[164:167], v[212:215], v[72:75]
	v_mfma_f32_16x16x32_bf16 v[68:71], v[172:175], v[212:215], v[68:71]
	v_mfma_f32_16x16x32_bf16 v[120:123], v[168:171], v[184:187], v[120:123]
	v_mfma_f32_16x16x32_bf16 v[116:119], v[176:179], v[184:187], v[116:119]
	v_mfma_f32_16x16x32_bf16 v[104:107], v[168:171], v[200:203], v[104:107]
	v_mfma_f32_16x16x32_bf16 v[100:103], v[176:179], v[200:203], v[100:103]
	v_mfma_f32_16x16x32_bf16 v[88:91], v[168:171], v[208:211], v[88:91]
	v_mfma_f32_16x16x32_bf16 v[84:87], v[176:179], v[208:211], v[84:87]
	v_mfma_f32_16x16x32_bf16 v[72:75], v[168:171], v[216:219], v[72:75]
	v_mfma_f32_16x16x32_bf16 v[68:71], v[176:179], v[216:219], v[68:71]
	s_barrier
	s_setprio 0
	s_add_i32 s0, s0, s4
	v_lshl_add_u64 v[198:199], v[198:199], 0, s[90:91]
	s_mov_b32 m0, s0
	ds_read_b128 v[180:183], v190 offset:49152
	ds_read_b128 v[184:187], v190 offset:50176
	ds_read_b128 v[192:195], v190 offset:51200
	ds_read_b128 v[200:203], v190 offset:52224
	ds_read_b128 v[204:207], v190 offset:53248
	ds_read_b128 v[208:211], v190 offset:54272
	ds_read_b128 v[212:215], v190 offset:55296
	ds_read_b128 v[216:219], v190 offset:56320
	global_load_lds_dwordx4 v[198:199], off
	s_add_i32 m0, s0, 0x2000
	s_add_u32 s30, s30, 0x80080
	v_lshl_add_u64 v[198:199], v[220:221], 0, s[90:91]
	s_addc_u32 s31, s31, 0
	s_add_i32 s0, s6, s4
	global_load_lds_dwordx4 v[198:199], off
	s_mov_b32 m0, s0
	v_lshl_add_u64 v[198:199], s[30:31], 0, v[152:153]
	global_load_lds_dwordx4 v[198:199], off
	s_add_i32 m0, s0, 0x2000
	v_lshl_add_u64 v[198:199], s[30:31], 0, v[148:149]
	global_load_lds_dwordx4 v[198:199], off
	s_mov_b32 m0, s40
	v_lshl_add_u64 v[198:199], v[222:223], 0, s[90:91]
	global_load_lds_dwordx4 v[198:199], off
	s_mov_b32 m0, s66
	v_lshl_add_u64 v[198:199], v[224:225], 0, s[90:91]
	global_load_lds_dwordx4 v[198:199], off
	s_waitcnt vmcnt(8)
	s_waitcnt lgkmcnt(0)
	s_setprio 1
	s_barrier
	v_mfma_f32_16x16x32_bf16 v[64:67], v[132:135], v[180:183], v[64:67]
	v_mfma_f32_16x16x32_bf16 v[60:63], v[140:143], v[180:183], v[60:63]
	v_mfma_f32_16x16x32_bf16 v[48:51], v[132:135], v[192:195], v[48:51]
	v_mfma_f32_16x16x32_bf16 v[44:47], v[140:143], v[192:195], v[44:47]
	v_mfma_f32_16x16x32_bf16 v[32:35], v[132:135], v[204:207], v[32:35]
	v_mfma_f32_16x16x32_bf16 v[28:31], v[140:143], v[204:207], v[28:31]
	v_mfma_f32_16x16x32_bf16 v[16:19], v[132:135], v[212:215], v[16:19]
	v_mfma_f32_16x16x32_bf16 v[12:15], v[140:143], v[212:215], v[12:15]
	v_mfma_f32_16x16x32_bf16 v[64:67], v[136:139], v[184:187], v[64:67]
	v_mfma_f32_16x16x32_bf16 v[60:63], v[144:147], v[184:187], v[60:63]
	v_mfma_f32_16x16x32_bf16 v[48:51], v[136:139], v[200:203], v[48:51]
	v_mfma_f32_16x16x32_bf16 v[44:47], v[144:147], v[200:203], v[44:47]
	v_mfma_f32_16x16x32_bf16 v[32:35], v[136:139], v[208:211], v[32:35]
	v_mfma_f32_16x16x32_bf16 v[28:31], v[144:147], v[208:211], v[28:31]
	v_mfma_f32_16x16x32_bf16 v[16:19], v[136:139], v[216:219], v[16:19]
	v_mfma_f32_16x16x32_bf16 v[12:15], v[144:147], v[216:219], v[12:15]
	s_setprio 0
	s_setprio 1
	v_mfma_f32_16x16x32_bf16 v[56:59], v[164:167], v[180:183], v[56:59]
	v_mfma_f32_16x16x32_bf16 v[52:55], v[172:175], v[180:183], v[52:55]
	v_mfma_f32_16x16x32_bf16 v[40:43], v[164:167], v[192:195], v[40:43]
	v_mfma_f32_16x16x32_bf16 v[36:39], v[172:175], v[192:195], v[36:39]
	v_mfma_f32_16x16x32_bf16 v[24:27], v[164:167], v[204:207], v[24:27]
	v_mfma_f32_16x16x32_bf16 v[20:23], v[172:175], v[204:207], v[20:23]
	v_mfma_f32_16x16x32_bf16 v[8:11], v[164:167], v[212:215], v[8:11]
	v_mfma_f32_16x16x32_bf16 v[4:7], v[172:175], v[212:215], v[4:7]
	v_mfma_f32_16x16x32_bf16 v[56:59], v[168:171], v[184:187], v[56:59]
	v_mfma_f32_16x16x32_bf16 v[52:55], v[176:179], v[184:187], v[52:55]
	v_mfma_f32_16x16x32_bf16 v[40:43], v[168:171], v[200:203], v[40:43]
	v_mfma_f32_16x16x32_bf16 v[36:39], v[176:179], v[200:203], v[36:39]
	v_mfma_f32_16x16x32_bf16 v[24:27], v[168:171], v[208:211], v[24:27]
	v_mfma_f32_16x16x32_bf16 v[20:23], v[176:179], v[208:211], v[20:23]
	v_mfma_f32_16x16x32_bf16 v[8:11], v[168:171], v[216:219], v[8:11]
	v_mfma_f32_16x16x32_bf16 v[4:7], v[176:179], v[216:219], v[4:7]
	s_barrier
	s_setprio 0
	s_add_i32 s67, s67, 2
	s_add_u32 s36, s36, 0x100
	s_addc_u32 s37, s37, 0
	s_add_u32 s38, s38, 0x100
	s_addc_u32 s39, s39, 0
	s_cmp_gt_u32 s67, 29
	s_cbranch_scc0 .LBB0_1395
	s_and_b64 vcc, exec, s[28:29]
	s_cbranch_vccz .LBB0_1398
	s_barrier

.LBB0_1441:
	s_add_u32 s0, s62, s30
	s_addc_u32 s6, s63, 0
	s_add_u32 s31, s0, 0x100
	s_addc_u32 s46, s6, 0
	s_and_b64 s[34:35], s[38:39], exec
	s_cselect_b32 s53, s43, s46
	s_cselect_b32 s52, s75, s31
	s_add_u32 s30, s66, s30
	s_addc_u32 s31, s67, 0
	s_add_u32 s34, s30, 0x100
	s_addc_u32 s35, s31, 0
	s_add_i32 s83, 0, 0x10000
	s_and_b64 s[30:31], s[38:39], exec
	s_cselect_b32 s31, s45, s35
	s_cselect_b32 s30, s81, s34
	s_add_i32 s39, 0, 0x14000
	s_add_u32 s46, s0, 0x80080
	s_addc_u32 s47, s6, 0
	s_add_i32 s49, s83, s4
	s_add_i32 m0, s59, 0xc000
	s_add_i32 s97, s59, 0xe000
	s_add_i32 s82, s49, 0x2000
	s_add_u32 s34, s30, 0x80000
	v_add_u32_e32 v144, s83, v3
	v_add_u32_e32 v172, s39, v3
	s_addc_u32 s35, s31, 0
	s_add_i32 s85, s39, s4
	ds_read_b128 v[132:135], v144
	ds_read_b128 v[136:139], v144 offset:1024
	ds_read_b128 v[140:143], v144 offset:2048
	ds_read_b128 v[144:147], v144 offset:3072
	ds_read_b128 v[160:163], v172
	ds_read_b128 v[164:167], v172 offset:1024
	ds_read_b128 v[168:171], v172 offset:2048
	ds_read_b128 v[172:175], v172 offset:3072
	s_add_i32 s84, s85, 0x2000
	s_add_i32 s0, 0, 0x18000
	s_add_i32 s54, 0, 0x1c000
	s_add_u32 vcc_lo, s52, 0x80000
	s_addc_u32 vcc_hi, s53, 0
	s_add_i32 s73, s0, s4
	s_add_i32 s6, s73, 0x2000
	s_add_u32 s38, s30, 0x80080
	s_addc_u32 s39, s31, 0
	s_add_i32 s83, s54, s4
	s_add_i32 s96, s83, 0x2000
	v_lshl_add_u64 v[198:199], s[46:47], 0, v[154:155]
	ds_read_b128 v[176:179], v186
	ds_read_b128 v[180:183], v186 offset:1024
	ds_read_b128 v[188:191], v186 offset:2048
	ds_read_b128 v[192:195], v186 offset:3072
	ds_read_b128 v[200:203], v186 offset:4096
	ds_read_b128 v[204:207], v186 offset:5120
	ds_read_b128 v[208:211], v186 offset:6144
	ds_read_b128 v[212:215], v186 offset:7168
	global_load_lds_dwordx4 v[198:199], off
	s_mov_b32 m0, s97
	v_lshl_add_u64 v[198:199], s[46:47], 0, v[150:151]
	global_load_lds_dwordx4 v[198:199], off
	s_waitcnt vmcnt(8)
	s_waitcnt lgkmcnt(0)
	s_setprio 1
	s_barrier
	v_mfma_f32_16x16x32_bf16 v[128:131], v[132:135], v[176:179], v[128:131]
	v_mfma_f32_16x16x32_bf16 v[124:127], v[140:143], v[176:179], v[124:127]
	v_mfma_f32_16x16x32_bf16 v[112:115], v[132:135], v[188:191], v[112:115]
	v_mfma_f32_16x16x32_bf16 v[108:111], v[140:143], v[188:191], v[108:111]
	v_mfma_f32_16x16x32_bf16 v[96:99], v[132:135], v[200:203], v[96:99]
	v_mfma_f32_16x16x32_bf16 v[92:95], v[140:143], v[200:203], v[92:95]
	v_mfma_f32_16x16x32_bf16 v[80:83], v[132:135], v[208:211], v[80:83]
	v_mfma_f32_16x16x32_bf16 v[76:79], v[140:143], v[208:211], v[76:79]
	v_mfma_f32_16x16x32_bf16 v[128:131], v[136:139], v[180:183], v[128:131]
	v_mfma_f32_16x16x32_bf16 v[124:127], v[144:147], v[180:183], v[124:127]
	v_mfma_f32_16x16x32_bf16 v[112:115], v[136:139], v[192:195], v[112:115]
	v_mfma_f32_16x16x32_bf16 v[108:111], v[144:147], v[192:195], v[108:111]
	v_mfma_f32_16x16x32_bf16 v[96:99], v[136:139], v[204:207], v[96:99]
	v_mfma_f32_16x16x32_bf16 v[92:95], v[144:147], v[204:207], v[92:95]
	v_mfma_f32_16x16x32_bf16 v[80:83], v[136:139], v[212:215], v[80:83]
	v_mfma_f32_16x16x32_bf16 v[76:79], v[144:147], v[212:215], v[76:79]
	s_setprio 0
	s_setprio 1
	v_mfma_f32_16x16x32_bf16 v[120:123], v[160:163], v[176:179], v[120:123]
	v_mfma_f32_16x16x32_bf16 v[116:119], v[168:171], v[176:179], v[116:119]
	v_mfma_f32_16x16x32_bf16 v[104:107], v[160:163], v[188:191], v[104:107]
	v_mfma_f32_16x16x32_bf16 v[100:103], v[168:171], v[188:191], v[100:103]
	v_mfma_f32_16x16x32_bf16 v[88:91], v[160:163], v[200:203], v[88:91]
	v_mfma_f32_16x16x32_bf16 v[84:87], v[168:171], v[200:203], v[84:87]
	v_mfma_f32_16x16x32_bf16 v[72:75], v[160:163], v[208:211], v[72:75]
	v_mfma_f32_16x16x32_bf16 v[68:71], v[168:171], v[208:211], v[68:71]
	v_mfma_f32_16x16x32_bf16 v[120:123], v[164:167], v[180:183], v[120:123]
	v_mfma_f32_16x16x32_bf16 v[116:119], v[172:175], v[180:183], v[116:119]
	v_mfma_f32_16x16x32_bf16 v[104:107], v[164:167], v[192:195], v[104:107]
	v_mfma_f32_16x16x32_bf16 v[100:103], v[172:175], v[192:195], v[100:103]
	v_mfma_f32_16x16x32_bf16 v[88:91], v[164:167], v[204:207], v[88:91]
	v_mfma_f32_16x16x32_bf16 v[84:87], v[172:175], v[204:207], v[84:87]
	v_mfma_f32_16x16x32_bf16 v[72:75], v[164:167], v[212:215], v[72:75]
	v_mfma_f32_16x16x32_bf16 v[68:71], v[172:175], v[212:215], v[68:71]
	s_barrier
	s_setprio 0
	s_mov_b32 m0, s49
	v_lshl_add_u64 v[198:199], s[30:31], 0, v[152:153]
	ds_read_b128 v[176:179], v186 offset:16384
	ds_read_b128 v[180:183], v186 offset:17408
	ds_read_b128 v[188:191], v186 offset:18432
	ds_read_b128 v[192:195], v186 offset:19456
	ds_read_b128 v[200:203], v186 offset:20480
	ds_read_b128 v[204:207], v186 offset:21504
	ds_read_b128 v[208:211], v186 offset:22528
	ds_read_b128 v[212:215], v186 offset:23552
	global_load_lds_dwordx4 v[198:199], off
	v_lshl_add_u64 v[216:217], s[30:31], 0, v[148:149]
	s_mov_b32 m0, s82
	v_lshl_add_u64 v[218:219], s[34:35], 0, v[152:153]
	global_load_lds_dwordx4 v[216:217], off
	s_mov_b32 m0, s85
	global_load_lds_dwordx4 v[218:219], off
	s_mov_b32 m0, s84
	v_lshl_add_u64 v[218:219], s[34:35], 0, v[148:149]
	global_load_lds_dwordx4 v[218:219], off
	s_mov_b32 m0, s59
	v_lshl_add_u64 v[218:219], s[52:53], 0, v[154:155]
	global_load_lds_dwordx4 v[218:219], off
	s_mov_b32 m0, s40
	v_lshl_add_u64 v[220:221], s[52:53], 0, v[150:151]
	global_load_lds_dwordx4 v[220:221], off
	s_waitcnt vmcnt(8)
	s_waitcnt lgkmcnt(0)
	s_setprio 1
	s_barrier
	v_mfma_f32_16x16x32_bf16 v[64:67], v[132:135], v[176:179], v[64:67]
	v_mfma_f32_16x16x32_bf16 v[60:63], v[140:143], v[176:179], v[60:63]
	v_mfma_f32_16x16x32_bf16 v[48:51], v[132:135], v[188:191], v[48:51]
	v_mfma_f32_16x16x32_bf16 v[44:47], v[140:143], v[188:191], v[44:47]
	v_mfma_f32_16x16x32_bf16 v[32:35], v[132:135], v[200:203], v[32:35]
	v_mfma_f32_16x16x32_bf16 v[28:31], v[140:143], v[200:203], v[28:31]
	v_mfma_f32_16x16x32_bf16 v[16:19], v[132:135], v[208:211], v[16:19]
	v_mfma_f32_16x16x32_bf16 v[12:15], v[140:143], v[208:211], v[12:15]
	v_mfma_f32_16x16x32_bf16 v[64:67], v[136:139], v[180:183], v[64:67]
	v_mfma_f32_16x16x32_bf16 v[60:63], v[144:147], v[180:183], v[60:63]
	v_mfma_f32_16x16x32_bf16 v[48:51], v[136:139], v[192:195], v[48:51]
	v_mfma_f32_16x16x32_bf16 v[44:47], v[144:147], v[192:195], v[44:47]
	v_mfma_f32_16x16x32_bf16 v[32:35], v[136:139], v[204:207], v[32:35]
	v_mfma_f32_16x16x32_bf16 v[28:31], v[144:147], v[204:207], v[28:31]
	v_mfma_f32_16x16x32_bf16 v[16:19], v[136:139], v[212:215], v[16:19]
	v_mfma_f32_16x16x32_bf16 v[12:15], v[144:147], v[212:215], v[12:15]
	s_setprio 0
	s_setprio 1
	v_mfma_f32_16x16x32_bf16 v[56:59], v[160:163], v[176:179], v[56:59]
	v_mfma_f32_16x16x32_bf16 v[52:55], v[168:171], v[176:179], v[52:55]
	v_mfma_f32_16x16x32_bf16 v[40:43], v[160:163], v[188:191], v[40:43]
	v_mfma_f32_16x16x32_bf16 v[36:39], v[168:171], v[188:191], v[36:39]
	v_mfma_f32_16x16x32_bf16 v[24:27], v[160:163], v[200:203], v[24:27]
	v_mfma_f32_16x16x32_bf16 v[20:23], v[168:171], v[200:203], v[20:23]
	v_mfma_f32_16x16x32_bf16 v[8:11], v[160:163], v[208:211], v[8:11]
	v_mfma_f32_16x16x32_bf16 v[4:7], v[168:171], v[208:211], v[4:7]
	v_mfma_f32_16x16x32_bf16 v[56:59], v[164:167], v[180:183], v[56:59]
	v_mfma_f32_16x16x32_bf16 v[52:55], v[172:175], v[180:183], v[52:55]
	v_mfma_f32_16x16x32_bf16 v[40:43], v[164:167], v[192:195], v[40:43]
	v_mfma_f32_16x16x32_bf16 v[36:39], v[172:175], v[192:195], v[36:39]
	v_mfma_f32_16x16x32_bf16 v[24:27], v[164:167], v[204:207], v[24:27]
	v_mfma_f32_16x16x32_bf16 v[20:23], v[172:175], v[204:207], v[20:23]
	v_mfma_f32_16x16x32_bf16 v[8:11], v[164:167], v[212:215], v[8:11]
	v_mfma_f32_16x16x32_bf16 v[4:7], v[172:175], v[212:215], v[4:7]
	s_barrier
	s_setprio 0
	v_add_u32_e32 v144, s0, v3
	v_add_u32_e32 v172, s54, v3
	ds_read_b128 v[132:135], v144
	ds_read_b128 v[136:139], v144 offset:1024
	ds_read_b128 v[140:143], v144 offset:2048
	ds_read_b128 v[144:147], v144 offset:3072
	ds_read_b128 v[160:163], v172
	ds_read_b128 v[164:167], v172 offset:1024
	ds_read_b128 v[168:171], v172 offset:2048
	ds_read_b128 v[172:175], v172 offset:3072
	s_mov_b32 m0, s55
	v_lshl_add_u64 v[222:223], vcc, 0, v[154:155]
	ds_read_b128 v[176:179], v186 offset:32768
	ds_read_b128 v[180:183], v186 offset:33792
	ds_read_b128 v[188:191], v186 offset:34816
	ds_read_b128 v[192:195], v186 offset:35840
	ds_read_b128 v[200:203], v186 offset:36864
	ds_read_b128 v[204:207], v186 offset:37888
	ds_read_b128 v[208:211], v186 offset:38912
	ds_read_b128 v[212:215], v186 offset:39936
	global_load_lds_dwordx4 v[222:223], off
	s_mov_b32 m0, s50
	v_lshl_add_u64 v[222:223], vcc, 0, v[150:151]
	global_load_lds_dwordx4 v[222:223], off
	s_waitcnt vmcnt(8)
	s_waitcnt lgkmcnt(0)
	s_setprio 1
	s_barrier
	v_mfma_f32_16x16x32_bf16 v[128:131], v[132:135], v[176:179], v[128:131]
	v_mfma_f32_16x16x32_bf16 v[124:127], v[140:143], v[176:179], v[124:127]
	v_mfma_f32_16x16x32_bf16 v[112:115], v[132:135], v[188:191], v[112:115]
	v_mfma_f32_16x16x32_bf16 v[108:111], v[140:143], v[188:191], v[108:111]
	v_mfma_f32_16x16x32_bf16 v[96:99], v[132:135], v[200:203], v[96:99]
	v_mfma_f32_16x16x32_bf16 v[92:95], v[140:143], v[200:203], v[92:95]
	v_mfma_f32_16x16x32_bf16 v[80:83], v[132:135], v[208:211], v[80:83]
	v_mfma_f32_16x16x32_bf16 v[76:79], v[140:143], v[208:211], v[76:79]
	v_mfma_f32_16x16x32_bf16 v[128:131], v[136:139], v[180:183], v[128:131]
	v_mfma_f32_16x16x32_bf16 v[124:127], v[144:147], v[180:183], v[124:127]
	v_mfma_f32_16x16x32_bf16 v[112:115], v[136:139], v[192:195], v[112:115]
	v_mfma_f32_16x16x32_bf16 v[108:111], v[144:147], v[192:195], v[108:111]
	v_mfma_f32_16x16x32_bf16 v[96:99], v[136:139], v[204:207], v[96:99]
	v_mfma_f32_16x16x32_bf16 v[92:95], v[144:147], v[204:207], v[92:95]
	v_mfma_f32_16x16x32_bf16 v[80:83], v[136:139], v[212:215], v[80:83]
	v_mfma_f32_16x16x32_bf16 v[76:79], v[144:147], v[212:215], v[76:79]
	s_setprio 0
	s_setprio 1
	v_mfma_f32_16x16x32_bf16 v[120:123], v[160:163], v[176:179], v[120:123]
	v_mfma_f32_16x16x32_bf16 v[116:119], v[168:171], v[176:179], v[116:119]
	v_mfma_f32_16x16x32_bf16 v[104:107], v[160:163], v[188:191], v[104:107]
	v_mfma_f32_16x16x32_bf16 v[100:103], v[168:171], v[188:191], v[100:103]
	v_mfma_f32_16x16x32_bf16 v[88:91], v[160:163], v[200:203], v[88:91]
	v_mfma_f32_16x16x32_bf16 v[84:87], v[168:171], v[200:203], v[84:87]
	v_mfma_f32_16x16x32_bf16 v[72:75], v[160:163], v[208:211], v[72:75]
	v_mfma_f32_16x16x32_bf16 v[68:71], v[168:171], v[208:211], v[68:71]
	v_mfma_f32_16x16x32_bf16 v[120:123], v[164:167], v[180:183], v[120:123]
	v_mfma_f32_16x16x32_bf16 v[116:119], v[172:175], v[180:183], v[116:119]
	v_mfma_f32_16x16x32_bf16 v[104:107], v[164:167], v[192:195], v[104:107]
	v_mfma_f32_16x16x32_bf16 v[100:103], v[172:175], v[192:195], v[100:103]
	v_mfma_f32_16x16x32_bf16 v[88:91], v[164:167], v[204:207], v[88:91]
	v_mfma_f32_16x16x32_bf16 v[84:87], v[172:175], v[204:207], v[84:87]
	v_mfma_f32_16x16x32_bf16 v[72:75], v[164:167], v[212:215], v[72:75]
	v_mfma_f32_16x16x32_bf16 v[68:71], v[172:175], v[212:215], v[68:71]
	s_barrier
	s_setprio 0
	s_mov_b32 m0, s73
	v_lshl_add_u64 v[198:199], v[198:199], 0, s[90:91]
	ds_read_b128 v[176:179], v186 offset:49152
	ds_read_b128 v[180:183], v186 offset:50176
	ds_read_b128 v[188:191], v186 offset:51200
	ds_read_b128 v[192:195], v186 offset:52224
	ds_read_b128 v[200:203], v186 offset:53248
	ds_read_b128 v[204:207], v186 offset:54272
	ds_read_b128 v[208:211], v186 offset:55296
	ds_read_b128 v[212:215], v186 offset:56320
	global_load_lds_dwordx4 v[198:199], off
	s_mov_b32 m0, s6
	v_lshl_add_u64 v[198:199], v[216:217], 0, s[90:91]
	global_load_lds_dwordx4 v[198:199], off
	s_mov_b32 m0, s83
	v_lshl_add_u64 v[198:199], s[38:39], 0, v[152:153]
	global_load_lds_dwordx4 v[198:199], off
	s_mov_b32 m0, s96
	v_lshl_add_u64 v[198:199], s[38:39], 0, v[148:149]
	global_load_lds_dwordx4 v[198:199], off
	s_mov_b32 m0, s1
	v_lshl_add_u64 v[198:199], v[218:219], 0, s[90:91]
	global_load_lds_dwordx4 v[198:199], off
	s_mov_b32 m0, s24
	v_lshl_add_u64 v[198:199], v[220:221], 0, s[90:91]
	global_load_lds_dwordx4 v[198:199], off
	s_waitcnt vmcnt(8)
	s_waitcnt lgkmcnt(0)
	s_setprio 1
	s_barrier
	v_mfma_f32_16x16x32_bf16 v[64:67], v[132:135], v[176:179], v[64:67]
	v_mfma_f32_16x16x32_bf16 v[60:63], v[140:143], v[176:179], v[60:63]
	v_mfma_f32_16x16x32_bf16 v[48:51], v[132:135], v[188:191], v[48:51]
	v_mfma_f32_16x16x32_bf16 v[44:47], v[140:143], v[188:191], v[44:47]
	v_mfma_f32_16x16x32_bf16 v[32:35], v[132:135], v[200:203], v[32:35]
	v_mfma_f32_16x16x32_bf16 v[28:31], v[140:143], v[200:203], v[28:31]
	v_mfma_f32_16x16x32_bf16 v[16:19], v[132:135], v[208:211], v[16:19]
	v_mfma_f32_16x16x32_bf16 v[12:15], v[140:143], v[208:211], v[12:15]
	v_mfma_f32_16x16x32_bf16 v[64:67], v[136:139], v[180:183], v[64:67]
	v_mfma_f32_16x16x32_bf16 v[60:63], v[144:147], v[180:183], v[60:63]
	v_mfma_f32_16x16x32_bf16 v[48:51], v[136:139], v[192:195], v[48:51]
	v_mfma_f32_16x16x32_bf16 v[44:47], v[144:147], v[192:195], v[44:47]
	v_mfma_f32_16x16x32_bf16 v[32:35], v[136:139], v[204:207], v[32:35]
	v_mfma_f32_16x16x32_bf16 v[28:31], v[144:147], v[204:207], v[28:31]
	v_mfma_f32_16x16x32_bf16 v[16:19], v[136:139], v[212:215], v[16:19]
	v_mfma_f32_16x16x32_bf16 v[12:15], v[144:147], v[212:215], v[12:15]
	s_setprio 0
	s_setprio 1
	v_mfma_f32_16x16x32_bf16 v[56:59], v[160:163], v[176:179], v[56:59]
	v_mfma_f32_16x16x32_bf16 v[52:55], v[168:171], v[176:179], v[52:55]
	v_mfma_f32_16x16x32_bf16 v[40:43], v[160:163], v[188:191], v[40:43]
	v_mfma_f32_16x16x32_bf16 v[36:39], v[168:171], v[188:191], v[36:39]
	v_mfma_f32_16x16x32_bf16 v[24:27], v[160:163], v[200:203], v[24:27]
	v_mfma_f32_16x16x32_bf16 v[20:23], v[168:171], v[200:203], v[20:23]
	v_mfma_f32_16x16x32_bf16 v[8:11], v[160:163], v[208:211], v[8:11]
	v_mfma_f32_16x16x32_bf16 v[4:7], v[168:171], v[208:211], v[4:7]
	v_mfma_f32_16x16x32_bf16 v[56:59], v[164:167], v[180:183], v[56:59]
	v_mfma_f32_16x16x32_bf16 v[52:55], v[172:175], v[180:183], v[52:55]
	v_mfma_f32_16x16x32_bf16 v[40:43], v[164:167], v[192:195], v[40:43]
	v_mfma_f32_16x16x32_bf16 v[36:39], v[172:175], v[192:195], v[36:39]
	v_mfma_f32_16x16x32_bf16 v[24:27], v[164:167], v[204:207], v[24:27]
	v_mfma_f32_16x16x32_bf16 v[20:23], v[172:175], v[204:207], v[20:23]
	v_mfma_f32_16x16x32_bf16 v[8:11], v[164:167], v[212:215], v[8:11]
	v_mfma_f32_16x16x32_bf16 v[4:7], v[172:175], v[212:215], v[4:7]
	s_barrier
	s_setprio 0
	s_movk_i32 s30, 0x100
	s_andn2_b64 vcc, exec, s[36:37]
	s_mov_b64 s[38:39], -1
	s_mov_b64 s[36:37], 0
	s_cbranch_vccz .LBB0_1441
	s_and_b64 vcc, exec, s[28:29]
	s_cbranch_vccz .LBB0_1444
	s_barrier
